# redundant lgkmcnt(0) between the phase barrier and its MFMA block removed (the same wait sits in front of the barrier)
# speedup vs baseline: 1.0099x; 1.0030x over previous
; #define PG8_STAGE(bufoff, gbase, voff) do { _Pragma("unroll") for (int _i = 0; _i < 2; ++_i) \
;         __builtin_amdgcn_global_load_lds((const unsigned*)((const char*)(gbase) + (voff)[_i]), (PG8_LAS unsigned*)(lds + (bufoff) + ldsw + _i * 8192), 16, 0, 0); } while (0)
; #define PG8_LDA(dst, b, h) do { _Pragma("unroll") for (int m = 0; m < 4; ++m) _Pragma("unroll") for (int k = 0; k < 2; ++k) dst[m][k] = *(const PG8_LAS bf16x8*)(lds + PG8_SA(b, h) + aoff + m * 2048 + k * 1024); } while (0)
; #define PG8_LDB(dst, b, h) do { _Pragma("unroll") for (int n = 0; n < 2; ++n) _Pragma("unroll") for (int k = 0; k < 2; ++k) dst[n][k] = *(const PG8_LAS bf16x8*)(lds + PG8_SB(b, h) + boff + n * 2048 + k * 1024); } while (0)
; #define PG8_MMA(ai, bj, At, Bt) do { __builtin_amdgcn_s_setprio(1); _Pragma("unroll") for (int m = 0; m < 4; ++m) _Pragma("unroll") for (int n = 0; n < 2; ++n) _Pragma("unroll") for (int k = 0; k < 2; ++k) \
;         acc[ai][bj][m][n] = __builtin_amdgcn_mfma_f32_16x16x32_bf16(Bt[n][k], At[m][k], acc[ai][bj][m][n], 0, 0, 0); __builtin_amdgcn_s_setprio(0); } while (0)
; #define PG8_WAIT_V(n) asm volatile("s_waitcnt vmcnt(" #n ")" ::: "memory")
; #define PG8_WAIT_L(n) asm volatile("s_waitcnt lgkmcnt(" #n ")" ::: "memory")
; #define PG8_BAR __builtin_amdgcn_s_barrier()
; template <class Epi, class Sched, bool ALIGN_EPI = false, bool SP2 = false>
; __device__ __forceinline__ void gemm_phase(PG8_LAS unsigned char* lds, const Gemm g, const Sched& S, const Epi& E) {
;     ...
;             const char* a1 = cA + (size_t)(t + 1) * kstep;
;             const char* a2 = last ? nA : cA + (size_t)(t + 2) * kstep; const char* b2 = last ? nB : cB + (size_t)(t + 2) * kstep;
;             const char* a3 = a2 + kstep; const char* b3 = b2 + kstep;
;             if (last && has_next) S.a_ready(nxt);
;             if constexpr (SP2) {
;             PG8_LDB(B0, 0, 0); PG8_LDB(B1, 0, 1); PG8_SCHED; PG8_LDA(At, 0, 0); PG8_STAGE(PG8_SA(1, 1), a1 + hstep, voffA);
;             PG8_WAIT_V(8); PG8_WAIT_L(0); PG8_BAR; PG8_MMA(0, 0, At, B0); PG8_MMA(0, 1, At, B1); PG8_BAR; PG8_SCHED;
;             PG8_LDA(At, 0, 1); PG8_STAGE(PG8_SB(0, 0), b2, voffB); PG8_STAGE(PG8_SB(0, 1), b2 + hstep, voffB); PG8_STAGE(PG8_SA(0, 0), a2, voffA);
;             PG8_WAIT_V(8); PG8_WAIT_L(0); PG8_BAR; PG8_MMA(1, 0, At, B0); PG8_MMA(1, 1, At, B1); PG8_BAR; PG8_SCHED;
.LBB0_96:
	ds_read_b128 v[128:131], v178
	ds_read_b128 v[132:135], v178 offset:1024
	ds_read_b128 v[136:139], v178 offset:2048
	ds_read_b128 v[140:143], v178 offset:3072
	ds_read_b128 v[166:169], v179
	ds_read_b128 v[170:173], v179 offset:1024
	ds_read_b128 v[190:193], v179 offset:2048
	ds_read_b128 v[194:197], v179 offset:3072
	s_add_u32 s36, s80, 0xfffc0080
	s_addc_u32 s37, s81, -1
	s_cmp_eq_u32 s35, 12
	s_cselect_b32 s87, s8, s37
	s_cselect_b32 s86, s55, s36
	s_cselect_b32 s83, s49, s34
	s_cselect_b32 s82, vcc_lo, vcc_hi
	s_add_i32 m0, s93, 0xc000
	ds_read_b128 v[198:201], v181
	ds_read_b128 v[202:205], v181 offset:1024
	ds_read_b128 v[206:209], v181 offset:2048
	ds_read_b128 v[210:213], v181 offset:3072
	ds_read_b128 v[214:217], v181 offset:4096
	ds_read_b128 v[218:221], v181 offset:5120
	ds_read_b128 v[222:225], v181 offset:6144
	ds_read_b128 v[226:229], v181 offset:7168
	global_load_lds_dwordx4 v158, s[80:81]
	s_add_i32 m0, s93, 0xe000
	s_nop 0
	global_load_lds_dwordx4 v160, s[80:81]
	s_waitcnt vmcnt(8)
	s_waitcnt lgkmcnt(0)
	s_barrier
	s_setprio 1
	v_mfma_f32_16x16x32_bf16 v[124:127], v[128:131], v[198:201], v[124:127]
	v_mfma_f32_16x16x32_bf16 v[120:123], v[136:139], v[198:201], v[120:123]
	v_mfma_f32_16x16x32_bf16 v[108:111], v[128:131], v[206:209], v[108:111]
	v_mfma_f32_16x16x32_bf16 v[104:107], v[136:139], v[206:209], v[104:107]
	v_mfma_f32_16x16x32_bf16 v[92:95], v[128:131], v[214:217], v[92:95]
	v_mfma_f32_16x16x32_bf16 v[88:91], v[136:139], v[214:217], v[88:91]
	v_mfma_f32_16x16x32_bf16 v[76:79], v[128:131], v[222:225], v[76:79]
	v_mfma_f32_16x16x32_bf16 v[72:75], v[136:139], v[222:225], v[72:75]
	v_mfma_f32_16x16x32_bf16 v[124:127], v[132:135], v[202:205], v[124:127]
	v_mfma_f32_16x16x32_bf16 v[120:123], v[140:143], v[202:205], v[120:123]
	v_mfma_f32_16x16x32_bf16 v[108:111], v[132:135], v[210:213], v[108:111]
	v_mfma_f32_16x16x32_bf16 v[104:107], v[140:143], v[210:213], v[104:107]
	v_mfma_f32_16x16x32_bf16 v[92:95], v[132:135], v[218:221], v[92:95]
	v_mfma_f32_16x16x32_bf16 v[88:91], v[140:143], v[218:221], v[88:91]
	v_mfma_f32_16x16x32_bf16 v[76:79], v[132:135], v[226:229], v[76:79]
	v_mfma_f32_16x16x32_bf16 v[72:75], v[140:143], v[226:229], v[72:75]
	v_mfma_f32_16x16x32_bf16 v[116:119], v[166:169], v[198:201], v[116:119]
	v_mfma_f32_16x16x32_bf16 v[112:115], v[190:193], v[198:201], v[112:115]
	v_mfma_f32_16x16x32_bf16 v[100:103], v[166:169], v[206:209], v[100:103]
	v_mfma_f32_16x16x32_bf16 v[96:99], v[190:193], v[206:209], v[96:99]
	v_mfma_f32_16x16x32_bf16 v[84:87], v[166:169], v[214:217], v[84:87]
	v_mfma_f32_16x16x32_bf16 v[80:83], v[190:193], v[214:217], v[80:83]
	v_mfma_f32_16x16x32_bf16 v[68:71], v[166:169], v[222:225], v[68:71]
	v_mfma_f32_16x16x32_bf16 v[64:67], v[190:193], v[222:225], v[64:67]
	v_mfma_f32_16x16x32_bf16 v[116:119], v[170:173], v[202:205], v[116:119]
	v_mfma_f32_16x16x32_bf16 v[112:115], v[194:197], v[202:205], v[112:115]
	v_mfma_f32_16x16x32_bf16 v[100:103], v[170:173], v[210:213], v[100:103]
	v_mfma_f32_16x16x32_bf16 v[96:99], v[194:197], v[210:213], v[96:99]
	v_mfma_f32_16x16x32_bf16 v[84:87], v[170:173], v[218:221], v[84:87]
	v_mfma_f32_16x16x32_bf16 v[80:83], v[194:197], v[218:221], v[80:83]
	v_mfma_f32_16x16x32_bf16 v[68:71], v[170:173], v[226:229], v[68:71]
	v_mfma_f32_16x16x32_bf16 v[64:67], v[194:197], v[226:229], v[64:67]
	s_setprio 0
	s_barrier
	s_add_i32 s36, s23, s90
	v_lshl_add_u64 v[174:175], s[82:83], 0, v[148:149]
	s_mov_b32 m0, s36
	ds_read_b128 v[198:201], v181 offset:16384
	ds_read_b128 v[202:205], v181 offset:17408
	ds_read_b128 v[206:209], v181 offset:18432
	ds_read_b128 v[210:213], v181 offset:19456
	ds_read_b128 v[214:217], v181 offset:20480
	ds_read_b128 v[218:221], v181 offset:21504
	ds_read_b128 v[222:225], v181 offset:22528
	ds_read_b128 v[226:229], v181 offset:23552
	global_load_lds_dwordx4 v[174:175], off
	s_add_i32 m0, s36, 0x2000
	s_add_u32 s36, s82, 0x40000
	v_lshl_add_u64 v[186:187], s[82:83], 0, v[144:145]
	s_addc_u32 s37, s83, 0
	s_add_i32 s20, s41, s90
	global_load_lds_dwordx4 v[186:187], off
	s_mov_b32 m0, s20
	v_lshl_add_u64 v[232:233], s[86:87], 0, v[146:147]
	global_load_lds_dwordx4 v148, s[36:37]
	s_add_i32 m0, s20, 0x2000
	s_nop 0
	global_load_lds_dwordx4 v144, s[36:37]
	v_lshl_add_u64 v[230:231], s[86:87], 0, v[150:151]
	s_mov_b32 m0, s93
	s_nop 0
	global_load_lds_dwordx4 v[230:231], off
	s_mov_b32 m0, s94
	s_nop 0
	global_load_lds_dwordx4 v[232:233], off
	s_waitcnt vmcnt(8)
	s_waitcnt lgkmcnt(0)
	s_barrier
	s_setprio 1
	v_mfma_f32_16x16x32_bf16 v[60:63], v[128:131], v[198:201], v[60:63]
	v_mfma_f32_16x16x32_bf16 v[56:59], v[136:139], v[198:201], v[56:59]
	v_mfma_f32_16x16x32_bf16 v[44:47], v[128:131], v[206:209], v[44:47]
	v_mfma_f32_16x16x32_bf16 v[40:43], v[136:139], v[206:209], v[40:43]
	v_mfma_f32_16x16x32_bf16 v[28:31], v[128:131], v[214:217], v[28:31]
	v_mfma_f32_16x16x32_bf16 v[24:27], v[136:139], v[214:217], v[24:27]
	v_mfma_f32_16x16x32_bf16 v[12:15], v[128:131], v[222:225], v[12:15]
	v_mfma_f32_16x16x32_bf16 v[8:11], v[136:139], v[222:225], v[8:11]
	v_mfma_f32_16x16x32_bf16 v[60:63], v[132:135], v[202:205], v[60:63]
	v_mfma_f32_16x16x32_bf16 v[56:59], v[140:143], v[202:205], v[56:59]
	v_mfma_f32_16x16x32_bf16 v[44:47], v[132:135], v[210:213], v[44:47]
	v_mfma_f32_16x16x32_bf16 v[40:43], v[140:143], v[210:213], v[40:43]
	v_mfma_f32_16x16x32_bf16 v[28:31], v[132:135], v[218:221], v[28:31]
	v_mfma_f32_16x16x32_bf16 v[24:27], v[140:143], v[218:221], v[24:27]
	v_mfma_f32_16x16x32_bf16 v[12:15], v[132:135], v[226:229], v[12:15]
	v_mfma_f32_16x16x32_bf16 v[8:11], v[140:143], v[226:229], v[8:11]
	v_mfma_f32_16x16x32_bf16 v[52:55], v[166:169], v[198:201], v[52:55]
	v_mfma_f32_16x16x32_bf16 v[48:51], v[190:193], v[198:201], v[48:51]
	v_mfma_f32_16x16x32_bf16 v[36:39], v[166:169], v[206:209], v[36:39]
	v_mfma_f32_16x16x32_bf16 v[32:35], v[190:193], v[206:209], v[32:35]
	v_mfma_f32_16x16x32_bf16 v[20:23], v[166:169], v[214:217], v[20:23]
	v_mfma_f32_16x16x32_bf16 v[16:19], v[190:193], v[214:217], v[16:19]
	v_mfma_f32_16x16x32_bf16 v[4:7], v[166:169], v[222:225], v[4:7]
	v_mfma_f32_16x16x32_bf16 v[0:3], v[190:193], v[222:225], v[0:3]
	v_mfma_f32_16x16x32_bf16 v[52:55], v[170:173], v[202:205], v[52:55]
	v_mfma_f32_16x16x32_bf16 v[48:51], v[194:197], v[202:205], v[48:51]
	v_mfma_f32_16x16x32_bf16 v[36:39], v[170:173], v[210:213], v[36:39]
	v_mfma_f32_16x16x32_bf16 v[32:35], v[194:197], v[210:213], v[32:35]
	v_mfma_f32_16x16x32_bf16 v[20:23], v[170:173], v[218:221], v[20:23]
	v_mfma_f32_16x16x32_bf16 v[16:19], v[194:197], v[218:221], v[16:19]
	v_mfma_f32_16x16x32_bf16 v[4:7], v[170:173], v[226:229], v[4:7]
	v_mfma_f32_16x16x32_bf16 v[0:3], v[194:197], v[226:229], v[0:3]
	s_setprio 0
	s_barrier
; #define PG8_STAGE(bufoff, gbase, voff) do { _Pragma("unroll") for (int _i = 0; _i < 2; ++_i) \
;         __builtin_amdgcn_global_load_lds((const unsigned*)((const char*)(gbase) + (voff)[_i]), (PG8_LAS unsigned*)(lds + (bufoff) + ldsw + _i * 8192), 16, 0, 0); } while (0)
; #define PG8_LDA(dst, b, h) do { _Pragma("unroll") for (int m = 0; m < 4; ++m) _Pragma("unroll") for (int k = 0; k < 2; ++k) dst[m][k] = *(const PG8_LAS bf16x8*)(lds + PG8_SA(b, h) + aoff + m * 2048 + k * 1024); } while (0)
; #define PG8_LDB(dst, b, h) do { _Pragma("unroll") for (int n = 0; n < 2; ++n) _Pragma("unroll") for (int k = 0; k < 2; ++k) dst[n][k] = *(const PG8_LAS bf16x8*)(lds + PG8_SB(b, h) + boff + n * 2048 + k * 1024); } while (0)
; #define PG8_MMA(ai, bj, At, Bt) do { __builtin_amdgcn_s_setprio(1); _Pragma("unroll") for (int m = 0; m < 4; ++m) _Pragma("unroll") for (int n = 0; n < 2; ++n) _Pragma("unroll") for (int k = 0; k < 2; ++k) \
;         acc[ai][bj][m][n] = __builtin_amdgcn_mfma_f32_16x16x32_bf16(Bt[n][k], At[m][k], acc[ai][bj][m][n], 0, 0, 0); __builtin_amdgcn_s_setprio(0); } while (0)
; #define PG8_WAIT_V(n) asm volatile("s_waitcnt vmcnt(" #n ")" ::: "memory")
; #define PG8_WAIT_L(n) asm volatile("s_waitcnt lgkmcnt(" #n ")" ::: "memory")
; #define PG8_BAR __builtin_amdgcn_s_barrier()
; #define PG8_SCHED __builtin_amdgcn_sched_barrier(0)
; template <class Epi, class Sched, bool ALIGN_EPI = false, bool SP2 = false>
; __device__ __forceinline__ void gemm_phase(PG8_LAS unsigned char* lds, const Gemm g, const Sched& S, const Epi& E) {
;     ...
;         for (int t = 0; t < nt; t += 2) {
;             const bool last = (t == nt - 2);
;     ...
;             PG8_LDB(B0, 1, 0); PG8_LDB(B1, 1, 1); PG8_SCHED; PG8_LDA(At, 1, 0); PG8_STAGE(PG8_SA(0, 1), a2 + hstep, voffA);
;             PG8_WAIT_V(8); PG8_WAIT_L(0); PG8_BAR; PG8_MMA(0, 0, At, B0); PG8_MMA(0, 1, At, B1); PG8_BAR; PG8_SCHED;
;             PG8_LDA(At, 1, 1); PG8_STAGE(PG8_SB(1, 0), b3, voffB); PG8_STAGE(PG8_SB(1, 1), b3 + hstep, voffB); PG8_STAGE(PG8_SA(1, 0), a3, voffA);
;             PG8_WAIT_V(8); PG8_WAIT_L(0); PG8_BAR; PG8_MMA(1, 0, At, B0); PG8_MMA(1, 1, At, B1); PG8_BAR; PG8_SCHED;
	s_add_i32 s20, 0, 0x18000
	s_add_i32 s21, 0, 0x1c000
	v_add_u32_e32 v140, s20, v176
	v_add_u32_e32 v152, s21, v176
	ds_read_b128 v[128:131], v140
	ds_read_b128 v[132:135], v140 offset:1024
	ds_read_b128 v[136:139], v140 offset:2048
	ds_read_b128 v[140:143], v140 offset:3072
	ds_read_b128 v[166:169], v152
	ds_read_b128 v[170:173], v152 offset:1024
	ds_read_b128 v[190:193], v152 offset:2048
	ds_read_b128 v[194:197], v152 offset:3072
	s_add_u32 s36, s86, 0x40000
	s_addc_u32 s37, s87, 0
	s_mov_b32 m0, s95
	ds_read_b128 v[198:201], v181 offset:32768
	ds_read_b128 v[202:205], v181 offset:33792
	ds_read_b128 v[206:209], v181 offset:34816
	ds_read_b128 v[210:213], v181 offset:35840
	ds_read_b128 v[214:217], v181 offset:36864
	ds_read_b128 v[218:221], v181 offset:37888
	ds_read_b128 v[222:225], v181 offset:38912
	ds_read_b128 v[226:229], v181 offset:39936
	global_load_lds_dwordx4 v150, s[36:37]
	s_mov_b32 m0, s97
	s_nop 0
	global_load_lds_dwordx4 v146, s[36:37]
	s_waitcnt vmcnt(8)
	s_waitcnt lgkmcnt(0)
	s_barrier
	s_setprio 1
	v_mfma_f32_16x16x32_bf16 v[124:127], v[128:131], v[198:201], v[124:127]
	v_mfma_f32_16x16x32_bf16 v[120:123], v[136:139], v[198:201], v[120:123]
	v_mfma_f32_16x16x32_bf16 v[108:111], v[128:131], v[206:209], v[108:111]
	v_mfma_f32_16x16x32_bf16 v[104:107], v[136:139], v[206:209], v[104:107]
	v_mfma_f32_16x16x32_bf16 v[92:95], v[128:131], v[214:217], v[92:95]
	v_mfma_f32_16x16x32_bf16 v[88:91], v[136:139], v[214:217], v[88:91]
	v_mfma_f32_16x16x32_bf16 v[76:79], v[128:131], v[222:225], v[76:79]
	v_mfma_f32_16x16x32_bf16 v[72:75], v[136:139], v[222:225], v[72:75]
	v_mfma_f32_16x16x32_bf16 v[124:127], v[132:135], v[202:205], v[124:127]
	v_mfma_f32_16x16x32_bf16 v[120:123], v[140:143], v[202:205], v[120:123]
	v_mfma_f32_16x16x32_bf16 v[108:111], v[132:135], v[210:213], v[108:111]
	v_mfma_f32_16x16x32_bf16 v[104:107], v[140:143], v[210:213], v[104:107]
	v_mfma_f32_16x16x32_bf16 v[92:95], v[132:135], v[218:221], v[92:95]
	v_mfma_f32_16x16x32_bf16 v[88:91], v[140:143], v[218:221], v[88:91]
	v_mfma_f32_16x16x32_bf16 v[76:79], v[132:135], v[226:229], v[76:79]
	v_mfma_f32_16x16x32_bf16 v[72:75], v[140:143], v[226:229], v[72:75]
	v_mfma_f32_16x16x32_bf16 v[116:119], v[166:169], v[198:201], v[116:119]
	v_mfma_f32_16x16x32_bf16 v[112:115], v[190:193], v[198:201], v[112:115]
	v_mfma_f32_16x16x32_bf16 v[100:103], v[166:169], v[206:209], v[100:103]
	v_mfma_f32_16x16x32_bf16 v[96:99], v[190:193], v[206:209], v[96:99]
	v_mfma_f32_16x16x32_bf16 v[84:87], v[166:169], v[214:217], v[84:87]
	v_mfma_f32_16x16x32_bf16 v[80:83], v[190:193], v[214:217], v[80:83]
	v_mfma_f32_16x16x32_bf16 v[68:71], v[166:169], v[222:225], v[68:71]
	v_mfma_f32_16x16x32_bf16 v[64:67], v[190:193], v[222:225], v[64:67]
	v_mfma_f32_16x16x32_bf16 v[116:119], v[170:173], v[202:205], v[116:119]
	v_mfma_f32_16x16x32_bf16 v[112:115], v[194:197], v[202:205], v[112:115]
	v_mfma_f32_16x16x32_bf16 v[100:103], v[170:173], v[210:213], v[100:103]
	v_mfma_f32_16x16x32_bf16 v[96:99], v[194:197], v[210:213], v[96:99]
	v_mfma_f32_16x16x32_bf16 v[84:87], v[170:173], v[218:221], v[84:87]
	v_mfma_f32_16x16x32_bf16 v[80:83], v[194:197], v[218:221], v[80:83]
	v_mfma_f32_16x16x32_bf16 v[68:71], v[170:173], v[226:229], v[68:71]
	v_mfma_f32_16x16x32_bf16 v[64:67], v[194:197], v[226:229], v[64:67]
	s_setprio 0
	s_barrier
	s_add_i32 s20, s20, s90
	v_lshl_add_u64 v[174:175], v[174:175], 0, s[26:27]
	s_mov_b32 m0, s20
	ds_read_b128 v[198:201], v181 offset:49152
	ds_read_b128 v[202:205], v181 offset:50176
	ds_read_b128 v[206:209], v181 offset:51200
	ds_read_b128 v[210:213], v181 offset:52224
	ds_read_b128 v[214:217], v181 offset:53248
	ds_read_b128 v[218:221], v181 offset:54272
	ds_read_b128 v[222:225], v181 offset:55296
	ds_read_b128 v[226:229], v181 offset:56320
	global_load_lds_dwordx4 v[174:175], off
	s_add_i32 m0, s20, 0x2000
	s_add_u32 s36, s82, 0x40080
	v_lshl_add_u64 v[174:175], v[186:187], 0, s[26:27]
	s_addc_u32 s37, s83, 0
	s_add_i32 s20, s21, s90
	global_load_lds_dwordx4 v[174:175], off
	s_mov_b32 m0, s20
	s_nop 0
	global_load_lds_dwordx4 v148, s[36:37]
	s_add_i32 m0, s20, 0x2000
	s_nop 0
	global_load_lds_dwordx4 v144, s[36:37]
	v_lshl_add_u64 v[174:175], v[230:231], 0, s[26:27]
	s_mov_b32 m0, s42
	s_nop 0
	global_load_lds_dwordx4 v[174:175], off
	v_lshl_add_u64 v[174:175], v[232:233], 0, s[26:27]
	s_mov_b32 m0, s43
	s_nop 0
	global_load_lds_dwordx4 v[174:175], off
	s_waitcnt vmcnt(8)
	s_waitcnt lgkmcnt(0)
	s_barrier
	s_setprio 1
	v_mfma_f32_16x16x32_bf16 v[60:63], v[128:131], v[198:201], v[60:63]
	v_mfma_f32_16x16x32_bf16 v[56:59], v[136:139], v[198:201], v[56:59]
	v_mfma_f32_16x16x32_bf16 v[44:47], v[128:131], v[206:209], v[44:47]
	v_mfma_f32_16x16x32_bf16 v[40:43], v[136:139], v[206:209], v[40:43]
	v_mfma_f32_16x16x32_bf16 v[28:31], v[128:131], v[214:217], v[28:31]
	v_mfma_f32_16x16x32_bf16 v[24:27], v[136:139], v[214:217], v[24:27]
	v_mfma_f32_16x16x32_bf16 v[12:15], v[128:131], v[222:225], v[12:15]
	v_mfma_f32_16x16x32_bf16 v[8:11], v[136:139], v[222:225], v[8:11]
	v_mfma_f32_16x16x32_bf16 v[60:63], v[132:135], v[202:205], v[60:63]
	v_mfma_f32_16x16x32_bf16 v[56:59], v[140:143], v[202:205], v[56:59]
	v_mfma_f32_16x16x32_bf16 v[44:47], v[132:135], v[210:213], v[44:47]
	v_mfma_f32_16x16x32_bf16 v[40:43], v[140:143], v[210:213], v[40:43]
	v_mfma_f32_16x16x32_bf16 v[28:31], v[132:135], v[218:221], v[28:31]
	v_mfma_f32_16x16x32_bf16 v[24:27], v[140:143], v[218:221], v[24:27]
	v_mfma_f32_16x16x32_bf16 v[12:15], v[132:135], v[226:229], v[12:15]
	v_mfma_f32_16x16x32_bf16 v[8:11], v[140:143], v[226:229], v[8:11]
	v_mfma_f32_16x16x32_bf16 v[52:55], v[166:169], v[198:201], v[52:55]
	v_mfma_f32_16x16x32_bf16 v[48:51], v[190:193], v[198:201], v[48:51]
	v_mfma_f32_16x16x32_bf16 v[36:39], v[166:169], v[206:209], v[36:39]
	v_mfma_f32_16x16x32_bf16 v[32:35], v[190:193], v[206:209], v[32:35]
	v_mfma_f32_16x16x32_bf16 v[20:23], v[166:169], v[214:217], v[20:23]
	v_mfma_f32_16x16x32_bf16 v[16:19], v[190:193], v[214:217], v[16:19]
	v_mfma_f32_16x16x32_bf16 v[4:7], v[166:169], v[222:225], v[4:7]
	v_mfma_f32_16x16x32_bf16 v[0:3], v[190:193], v[222:225], v[0:3]
	v_mfma_f32_16x16x32_bf16 v[52:55], v[170:173], v[202:205], v[52:55]
	v_mfma_f32_16x16x32_bf16 v[48:51], v[194:197], v[202:205], v[48:51]
	v_mfma_f32_16x16x32_bf16 v[36:39], v[170:173], v[210:213], v[36:39]
	v_mfma_f32_16x16x32_bf16 v[32:35], v[194:197], v[210:213], v[32:35]
	v_mfma_f32_16x16x32_bf16 v[20:23], v[170:173], v[218:221], v[20:23]
	v_mfma_f32_16x16x32_bf16 v[16:19], v[194:197], v[218:221], v[16:19]
	v_mfma_f32_16x16x32_bf16 v[4:7], v[170:173], v[226:229], v[4:7]
	v_mfma_f32_16x16x32_bf16 v[0:3], v[194:197], v[226:229], v[0:3]
	s_setprio 0
	s_barrier
	s_add_i32 s35, s35, 2
	s_add_u32 s80, s80, 0x100
	s_addc_u32 s81, s81, 0
	s_add_u32 vcc_hi, vcc_hi, 0x100
	s_addc_u32 s34, s34, 0
	s_cmp_gt_u32 s35, 13
	s_cbranch_scc0 .LBB0_96
	s_and_b64 vcc, exec, s[28:29]
	s_cbranch_vccz .LBB0_99
	s_barrier

; #define PG8_STAGE(bufoff, gbase, voff) do { _Pragma("unroll") for (int _i = 0; _i < 2; ++_i) \
;         __builtin_amdgcn_global_load_lds((const unsigned*)((const char*)(gbase) + (voff)[_i]), (PG8_LAS unsigned*)(lds + (bufoff) + ldsw + _i * 8192), 16, 0, 0); } while (0)
; #define PG8_LDA(dst, b, h) do { _Pragma("unroll") for (int m = 0; m < 4; ++m) _Pragma("unroll") for (int k = 0; k < 2; ++k) dst[m][k] = *(const PG8_LAS bf16x8*)(lds + PG8_SA(b, h) + aoff + m * 2048 + k * 1024); } while (0)
; #define PG8_LDB(dst, b, h) do { _Pragma("unroll") for (int n = 0; n < 2; ++n) _Pragma("unroll") for (int k = 0; k < 2; ++k) dst[n][k] = *(const PG8_LAS bf16x8*)(lds + PG8_SB(b, h) + boff + n * 2048 + k * 1024); } while (0)
; #define PG8_MMA(ai, bj, At, Bt) do { __builtin_amdgcn_s_setprio(1); _Pragma("unroll") for (int m = 0; m < 4; ++m) _Pragma("unroll") for (int n = 0; n < 2; ++n) _Pragma("unroll") for (int k = 0; k < 2; ++k) \
;         acc[ai][bj][m][n] = __builtin_amdgcn_mfma_f32_16x16x32_bf16(Bt[n][k], At[m][k], acc[ai][bj][m][n], 0, 0, 0); __builtin_amdgcn_s_setprio(0); } while (0)
; #define PG8_WAIT_V(n) asm volatile("s_waitcnt vmcnt(" #n ")" ::: "memory")
; #define PG8_WAIT_L(n) asm volatile("s_waitcnt lgkmcnt(" #n ")" ::: "memory")
; #define PG8_BAR __builtin_amdgcn_s_barrier()
; #define PG8_SCHED __builtin_amdgcn_sched_barrier(0)
; template <class Epi, class Sched, bool ALIGN_EPI = false, bool SP2 = false>
; __device__ __forceinline__ void gemm_phase(PG8_LAS unsigned char* lds, const Gemm g, const Sched& S, const Epi& E) {
;     ...
;             const char* a1 = cA + (size_t)(t + 1) * kstep;
;             const char* a2 = last ? nA : cA + (size_t)(t + 2) * kstep; const char* b2 = last ? nB : cB + (size_t)(t + 2) * kstep;
;             const char* a3 = a2 + kstep; const char* b3 = b2 + kstep;
;             if (last && has_next) S.a_ready(nxt);
;             if constexpr (SP2) {
;             PG8_LDB(B0, 0, 0); PG8_LDB(B1, 0, 1); PG8_SCHED; PG8_LDA(At, 0, 0); PG8_STAGE(PG8_SA(1, 1), a1 + hstep, voffA);
;             PG8_WAIT_V(8); PG8_WAIT_L(0); PG8_BAR; PG8_MMA(0, 0, At, B0); PG8_MMA(0, 1, At, B1); PG8_BAR; PG8_SCHED;
;             PG8_LDA(At, 0, 1); PG8_STAGE(PG8_SB(0, 0), b2, voffB); PG8_STAGE(PG8_SB(0, 1), b2 + hstep, voffB); PG8_STAGE(PG8_SA(0, 0), a2, voffA);
.LBB0_150:
	s_add_u32 s24, s22, 0xfffc0080
	s_addc_u32 s25, s23, -1
	s_waitcnt lgkmcnt(0)
	s_add_i32 s54, 0, 0x10000
	v_add_u32_e32 v147, s54, v152
	ds_read_b128 v[156:159], v147
	ds_read_b128 v[160:163], v147 offset:1024
	ds_read_b128 v[164:167], v147 offset:2048
	ds_read_b128 v[168:171], v147 offset:3072
	ds_read_b128 v[172:175], v154
	ds_read_b128 v[176:179], v154 offset:1024
	ds_read_b128 v[182:185], v154 offset:2048
	ds_read_b128 v[190:193], v154 offset:3072
	s_cmp_eq_u32 s49, 12
	s_cselect_b32 s27, s17, s25
	s_cselect_b32 s26, s45, s24
	s_cselect_b32 s25, s15, s48
	s_cselect_b32 s24, s46, s47
	s_add_i32 m0, s13, 0xc000
	ds_read_b128 v[194:197], v155
	ds_read_b128 v[198:201], v155 offset:1024
	ds_read_b128 v[202:205], v155 offset:2048
	ds_read_b128 v[206:209], v155 offset:3072
	ds_read_b128 v[210:213], v155 offset:4096
	ds_read_b128 v[214:217], v155 offset:5120
	ds_read_b128 v[218:221], v155 offset:6144
	ds_read_b128 v[222:225], v155 offset:7168
	global_load_lds_dwordx4 v138, s[22:23]
	s_add_i32 m0, s13, 0xe000
	s_nop 0
	global_load_lds_dwordx4 v140, s[22:23]
	s_waitcnt vmcnt(8)
	s_waitcnt lgkmcnt(0)
	s_barrier
	s_setprio 1
	v_mfma_f32_16x16x32_bf16 v[124:127], v[156:159], v[194:197], v[124:127]
	v_mfma_f32_16x16x32_bf16 v[120:123], v[164:167], v[194:197], v[120:123]
	v_mfma_f32_16x16x32_bf16 v[116:119], v[156:159], v[202:205], v[116:119]
	v_mfma_f32_16x16x32_bf16 v[112:115], v[164:167], v[202:205], v[112:115]
	v_mfma_f32_16x16x32_bf16 v[100:103], v[156:159], v[210:213], v[100:103]
	v_mfma_f32_16x16x32_bf16 v[96:99], v[164:167], v[210:213], v[96:99]
	v_mfma_f32_16x16x32_bf16 v[84:87], v[156:159], v[218:221], v[84:87]
	v_mfma_f32_16x16x32_bf16 v[80:83], v[164:167], v[218:221], v[80:83]
	v_mfma_f32_16x16x32_bf16 v[124:127], v[160:163], v[198:201], v[124:127]
	v_mfma_f32_16x16x32_bf16 v[120:123], v[168:171], v[198:201], v[120:123]
	v_mfma_f32_16x16x32_bf16 v[116:119], v[160:163], v[206:209], v[116:119]
	v_mfma_f32_16x16x32_bf16 v[112:115], v[168:171], v[206:209], v[112:115]
	v_mfma_f32_16x16x32_bf16 v[100:103], v[160:163], v[214:217], v[100:103]
	v_mfma_f32_16x16x32_bf16 v[96:99], v[168:171], v[214:217], v[96:99]
	v_mfma_f32_16x16x32_bf16 v[84:87], v[160:163], v[222:225], v[84:87]
	v_mfma_f32_16x16x32_bf16 v[80:83], v[168:171], v[222:225], v[80:83]
	v_mfma_f32_16x16x32_bf16 v[108:111], v[172:175], v[194:197], v[108:111]
	v_mfma_f32_16x16x32_bf16 v[104:107], v[182:185], v[194:197], v[104:107]
	v_mfma_f32_16x16x32_bf16 v[92:95], v[172:175], v[202:205], v[92:95]
	v_mfma_f32_16x16x32_bf16 v[88:91], v[182:185], v[202:205], v[88:91]
	v_mfma_f32_16x16x32_bf16 v[76:79], v[172:175], v[210:213], v[76:79]
	v_mfma_f32_16x16x32_bf16 v[72:75], v[182:185], v[210:213], v[72:75]
	v_mfma_f32_16x16x32_bf16 v[68:71], v[172:175], v[218:221], v[68:71]
	v_mfma_f32_16x16x32_bf16 v[64:67], v[182:185], v[218:221], v[64:67]
	v_mfma_f32_16x16x32_bf16 v[108:111], v[176:179], v[198:201], v[108:111]
	v_mfma_f32_16x16x32_bf16 v[104:107], v[190:193], v[198:201], v[104:107]
	v_mfma_f32_16x16x32_bf16 v[92:95], v[176:179], v[206:209], v[92:95]
	v_mfma_f32_16x16x32_bf16 v[88:91], v[190:193], v[206:209], v[88:91]
	v_mfma_f32_16x16x32_bf16 v[76:79], v[176:179], v[214:217], v[76:79]
	v_mfma_f32_16x16x32_bf16 v[72:75], v[190:193], v[214:217], v[72:75]
	v_mfma_f32_16x16x32_bf16 v[68:71], v[176:179], v[222:225], v[68:71]
	v_mfma_f32_16x16x32_bf16 v[64:67], v[190:193], v[222:225], v[64:67]
	s_setprio 0
	s_barrier
	s_add_i32 s54, s54, s31
	v_lshl_add_u64 v[186:187], s[24:25], 0, v[130:131]
	s_mov_b32 m0, s54
	ds_read_b128 v[194:197], v155 offset:16384
	ds_read_b128 v[198:201], v155 offset:17408
	ds_read_b128 v[202:205], v155 offset:18432
	ds_read_b128 v[206:209], v155 offset:19456
	ds_read_b128 v[210:213], v155 offset:20480
	ds_read_b128 v[214:217], v155 offset:21504
	ds_read_b128 v[218:221], v155 offset:22528
	ds_read_b128 v[222:225], v155 offset:23552
	global_load_lds_dwordx4 v[186:187], off
	s_add_i32 m0, s54, 0x2000
	s_add_u32 s54, s24, 0x40000
	v_lshl_add_u64 v[226:227], s[24:25], 0, v[134:135]
	s_addc_u32 s55, s25, 0
	s_add_i32 s76, s43, s31
	global_load_lds_dwordx4 v[226:227], off
	s_mov_b32 m0, s76
	v_lshl_add_u64 v[230:231], s[26:27], 0, v[132:133]
	global_load_lds_dwordx4 v130, s[54:55]
	s_add_i32 m0, s76, 0x2000
	s_nop 0
	global_load_lds_dwordx4 v134, s[54:55]
	v_lshl_add_u64 v[228:229], s[26:27], 0, v[128:129]
	s_mov_b32 m0, s13
	s_nop 0
	global_load_lds_dwordx4 v[228:229], off
	s_mov_b32 m0, s34
	s_nop 0
	global_load_lds_dwordx4 v[230:231], off
	s_waitcnt vmcnt(8)
	s_waitcnt lgkmcnt(0)
	s_barrier
; #define PG8_STAGE(bufoff, gbase, voff) do { _Pragma("unroll") for (int _i = 0; _i < 2; ++_i) \
;         __builtin_amdgcn_global_load_lds((const unsigned*)((const char*)(gbase) + (voff)[_i]), (PG8_LAS unsigned*)(lds + (bufoff) + ldsw + _i * 8192), 16, 0, 0); } while (0)
; #define PG8_LDA(dst, b, h) do { _Pragma("unroll") for (int m = 0; m < 4; ++m) _Pragma("unroll") for (int k = 0; k < 2; ++k) dst[m][k] = *(const PG8_LAS bf16x8*)(lds + PG8_SA(b, h) + aoff + m * 2048 + k * 1024); } while (0)
; #define PG8_LDB(dst, b, h) do { _Pragma("unroll") for (int n = 0; n < 2; ++n) _Pragma("unroll") for (int k = 0; k < 2; ++k) dst[n][k] = *(const PG8_LAS bf16x8*)(lds + PG8_SB(b, h) + boff + n * 2048 + k * 1024); } while (0)
; #define PG8_MMA(ai, bj, At, Bt) do { __builtin_amdgcn_s_setprio(1); _Pragma("unroll") for (int m = 0; m < 4; ++m) _Pragma("unroll") for (int n = 0; n < 2; ++n) _Pragma("unroll") for (int k = 0; k < 2; ++k) \
;         acc[ai][bj][m][n] = __builtin_amdgcn_mfma_f32_16x16x32_bf16(Bt[n][k], At[m][k], acc[ai][bj][m][n], 0, 0, 0); __builtin_amdgcn_s_setprio(0); } while (0)
; #define PG8_WAIT_V(n) asm volatile("s_waitcnt vmcnt(" #n ")" ::: "memory")
; #define PG8_WAIT_L(n) asm volatile("s_waitcnt lgkmcnt(" #n ")" ::: "memory")
; #define PG8_BAR __builtin_amdgcn_s_barrier()
; #define PG8_SCHED __builtin_amdgcn_sched_barrier(0)
; template <class Epi, class Sched, bool ALIGN_EPI = false, bool SP2 = false>
; __device__ __forceinline__ void gemm_phase(PG8_LAS unsigned char* lds, const Gemm g, const Sched& S, const Epi& E) {
;     ...
;             PG8_WAIT_V(8); PG8_WAIT_L(0); PG8_BAR; PG8_MMA(1, 0, At, B0); PG8_MMA(1, 1, At, B1); PG8_BAR; PG8_SCHED;
;             PG8_LDB(B0, 1, 0); PG8_LDB(B1, 1, 1); PG8_SCHED; PG8_LDA(At, 1, 0); PG8_STAGE(PG8_SA(0, 1), a2 + hstep, voffA);
;             PG8_WAIT_V(8); PG8_WAIT_L(0); PG8_BAR; PG8_MMA(0, 0, At, B0); PG8_MMA(0, 1, At, B1); PG8_BAR; PG8_SCHED;
	s_setprio 1
	v_mfma_f32_16x16x32_bf16 v[60:63], v[156:159], v[194:197], v[60:63]
	v_mfma_f32_16x16x32_bf16 v[56:59], v[164:167], v[194:197], v[56:59]
	v_mfma_f32_16x16x32_bf16 v[52:55], v[156:159], v[202:205], v[52:55]
	v_mfma_f32_16x16x32_bf16 v[48:51], v[164:167], v[202:205], v[48:51]
	v_mfma_f32_16x16x32_bf16 v[36:39], v[156:159], v[210:213], v[36:39]
	v_mfma_f32_16x16x32_bf16 v[32:35], v[164:167], v[210:213], v[32:35]
	v_mfma_f32_16x16x32_bf16 v[20:23], v[156:159], v[218:221], v[20:23]
	v_mfma_f32_16x16x32_bf16 v[16:19], v[164:167], v[218:221], v[16:19]
	v_mfma_f32_16x16x32_bf16 v[60:63], v[160:163], v[198:201], v[60:63]
	v_mfma_f32_16x16x32_bf16 v[56:59], v[168:171], v[198:201], v[56:59]
	v_mfma_f32_16x16x32_bf16 v[52:55], v[160:163], v[206:209], v[52:55]
	v_mfma_f32_16x16x32_bf16 v[48:51], v[168:171], v[206:209], v[48:51]
	v_mfma_f32_16x16x32_bf16 v[36:39], v[160:163], v[214:217], v[36:39]
	v_mfma_f32_16x16x32_bf16 v[32:35], v[168:171], v[214:217], v[32:35]
	v_mfma_f32_16x16x32_bf16 v[20:23], v[160:163], v[222:225], v[20:23]
	v_mfma_f32_16x16x32_bf16 v[16:19], v[168:171], v[222:225], v[16:19]
	v_mfma_f32_16x16x32_bf16 v[44:47], v[172:175], v[194:197], v[44:47]
	v_mfma_f32_16x16x32_bf16 v[40:43], v[182:185], v[194:197], v[40:43]
	v_mfma_f32_16x16x32_bf16 v[28:31], v[172:175], v[202:205], v[28:31]
	v_mfma_f32_16x16x32_bf16 v[24:27], v[182:185], v[202:205], v[24:27]
	v_mfma_f32_16x16x32_bf16 v[12:15], v[172:175], v[210:213], v[12:15]
	v_mfma_f32_16x16x32_bf16 v[8:11], v[182:185], v[210:213], v[8:11]
	v_mfma_f32_16x16x32_bf16 v[4:7], v[172:175], v[218:221], v[4:7]
	v_mfma_f32_16x16x32_bf16 v[0:3], v[182:185], v[218:221], v[0:3]
	v_mfma_f32_16x16x32_bf16 v[44:47], v[176:179], v[198:201], v[44:47]
	v_mfma_f32_16x16x32_bf16 v[40:43], v[190:193], v[198:201], v[40:43]
	v_mfma_f32_16x16x32_bf16 v[28:31], v[176:179], v[206:209], v[28:31]
	v_mfma_f32_16x16x32_bf16 v[24:27], v[190:193], v[206:209], v[24:27]
	v_mfma_f32_16x16x32_bf16 v[12:15], v[176:179], v[214:217], v[12:15]
	v_mfma_f32_16x16x32_bf16 v[8:11], v[190:193], v[214:217], v[8:11]
	v_mfma_f32_16x16x32_bf16 v[4:7], v[176:179], v[222:225], v[4:7]
	v_mfma_f32_16x16x32_bf16 v[0:3], v[190:193], v[222:225], v[0:3]
	s_setprio 0
	s_barrier
	s_add_i32 s54, 0, 0x18000
	v_add_u32_e32 v147, s54, v152
	s_add_i32 s55, 0, 0x1c000
	ds_read_b128 v[156:159], v147
	ds_read_b128 v[160:163], v147 offset:1024
	ds_read_b128 v[164:167], v147 offset:2048
	ds_read_b128 v[168:171], v147 offset:3072
	v_add_u32_e32 v147, s55, v152
	ds_read_b128 v[172:175], v147
	ds_read_b128 v[176:179], v147 offset:1024
	ds_read_b128 v[182:185], v147 offset:2048
	ds_read_b128 v[190:193], v147 offset:3072
	s_add_u32 s26, s26, 0x40000
	s_addc_u32 s27, s27, 0
	s_mov_b32 m0, s35
	ds_read_b128 v[194:197], v155 offset:32768
	ds_read_b128 v[198:201], v155 offset:33792
	ds_read_b128 v[202:205], v155 offset:34816
	ds_read_b128 v[206:209], v155 offset:35840
	ds_read_b128 v[210:213], v155 offset:36864
	ds_read_b128 v[214:217], v155 offset:37888
	ds_read_b128 v[218:221], v155 offset:38912
	ds_read_b128 v[222:225], v155 offset:39936
	global_load_lds_dwordx4 v128, s[26:27]
	s_mov_b32 m0, s36
	s_nop 0
	global_load_lds_dwordx4 v132, s[26:27]
	s_waitcnt vmcnt(8)
	s_waitcnt lgkmcnt(0)
	s_barrier
	s_setprio 1
	v_mfma_f32_16x16x32_bf16 v[124:127], v[156:159], v[194:197], v[124:127]
	v_mfma_f32_16x16x32_bf16 v[120:123], v[164:167], v[194:197], v[120:123]
	v_mfma_f32_16x16x32_bf16 v[116:119], v[156:159], v[202:205], v[116:119]
	v_mfma_f32_16x16x32_bf16 v[112:115], v[164:167], v[202:205], v[112:115]
	v_mfma_f32_16x16x32_bf16 v[100:103], v[156:159], v[210:213], v[100:103]
	v_mfma_f32_16x16x32_bf16 v[96:99], v[164:167], v[210:213], v[96:99]
	v_mfma_f32_16x16x32_bf16 v[84:87], v[156:159], v[218:221], v[84:87]
	v_mfma_f32_16x16x32_bf16 v[80:83], v[164:167], v[218:221], v[80:83]
	v_mfma_f32_16x16x32_bf16 v[124:127], v[160:163], v[198:201], v[124:127]
	v_mfma_f32_16x16x32_bf16 v[120:123], v[168:171], v[198:201], v[120:123]
	v_mfma_f32_16x16x32_bf16 v[116:119], v[160:163], v[206:209], v[116:119]
	v_mfma_f32_16x16x32_bf16 v[112:115], v[168:171], v[206:209], v[112:115]
	v_mfma_f32_16x16x32_bf16 v[100:103], v[160:163], v[214:217], v[100:103]
	v_mfma_f32_16x16x32_bf16 v[96:99], v[168:171], v[214:217], v[96:99]
	v_mfma_f32_16x16x32_bf16 v[84:87], v[160:163], v[222:225], v[84:87]
	v_mfma_f32_16x16x32_bf16 v[80:83], v[168:171], v[222:225], v[80:83]
	v_mfma_f32_16x16x32_bf16 v[108:111], v[172:175], v[194:197], v[108:111]
	v_mfma_f32_16x16x32_bf16 v[104:107], v[182:185], v[194:197], v[104:107]
	v_mfma_f32_16x16x32_bf16 v[92:95], v[172:175], v[202:205], v[92:95]
	v_mfma_f32_16x16x32_bf16 v[88:91], v[182:185], v[202:205], v[88:91]
	v_mfma_f32_16x16x32_bf16 v[76:79], v[172:175], v[210:213], v[76:79]
	v_mfma_f32_16x16x32_bf16 v[72:75], v[182:185], v[210:213], v[72:75]
	v_mfma_f32_16x16x32_bf16 v[68:71], v[172:175], v[218:221], v[68:71]
	v_mfma_f32_16x16x32_bf16 v[64:67], v[182:185], v[218:221], v[64:67]
	v_mfma_f32_16x16x32_bf16 v[108:111], v[176:179], v[198:201], v[108:111]
	v_mfma_f32_16x16x32_bf16 v[104:107], v[190:193], v[198:201], v[104:107]
	v_mfma_f32_16x16x32_bf16 v[92:95], v[176:179], v[206:209], v[92:95]
	v_mfma_f32_16x16x32_bf16 v[88:91], v[190:193], v[206:209], v[88:91]
	v_mfma_f32_16x16x32_bf16 v[76:79], v[176:179], v[214:217], v[76:79]
	v_mfma_f32_16x16x32_bf16 v[72:75], v[190:193], v[214:217], v[72:75]
	v_mfma_f32_16x16x32_bf16 v[68:71], v[176:179], v[222:225], v[68:71]
	v_mfma_f32_16x16x32_bf16 v[64:67], v[190:193], v[222:225], v[64:67]
	s_setprio 0
	s_barrier
; #define PG8_STAGE(bufoff, gbase, voff) do { _Pragma("unroll") for (int _i = 0; _i < 2; ++_i) \
;         __builtin_amdgcn_global_load_lds((const unsigned*)((const char*)(gbase) + (voff)[_i]), (PG8_LAS unsigned*)(lds + (bufoff) + ldsw + _i * 8192), 16, 0, 0); } while (0)
; #define PG8_LDA(dst, b, h) do { _Pragma("unroll") for (int m = 0; m < 4; ++m) _Pragma("unroll") for (int k = 0; k < 2; ++k) dst[m][k] = *(const PG8_LAS bf16x8*)(lds + PG8_SA(b, h) + aoff + m * 2048 + k * 1024); } while (0)
; #define PG8_MMA(ai, bj, At, Bt) do { __builtin_amdgcn_s_setprio(1); _Pragma("unroll") for (int m = 0; m < 4; ++m) _Pragma("unroll") for (int n = 0; n < 2; ++n) _Pragma("unroll") for (int k = 0; k < 2; ++k) \
;         acc[ai][bj][m][n] = __builtin_amdgcn_mfma_f32_16x16x32_bf16(Bt[n][k], At[m][k], acc[ai][bj][m][n], 0, 0, 0); __builtin_amdgcn_s_setprio(0); } while (0)
; #define PG8_WAIT_V(n) asm volatile("s_waitcnt vmcnt(" #n ")" ::: "memory")
; #define PG8_WAIT_L(n) asm volatile("s_waitcnt lgkmcnt(" #n ")" ::: "memory")
; #define PG8_BAR __builtin_amdgcn_s_barrier()
; #define PG8_SCHED __builtin_amdgcn_sched_barrier(0)
; template <class Epi, class Sched, bool ALIGN_EPI = false, bool SP2 = false>
; __device__ __forceinline__ void gemm_phase(PG8_LAS unsigned char* lds, const Gemm g, const Sched& S, const Epi& E) {
;     ...
;         for (int t = 0; t < nt; t += 2) {
;             const bool last = (t == nt - 2);
;     ...
;             PG8_LDA(At, 1, 1); PG8_STAGE(PG8_SB(1, 0), b3, voffB); PG8_STAGE(PG8_SB(1, 1), b3 + hstep, voffB); PG8_STAGE(PG8_SA(1, 0), a3, voffA);
;             PG8_WAIT_V(8); PG8_WAIT_L(0); PG8_BAR; PG8_MMA(1, 0, At, B0); PG8_MMA(1, 1, At, B1); PG8_BAR; PG8_SCHED;
	s_add_i32 s26, s54, s31
	v_lshl_add_u64 v[186:187], v[186:187], 0, s[8:9]
	s_mov_b32 m0, s26
	ds_read_b128 v[194:197], v155 offset:49152
	ds_read_b128 v[198:201], v155 offset:50176
	ds_read_b128 v[202:205], v155 offset:51200
	ds_read_b128 v[206:209], v155 offset:52224
	ds_read_b128 v[210:213], v155 offset:53248
	ds_read_b128 v[214:217], v155 offset:54272
	ds_read_b128 v[218:221], v155 offset:55296
	ds_read_b128 v[222:225], v155 offset:56320
	global_load_lds_dwordx4 v[186:187], off
	s_add_i32 m0, s26, 0x2000
	s_add_u32 s24, s24, 0x40080
	v_lshl_add_u64 v[186:187], v[226:227], 0, s[8:9]
	s_addc_u32 s25, s25, 0
	s_add_i32 s26, s55, s31
	global_load_lds_dwordx4 v[186:187], off
	s_mov_b32 m0, s26
	s_nop 0
	global_load_lds_dwordx4 v130, s[24:25]
	s_add_i32 m0, s26, 0x2000
	s_nop 0
	global_load_lds_dwordx4 v134, s[24:25]
	v_lshl_add_u64 v[186:187], v[228:229], 0, s[8:9]
	s_mov_b32 m0, s39
	s_nop 0
	global_load_lds_dwordx4 v[186:187], off
	v_lshl_add_u64 v[186:187], v[230:231], 0, s[8:9]
	s_mov_b32 m0, s40
	s_nop 0
	global_load_lds_dwordx4 v[186:187], off
	s_waitcnt vmcnt(8)
	s_waitcnt lgkmcnt(0)
	s_barrier
	s_setprio 1
	v_mfma_f32_16x16x32_bf16 v[60:63], v[156:159], v[194:197], v[60:63]
	v_mfma_f32_16x16x32_bf16 v[56:59], v[164:167], v[194:197], v[56:59]
	v_mfma_f32_16x16x32_bf16 v[52:55], v[156:159], v[202:205], v[52:55]
	v_mfma_f32_16x16x32_bf16 v[48:51], v[164:167], v[202:205], v[48:51]
	v_mfma_f32_16x16x32_bf16 v[36:39], v[156:159], v[210:213], v[36:39]
	v_mfma_f32_16x16x32_bf16 v[32:35], v[164:167], v[210:213], v[32:35]
	v_mfma_f32_16x16x32_bf16 v[20:23], v[156:159], v[218:221], v[20:23]
	v_mfma_f32_16x16x32_bf16 v[16:19], v[164:167], v[218:221], v[16:19]
	v_mfma_f32_16x16x32_bf16 v[60:63], v[160:163], v[198:201], v[60:63]
	v_mfma_f32_16x16x32_bf16 v[56:59], v[168:171], v[198:201], v[56:59]
	v_mfma_f32_16x16x32_bf16 v[52:55], v[160:163], v[206:209], v[52:55]
	v_mfma_f32_16x16x32_bf16 v[48:51], v[168:171], v[206:209], v[48:51]
	v_mfma_f32_16x16x32_bf16 v[36:39], v[160:163], v[214:217], v[36:39]
	v_mfma_f32_16x16x32_bf16 v[32:35], v[168:171], v[214:217], v[32:35]
	v_mfma_f32_16x16x32_bf16 v[20:23], v[160:163], v[222:225], v[20:23]
	v_mfma_f32_16x16x32_bf16 v[16:19], v[168:171], v[222:225], v[16:19]
	v_mfma_f32_16x16x32_bf16 v[44:47], v[172:175], v[194:197], v[44:47]
	v_mfma_f32_16x16x32_bf16 v[40:43], v[182:185], v[194:197], v[40:43]
	v_mfma_f32_16x16x32_bf16 v[28:31], v[172:175], v[202:205], v[28:31]
	v_mfma_f32_16x16x32_bf16 v[24:27], v[182:185], v[202:205], v[24:27]
	v_mfma_f32_16x16x32_bf16 v[12:15], v[172:175], v[210:213], v[12:15]
	v_mfma_f32_16x16x32_bf16 v[8:11], v[182:185], v[210:213], v[8:11]
	v_mfma_f32_16x16x32_bf16 v[4:7], v[172:175], v[218:221], v[4:7]
	v_mfma_f32_16x16x32_bf16 v[0:3], v[182:185], v[218:221], v[0:3]
	v_mfma_f32_16x16x32_bf16 v[44:47], v[176:179], v[198:201], v[44:47]
	v_mfma_f32_16x16x32_bf16 v[40:43], v[190:193], v[198:201], v[40:43]
	v_mfma_f32_16x16x32_bf16 v[28:31], v[176:179], v[206:209], v[28:31]
	v_mfma_f32_16x16x32_bf16 v[24:27], v[190:193], v[206:209], v[24:27]
	v_mfma_f32_16x16x32_bf16 v[12:15], v[176:179], v[214:217], v[12:15]
	v_mfma_f32_16x16x32_bf16 v[8:11], v[190:193], v[214:217], v[8:11]
	v_mfma_f32_16x16x32_bf16 v[4:7], v[176:179], v[222:225], v[4:7]
	v_mfma_f32_16x16x32_bf16 v[0:3], v[190:193], v[222:225], v[0:3]
	s_setprio 0
	s_barrier
	s_add_i32 s49, s49, 2
	s_add_u32 s22, s22, 0x100
	s_addc_u32 s23, s23, 0
	s_add_u32 s47, s47, 0x100
	s_addc_u32 s48, s48, 0
	s_cmp_gt_u32 s49, 13
	s_cbranch_scc0 .LBB0_150
	s_and_b64 vcc, exec, s[10:11]
	s_cbranch_vccz .LBB0_153
	s_barrier

; #define PG8_STAGE(bufoff, gbase, voff) do { _Pragma("unroll") for (int _i = 0; _i < 2; ++_i) \
;         __builtin_amdgcn_global_load_lds((const unsigned*)((const char*)(gbase) + (voff)[_i]), (PG8_LAS unsigned*)(lds + (bufoff) + ldsw + _i * 8192), 16, 0, 0); } while (0)
; #define PG8_LDA(dst, b, h) do { _Pragma("unroll") for (int m = 0; m < 4; ++m) _Pragma("unroll") for (int k = 0; k < 2; ++k) dst[m][k] = *(const PG8_LAS bf16x8*)(lds + PG8_SA(b, h) + aoff + m * 2048 + k * 1024); } while (0)
; #define PG8_LDB(dst, b, h) do { _Pragma("unroll") for (int n = 0; n < 2; ++n) _Pragma("unroll") for (int k = 0; k < 2; ++k) dst[n][k] = *(const PG8_LAS bf16x8*)(lds + PG8_SB(b, h) + boff + n * 2048 + k * 1024); } while (0)
; #define PG8_MMA(ai, bj, At, Bt) do { __builtin_amdgcn_s_setprio(1); _Pragma("unroll") for (int m = 0; m < 4; ++m) _Pragma("unroll") for (int n = 0; n < 2; ++n) _Pragma("unroll") for (int k = 0; k < 2; ++k) \
;         acc[ai][bj][m][n] = __builtin_amdgcn_mfma_f32_16x16x32_bf16(Bt[n][k], At[m][k], acc[ai][bj][m][n], 0, 0, 0); __builtin_amdgcn_s_setprio(0); } while (0)
; #define PG8_WAIT_V(n) asm volatile("s_waitcnt vmcnt(" #n ")" ::: "memory")
; #define PG8_WAIT_L(n) asm volatile("s_waitcnt lgkmcnt(" #n ")" ::: "memory")
; #define PG8_BAR __builtin_amdgcn_s_barrier()
; #define PG8_SCHED __builtin_amdgcn_sched_barrier(0)
; template <class Epi, class Sched, bool ALIGN_EPI = false, bool SP2 = false>
; __device__ __forceinline__ void gemm_phase(PG8_LAS unsigned char* lds, const Gemm g, const Sched& S, const Epi& E) {
;     ...
;             const char* a1 = cA + (size_t)(t + 1) * kstep;
;             const char* a2 = last ? nA : cA + (size_t)(t + 2) * kstep; const char* b2 = last ? nB : cB + (size_t)(t + 2) * kstep;
;             const char* a3 = a2 + kstep; const char* b3 = b2 + kstep;
;             if (last && has_next) S.a_ready(nxt);
;             if constexpr (SP2) {
;             PG8_LDB(B0, 0, 0); PG8_LDB(B1, 0, 1); PG8_SCHED; PG8_LDA(At, 0, 0); PG8_STAGE(PG8_SA(1, 1), a1 + hstep, voffA);
;             PG8_WAIT_V(8); PG8_WAIT_L(0); PG8_BAR; PG8_MMA(0, 0, At, B0); PG8_MMA(0, 1, At, B1); PG8_BAR; PG8_SCHED;
;             PG8_LDA(At, 0, 1); PG8_STAGE(PG8_SB(0, 0), b2, voffB); PG8_STAGE(PG8_SB(0, 1), b2 + hstep, voffB); PG8_STAGE(PG8_SA(0, 0), a2, voffA);
.LBB0_358:
	ds_read_b128 v[128:131], v178
	ds_read_b128 v[132:135], v178 offset:1024
	ds_read_b128 v[136:139], v178 offset:2048
	ds_read_b128 v[140:143], v178 offset:3072
	ds_read_b128 v[166:169], v179
	ds_read_b128 v[170:173], v179 offset:1024
	ds_read_b128 v[190:193], v179 offset:2048
	ds_read_b128 v[194:197], v179 offset:3072
	s_add_u32 s42, s40, 0xfffc0080
	s_addc_u32 s43, s41, -1
	s_cmp_eq_u32 s25, 12
	s_cselect_b32 s45, s1, s43
	s_cselect_b32 s44, s35, s42
	s_cselect_b32 s43, s31, s24
	s_cselect_b32 s42, vcc_lo, vcc_hi
	v_lshl_add_u64 v[174:175], s[40:41], 0, v[158:159]
	s_add_i32 m0, s47, 0xc000
	ds_read_b128 v[198:201], v181
	ds_read_b128 v[202:205], v181 offset:1024
	ds_read_b128 v[206:209], v181 offset:2048
	ds_read_b128 v[210:213], v181 offset:3072
	ds_read_b128 v[214:217], v181 offset:4096
	ds_read_b128 v[218:221], v181 offset:5120
	ds_read_b128 v[222:225], v181 offset:6144
	ds_read_b128 v[226:229], v181 offset:7168
	global_load_lds_dwordx4 v[174:175], off
	v_lshl_add_u64 v[174:175], s[40:41], 0, v[160:161]
	s_add_i32 m0, s47, 0xe000
	s_nop 0
	global_load_lds_dwordx4 v[174:175], off
	s_waitcnt vmcnt(8)
	s_waitcnt lgkmcnt(0)
	s_barrier
	s_setprio 1
	v_mfma_f32_16x16x32_bf16 v[124:127], v[128:131], v[198:201], v[124:127]
	v_mfma_f32_16x16x32_bf16 v[120:123], v[136:139], v[198:201], v[120:123]
	v_mfma_f32_16x16x32_bf16 v[108:111], v[128:131], v[206:209], v[108:111]
	v_mfma_f32_16x16x32_bf16 v[104:107], v[136:139], v[206:209], v[104:107]
	v_mfma_f32_16x16x32_bf16 v[92:95], v[128:131], v[214:217], v[92:95]
	v_mfma_f32_16x16x32_bf16 v[88:91], v[136:139], v[214:217], v[88:91]
	v_mfma_f32_16x16x32_bf16 v[76:79], v[128:131], v[222:225], v[76:79]
	v_mfma_f32_16x16x32_bf16 v[72:75], v[136:139], v[222:225], v[72:75]
	v_mfma_f32_16x16x32_bf16 v[124:127], v[132:135], v[202:205], v[124:127]
	v_mfma_f32_16x16x32_bf16 v[120:123], v[140:143], v[202:205], v[120:123]
	v_mfma_f32_16x16x32_bf16 v[108:111], v[132:135], v[210:213], v[108:111]
	v_mfma_f32_16x16x32_bf16 v[104:107], v[140:143], v[210:213], v[104:107]
	v_mfma_f32_16x16x32_bf16 v[92:95], v[132:135], v[218:221], v[92:95]
	v_mfma_f32_16x16x32_bf16 v[88:91], v[140:143], v[218:221], v[88:91]
	v_mfma_f32_16x16x32_bf16 v[76:79], v[132:135], v[226:229], v[76:79]
	v_mfma_f32_16x16x32_bf16 v[72:75], v[140:143], v[226:229], v[72:75]
	v_mfma_f32_16x16x32_bf16 v[116:119], v[166:169], v[198:201], v[116:119]
	v_mfma_f32_16x16x32_bf16 v[112:115], v[190:193], v[198:201], v[112:115]
	v_mfma_f32_16x16x32_bf16 v[100:103], v[166:169], v[206:209], v[100:103]
	v_mfma_f32_16x16x32_bf16 v[96:99], v[190:193], v[206:209], v[96:99]
	v_mfma_f32_16x16x32_bf16 v[84:87], v[166:169], v[214:217], v[84:87]
	v_mfma_f32_16x16x32_bf16 v[80:83], v[190:193], v[214:217], v[80:83]
	v_mfma_f32_16x16x32_bf16 v[68:71], v[166:169], v[222:225], v[68:71]
	v_mfma_f32_16x16x32_bf16 v[64:67], v[190:193], v[222:225], v[64:67]
	v_mfma_f32_16x16x32_bf16 v[116:119], v[170:173], v[202:205], v[116:119]
	v_mfma_f32_16x16x32_bf16 v[112:115], v[194:197], v[202:205], v[112:115]
	v_mfma_f32_16x16x32_bf16 v[100:103], v[170:173], v[210:213], v[100:103]
	v_mfma_f32_16x16x32_bf16 v[96:99], v[194:197], v[210:213], v[96:99]
	v_mfma_f32_16x16x32_bf16 v[84:87], v[170:173], v[218:221], v[84:87]
	v_mfma_f32_16x16x32_bf16 v[80:83], v[194:197], v[218:221], v[80:83]
	v_mfma_f32_16x16x32_bf16 v[68:71], v[170:173], v[226:229], v[68:71]
	v_mfma_f32_16x16x32_bf16 v[64:67], v[194:197], v[226:229], v[64:67]
	s_setprio 0
	s_barrier
	s_add_i32 s54, s93, s46
	v_lshl_add_u64 v[174:175], s[42:43], 0, v[146:147]
	s_mov_b32 m0, s54
	ds_read_b128 v[198:201], v181 offset:16384
	ds_read_b128 v[202:205], v181 offset:17408
	ds_read_b128 v[206:209], v181 offset:18432
	ds_read_b128 v[210:213], v181 offset:19456
	ds_read_b128 v[214:217], v181 offset:20480
	ds_read_b128 v[218:221], v181 offset:21504
	ds_read_b128 v[222:225], v181 offset:22528
	ds_read_b128 v[226:229], v181 offset:23552
	global_load_lds_dwordx4 v[174:175], off
	s_add_i32 m0, s54, 0x2000
	s_add_u32 s54, s42, 0x40000
	v_lshl_add_u64 v[186:187], s[42:43], 0, v[150:151]
	s_addc_u32 s55, s43, 0
	s_add_i32 s23, s94, s46
	global_load_lds_dwordx4 v[186:187], off
	v_lshl_add_u64 v[230:231], s[54:55], 0, v[146:147]
	s_mov_b32 m0, s23
	v_lshl_add_u64 v[232:233], s[44:45], 0, v[148:149]
	global_load_lds_dwordx4 v[230:231], off
	v_lshl_add_u64 v[230:231], s[54:55], 0, v[150:151]
	s_add_i32 m0, s23, 0x2000
	s_nop 0
	global_load_lds_dwordx4 v[230:231], off
	v_lshl_add_u64 v[230:231], s[44:45], 0, v[144:145]
	s_mov_b32 m0, s47
	s_nop 0
	global_load_lds_dwordx4 v[230:231], off
	s_mov_b32 m0, s48
	s_nop 0
	global_load_lds_dwordx4 v[232:233], off
	s_waitcnt vmcnt(8)
	s_waitcnt lgkmcnt(0)
	s_barrier
; #define PG8_STAGE(bufoff, gbase, voff) do { _Pragma("unroll") for (int _i = 0; _i < 2; ++_i) \
;         __builtin_amdgcn_global_load_lds((const unsigned*)((const char*)(gbase) + (voff)[_i]), (PG8_LAS unsigned*)(lds + (bufoff) + ldsw + _i * 8192), 16, 0, 0); } while (0)
; #define PG8_LDA(dst, b, h) do { _Pragma("unroll") for (int m = 0; m < 4; ++m) _Pragma("unroll") for (int k = 0; k < 2; ++k) dst[m][k] = *(const PG8_LAS bf16x8*)(lds + PG8_SA(b, h) + aoff + m * 2048 + k * 1024); } while (0)
; #define PG8_LDB(dst, b, h) do { _Pragma("unroll") for (int n = 0; n < 2; ++n) _Pragma("unroll") for (int k = 0; k < 2; ++k) dst[n][k] = *(const PG8_LAS bf16x8*)(lds + PG8_SB(b, h) + boff + n * 2048 + k * 1024); } while (0)
; #define PG8_MMA(ai, bj, At, Bt) do { __builtin_amdgcn_s_setprio(1); _Pragma("unroll") for (int m = 0; m < 4; ++m) _Pragma("unroll") for (int n = 0; n < 2; ++n) _Pragma("unroll") for (int k = 0; k < 2; ++k) \
;         acc[ai][bj][m][n] = __builtin_amdgcn_mfma_f32_16x16x32_bf16(Bt[n][k], At[m][k], acc[ai][bj][m][n], 0, 0, 0); __builtin_amdgcn_s_setprio(0); } while (0)
; #define PG8_WAIT_V(n) asm volatile("s_waitcnt vmcnt(" #n ")" ::: "memory")
; #define PG8_WAIT_L(n) asm volatile("s_waitcnt lgkmcnt(" #n ")" ::: "memory")
; #define PG8_BAR __builtin_amdgcn_s_barrier()
; #define PG8_SCHED __builtin_amdgcn_sched_barrier(0)
; template <class Epi, class Sched, bool ALIGN_EPI = false, bool SP2 = false>
; __device__ __forceinline__ void gemm_phase(PG8_LAS unsigned char* lds, const Gemm g, const Sched& S, const Epi& E) {
;     ...
;             PG8_WAIT_V(8); PG8_WAIT_L(0); PG8_BAR; PG8_MMA(1, 0, At, B0); PG8_MMA(1, 1, At, B1); PG8_BAR; PG8_SCHED;
;             PG8_LDB(B0, 1, 0); PG8_LDB(B1, 1, 1); PG8_SCHED; PG8_LDA(At, 1, 0); PG8_STAGE(PG8_SA(0, 1), a2 + hstep, voffA);
;             PG8_WAIT_V(8); PG8_WAIT_L(0); PG8_BAR; PG8_MMA(0, 0, At, B0); PG8_MMA(0, 1, At, B1); PG8_BAR; PG8_SCHED;
	s_setprio 1
	v_mfma_f32_16x16x32_bf16 v[60:63], v[128:131], v[198:201], v[60:63]
	v_mfma_f32_16x16x32_bf16 v[56:59], v[136:139], v[198:201], v[56:59]
	v_mfma_f32_16x16x32_bf16 v[44:47], v[128:131], v[206:209], v[44:47]
	v_mfma_f32_16x16x32_bf16 v[40:43], v[136:139], v[206:209], v[40:43]
	v_mfma_f32_16x16x32_bf16 v[28:31], v[128:131], v[214:217], v[28:31]
	v_mfma_f32_16x16x32_bf16 v[24:27], v[136:139], v[214:217], v[24:27]
	v_mfma_f32_16x16x32_bf16 v[12:15], v[128:131], v[222:225], v[12:15]
	v_mfma_f32_16x16x32_bf16 v[8:11], v[136:139], v[222:225], v[8:11]
	v_mfma_f32_16x16x32_bf16 v[60:63], v[132:135], v[202:205], v[60:63]
	v_mfma_f32_16x16x32_bf16 v[56:59], v[140:143], v[202:205], v[56:59]
	v_mfma_f32_16x16x32_bf16 v[44:47], v[132:135], v[210:213], v[44:47]
	v_mfma_f32_16x16x32_bf16 v[40:43], v[140:143], v[210:213], v[40:43]
	v_mfma_f32_16x16x32_bf16 v[28:31], v[132:135], v[218:221], v[28:31]
	v_mfma_f32_16x16x32_bf16 v[24:27], v[140:143], v[218:221], v[24:27]
	v_mfma_f32_16x16x32_bf16 v[12:15], v[132:135], v[226:229], v[12:15]
	v_mfma_f32_16x16x32_bf16 v[8:11], v[140:143], v[226:229], v[8:11]
	v_mfma_f32_16x16x32_bf16 v[52:55], v[166:169], v[198:201], v[52:55]
	v_mfma_f32_16x16x32_bf16 v[48:51], v[190:193], v[198:201], v[48:51]
	v_mfma_f32_16x16x32_bf16 v[36:39], v[166:169], v[206:209], v[36:39]
	v_mfma_f32_16x16x32_bf16 v[32:35], v[190:193], v[206:209], v[32:35]
	v_mfma_f32_16x16x32_bf16 v[20:23], v[166:169], v[214:217], v[20:23]
	v_mfma_f32_16x16x32_bf16 v[16:19], v[190:193], v[214:217], v[16:19]
	v_mfma_f32_16x16x32_bf16 v[4:7], v[166:169], v[222:225], v[4:7]
	v_mfma_f32_16x16x32_bf16 v[0:3], v[190:193], v[222:225], v[0:3]
	v_mfma_f32_16x16x32_bf16 v[52:55], v[170:173], v[202:205], v[52:55]
	v_mfma_f32_16x16x32_bf16 v[48:51], v[194:197], v[202:205], v[48:51]
	v_mfma_f32_16x16x32_bf16 v[36:39], v[170:173], v[210:213], v[36:39]
	v_mfma_f32_16x16x32_bf16 v[32:35], v[194:197], v[210:213], v[32:35]
	v_mfma_f32_16x16x32_bf16 v[20:23], v[170:173], v[218:221], v[20:23]
	v_mfma_f32_16x16x32_bf16 v[16:19], v[194:197], v[218:221], v[16:19]
	v_mfma_f32_16x16x32_bf16 v[4:7], v[170:173], v[226:229], v[4:7]
	v_mfma_f32_16x16x32_bf16 v[0:3], v[194:197], v[226:229], v[0:3]
	s_setprio 0
	s_barrier
	s_add_i32 s23, 0, 0x18000
	s_add_i32 s54, 0, 0x1c000
	v_add_u32_e32 v140, s23, v176
	v_add_u32_e32 v152, s54, v176
	ds_read_b128 v[128:131], v140
	ds_read_b128 v[132:135], v140 offset:1024
	ds_read_b128 v[136:139], v140 offset:2048
	ds_read_b128 v[140:143], v140 offset:3072
	ds_read_b128 v[166:169], v152
	ds_read_b128 v[170:173], v152 offset:1024
	ds_read_b128 v[190:193], v152 offset:2048
	ds_read_b128 v[194:197], v152 offset:3072
	s_add_u32 s44, s44, 0x40000
	s_addc_u32 s45, s45, 0
	s_mov_b32 m0, s49
	v_lshl_add_u64 v[234:235], s[44:45], 0, v[144:145]
	ds_read_b128 v[198:201], v181 offset:32768
	ds_read_b128 v[202:205], v181 offset:33792
	ds_read_b128 v[206:209], v181 offset:34816
	ds_read_b128 v[210:213], v181 offset:35840
	ds_read_b128 v[214:217], v181 offset:36864
	ds_read_b128 v[218:221], v181 offset:37888
	ds_read_b128 v[222:225], v181 offset:38912
	ds_read_b128 v[226:229], v181 offset:39936
	global_load_lds_dwordx4 v[234:235], off
	v_lshl_add_u64 v[234:235], s[44:45], 0, v[148:149]
	s_mov_b32 m0, s51
	s_nop 0
	global_load_lds_dwordx4 v[234:235], off
	s_waitcnt vmcnt(8)
	s_waitcnt lgkmcnt(0)
	s_barrier
	s_setprio 1
	v_mfma_f32_16x16x32_bf16 v[124:127], v[128:131], v[198:201], v[124:127]
	v_mfma_f32_16x16x32_bf16 v[120:123], v[136:139], v[198:201], v[120:123]
	v_mfma_f32_16x16x32_bf16 v[108:111], v[128:131], v[206:209], v[108:111]
	v_mfma_f32_16x16x32_bf16 v[104:107], v[136:139], v[206:209], v[104:107]
	v_mfma_f32_16x16x32_bf16 v[92:95], v[128:131], v[214:217], v[92:95]
	v_mfma_f32_16x16x32_bf16 v[88:91], v[136:139], v[214:217], v[88:91]
	v_mfma_f32_16x16x32_bf16 v[76:79], v[128:131], v[222:225], v[76:79]
	v_mfma_f32_16x16x32_bf16 v[72:75], v[136:139], v[222:225], v[72:75]
	v_mfma_f32_16x16x32_bf16 v[124:127], v[132:135], v[202:205], v[124:127]
	v_mfma_f32_16x16x32_bf16 v[120:123], v[140:143], v[202:205], v[120:123]
	v_mfma_f32_16x16x32_bf16 v[108:111], v[132:135], v[210:213], v[108:111]
	v_mfma_f32_16x16x32_bf16 v[104:107], v[140:143], v[210:213], v[104:107]
	v_mfma_f32_16x16x32_bf16 v[92:95], v[132:135], v[218:221], v[92:95]
	v_mfma_f32_16x16x32_bf16 v[88:91], v[140:143], v[218:221], v[88:91]
	v_mfma_f32_16x16x32_bf16 v[76:79], v[132:135], v[226:229], v[76:79]
	v_mfma_f32_16x16x32_bf16 v[72:75], v[140:143], v[226:229], v[72:75]
	v_mfma_f32_16x16x32_bf16 v[116:119], v[166:169], v[198:201], v[116:119]
	v_mfma_f32_16x16x32_bf16 v[112:115], v[190:193], v[198:201], v[112:115]
	v_mfma_f32_16x16x32_bf16 v[100:103], v[166:169], v[206:209], v[100:103]
	v_mfma_f32_16x16x32_bf16 v[96:99], v[190:193], v[206:209], v[96:99]
	v_mfma_f32_16x16x32_bf16 v[84:87], v[166:169], v[214:217], v[84:87]
	v_mfma_f32_16x16x32_bf16 v[80:83], v[190:193], v[214:217], v[80:83]
	v_mfma_f32_16x16x32_bf16 v[68:71], v[166:169], v[222:225], v[68:71]
	v_mfma_f32_16x16x32_bf16 v[64:67], v[190:193], v[222:225], v[64:67]
	v_mfma_f32_16x16x32_bf16 v[116:119], v[170:173], v[202:205], v[116:119]
	v_mfma_f32_16x16x32_bf16 v[112:115], v[194:197], v[202:205], v[112:115]
	v_mfma_f32_16x16x32_bf16 v[100:103], v[170:173], v[210:213], v[100:103]
	v_mfma_f32_16x16x32_bf16 v[96:99], v[194:197], v[210:213], v[96:99]
	v_mfma_f32_16x16x32_bf16 v[84:87], v[170:173], v[218:221], v[84:87]
	v_mfma_f32_16x16x32_bf16 v[80:83], v[194:197], v[218:221], v[80:83]
	v_mfma_f32_16x16x32_bf16 v[68:71], v[170:173], v[226:229], v[68:71]
	v_mfma_f32_16x16x32_bf16 v[64:67], v[194:197], v[226:229], v[64:67]
	s_setprio 0
	s_barrier
; #define PG8_STAGE(bufoff, gbase, voff) do { _Pragma("unroll") for (int _i = 0; _i < 2; ++_i) \
;         __builtin_amdgcn_global_load_lds((const unsigned*)((const char*)(gbase) + (voff)[_i]), (PG8_LAS unsigned*)(lds + (bufoff) + ldsw + _i * 8192), 16, 0, 0); } while (0)
; #define PG8_LDA(dst, b, h) do { _Pragma("unroll") for (int m = 0; m < 4; ++m) _Pragma("unroll") for (int k = 0; k < 2; ++k) dst[m][k] = *(const PG8_LAS bf16x8*)(lds + PG8_SA(b, h) + aoff + m * 2048 + k * 1024); } while (0)
; #define PG8_MMA(ai, bj, At, Bt) do { __builtin_amdgcn_s_setprio(1); _Pragma("unroll") for (int m = 0; m < 4; ++m) _Pragma("unroll") for (int n = 0; n < 2; ++n) _Pragma("unroll") for (int k = 0; k < 2; ++k) \
;         acc[ai][bj][m][n] = __builtin_amdgcn_mfma_f32_16x16x32_bf16(Bt[n][k], At[m][k], acc[ai][bj][m][n], 0, 0, 0); __builtin_amdgcn_s_setprio(0); } while (0)
; #define PG8_WAIT_V(n) asm volatile("s_waitcnt vmcnt(" #n ")" ::: "memory")
; #define PG8_WAIT_L(n) asm volatile("s_waitcnt lgkmcnt(" #n ")" ::: "memory")
; #define PG8_BAR __builtin_amdgcn_s_barrier()
; #define PG8_SCHED __builtin_amdgcn_sched_barrier(0)
; template <class Epi, class Sched, bool ALIGN_EPI = false, bool SP2 = false>
; __device__ __forceinline__ void gemm_phase(PG8_LAS unsigned char* lds, const Gemm g, const Sched& S, const Epi& E) {
;     ...
;         for (int t = 0; t < nt; t += 2) {
;             const bool last = (t == nt - 2);
;     ...
;             PG8_LDA(At, 1, 1); PG8_STAGE(PG8_SB(1, 0), b3, voffB); PG8_STAGE(PG8_SB(1, 1), b3 + hstep, voffB); PG8_STAGE(PG8_SA(1, 0), a3, voffA);
;             PG8_WAIT_V(8); PG8_WAIT_L(0); PG8_BAR; PG8_MMA(1, 0, At, B0); PG8_MMA(1, 1, At, B1); PG8_BAR; PG8_SCHED;
	s_add_i32 s23, s23, s46
	v_lshl_add_u64 v[174:175], v[174:175], 0, s[10:11]
	s_mov_b32 m0, s23
	ds_read_b128 v[198:201], v181 offset:49152
	ds_read_b128 v[202:205], v181 offset:50176
	ds_read_b128 v[206:209], v181 offset:51200
	ds_read_b128 v[210:213], v181 offset:52224
	ds_read_b128 v[214:217], v181 offset:53248
	ds_read_b128 v[218:221], v181 offset:54272
	ds_read_b128 v[222:225], v181 offset:55296
	ds_read_b128 v[226:229], v181 offset:56320
	global_load_lds_dwordx4 v[174:175], off
	s_add_i32 m0, s23, 0x2000
	s_add_u32 s42, s42, 0x40080
	v_lshl_add_u64 v[174:175], v[186:187], 0, s[10:11]
	s_addc_u32 s43, s43, 0
	s_add_i32 s23, s54, s46
	global_load_lds_dwordx4 v[174:175], off
	v_lshl_add_u64 v[174:175], s[42:43], 0, v[146:147]
	s_mov_b32 m0, s23
	s_nop 0
	global_load_lds_dwordx4 v[174:175], off
	v_lshl_add_u64 v[174:175], s[42:43], 0, v[150:151]
	s_add_i32 m0, s23, 0x2000
	s_nop 0
	global_load_lds_dwordx4 v[174:175], off
	v_lshl_add_u64 v[174:175], v[230:231], 0, s[10:11]
	s_mov_b32 m0, s80
	s_nop 0
	global_load_lds_dwordx4 v[174:175], off
	v_lshl_add_u64 v[174:175], v[232:233], 0, s[10:11]
	s_mov_b32 m0, s81
	s_nop 0
	global_load_lds_dwordx4 v[174:175], off
	s_waitcnt vmcnt(8)
	s_waitcnt lgkmcnt(0)
	s_barrier
	s_setprio 1
	v_mfma_f32_16x16x32_bf16 v[60:63], v[128:131], v[198:201], v[60:63]
	v_mfma_f32_16x16x32_bf16 v[56:59], v[136:139], v[198:201], v[56:59]
	v_mfma_f32_16x16x32_bf16 v[44:47], v[128:131], v[206:209], v[44:47]
	v_mfma_f32_16x16x32_bf16 v[40:43], v[136:139], v[206:209], v[40:43]
	v_mfma_f32_16x16x32_bf16 v[28:31], v[128:131], v[214:217], v[28:31]
	v_mfma_f32_16x16x32_bf16 v[24:27], v[136:139], v[214:217], v[24:27]
	v_mfma_f32_16x16x32_bf16 v[12:15], v[128:131], v[222:225], v[12:15]
	v_mfma_f32_16x16x32_bf16 v[8:11], v[136:139], v[222:225], v[8:11]
	v_mfma_f32_16x16x32_bf16 v[60:63], v[132:135], v[202:205], v[60:63]
	v_mfma_f32_16x16x32_bf16 v[56:59], v[140:143], v[202:205], v[56:59]
	v_mfma_f32_16x16x32_bf16 v[44:47], v[132:135], v[210:213], v[44:47]
	v_mfma_f32_16x16x32_bf16 v[40:43], v[140:143], v[210:213], v[40:43]
	v_mfma_f32_16x16x32_bf16 v[28:31], v[132:135], v[218:221], v[28:31]
	v_mfma_f32_16x16x32_bf16 v[24:27], v[140:143], v[218:221], v[24:27]
	v_mfma_f32_16x16x32_bf16 v[12:15], v[132:135], v[226:229], v[12:15]
	v_mfma_f32_16x16x32_bf16 v[8:11], v[140:143], v[226:229], v[8:11]
	v_mfma_f32_16x16x32_bf16 v[52:55], v[166:169], v[198:201], v[52:55]
	v_mfma_f32_16x16x32_bf16 v[48:51], v[190:193], v[198:201], v[48:51]
	v_mfma_f32_16x16x32_bf16 v[36:39], v[166:169], v[206:209], v[36:39]
	v_mfma_f32_16x16x32_bf16 v[32:35], v[190:193], v[206:209], v[32:35]
	v_mfma_f32_16x16x32_bf16 v[20:23], v[166:169], v[214:217], v[20:23]
	v_mfma_f32_16x16x32_bf16 v[16:19], v[190:193], v[214:217], v[16:19]
	v_mfma_f32_16x16x32_bf16 v[4:7], v[166:169], v[222:225], v[4:7]
	v_mfma_f32_16x16x32_bf16 v[0:3], v[190:193], v[222:225], v[0:3]
	v_mfma_f32_16x16x32_bf16 v[52:55], v[170:173], v[202:205], v[52:55]
	v_mfma_f32_16x16x32_bf16 v[48:51], v[194:197], v[202:205], v[48:51]
	v_mfma_f32_16x16x32_bf16 v[36:39], v[170:173], v[210:213], v[36:39]
	v_mfma_f32_16x16x32_bf16 v[32:35], v[194:197], v[210:213], v[32:35]
	v_mfma_f32_16x16x32_bf16 v[20:23], v[170:173], v[218:221], v[20:23]
	v_mfma_f32_16x16x32_bf16 v[16:19], v[194:197], v[218:221], v[16:19]
	v_mfma_f32_16x16x32_bf16 v[4:7], v[170:173], v[226:229], v[4:7]
	v_mfma_f32_16x16x32_bf16 v[0:3], v[194:197], v[226:229], v[0:3]
	s_setprio 0
	s_barrier
	s_add_i32 s25, s25, 2
	s_add_u32 s40, s40, 0x100
	s_addc_u32 s41, s41, 0
	s_add_u32 vcc_hi, vcc_hi, 0x100
	s_addc_u32 s24, s24, 0
	s_cmp_gt_u32 s25, 13
	s_cbranch_scc0 .LBB0_358
	s_and_b64 vcc, exec, s[12:13]
	s_cbranch_vccz .LBB0_361
	s_barrier

; #define PG8_STAGE(bufoff, gbase, voff) do { _Pragma("unroll") for (int _i = 0; _i < 2; ++_i) \
;         __builtin_amdgcn_global_load_lds((const unsigned*)((const char*)(gbase) + (voff)[_i]), (PG8_LAS unsigned*)(lds + (bufoff) + ldsw + _i * 8192), 16, 0, 0); } while (0)
; #define PG8_LDA(dst, b, h) do { _Pragma("unroll") for (int m = 0; m < 4; ++m) _Pragma("unroll") for (int k = 0; k < 2; ++k) dst[m][k] = *(const PG8_LAS bf16x8*)(lds + PG8_SA(b, h) + aoff + m * 2048 + k * 1024); } while (0)
; #define PG8_LDB(dst, b, h) do { _Pragma("unroll") for (int n = 0; n < 2; ++n) _Pragma("unroll") for (int k = 0; k < 2; ++k) dst[n][k] = *(const PG8_LAS bf16x8*)(lds + PG8_SB(b, h) + boff + n * 2048 + k * 1024); } while (0)
; #define PG8_MMA(ai, bj, At, Bt) do { __builtin_amdgcn_s_setprio(1); _Pragma("unroll") for (int m = 0; m < 4; ++m) _Pragma("unroll") for (int n = 0; n < 2; ++n) _Pragma("unroll") for (int k = 0; k < 2; ++k) \
;         acc[ai][bj][m][n] = __builtin_amdgcn_mfma_f32_16x16x32_bf16(Bt[n][k], At[m][k], acc[ai][bj][m][n], 0, 0, 0); __builtin_amdgcn_s_setprio(0); } while (0)
; #define PG8_WAIT_V(n) asm volatile("s_waitcnt vmcnt(" #n ")" ::: "memory")
; #define PG8_WAIT_L(n) asm volatile("s_waitcnt lgkmcnt(" #n ")" ::: "memory")
; #define PG8_BAR __builtin_amdgcn_s_barrier()
; #define PG8_SCHED __builtin_amdgcn_sched_barrier(0)
; template <class Epi, class Sched, bool ALIGN_EPI = false, bool SP2 = false>
; __device__ __forceinline__ void gemm_phase(PG8_LAS unsigned char* lds, const Gemm g, const Sched& S, const Epi& E) {
;     ...
;             PG8_LDB(B0, 0, 0); PG8_LDB(B1, 0, 1); PG8_SCHED; PG8_LDA(At, 0, 0); PG8_STAGE(PG8_SA(1, 1), a1 + hstep, voffA);
;             PG8_WAIT_V(8); PG8_WAIT_L(0); PG8_BAR; PG8_MMA(0, 0, At, B0); PG8_MMA(0, 1, At, B1); PG8_BAR; PG8_SCHED;
;             PG8_LDA(At, 0, 1); PG8_STAGE(PG8_SB(0, 0), b2, voffB); PG8_STAGE(PG8_SB(0, 1), b2 + hstep, voffB); PG8_STAGE(PG8_SA(0, 0), a2, voffA);
;             PG8_WAIT_V(8); PG8_WAIT_L(0); PG8_BAR; PG8_MMA(1, 0, At, B0); PG8_MMA(1, 1, At, B1); PG8_BAR; PG8_SCHED;
.LBB0_684:
	ds_read_b128 v[128:131], v174
	ds_read_b128 v[132:135], v174 offset:1024
	ds_read_b128 v[136:139], v174 offset:2048
	ds_read_b128 v[140:143], v174 offset:3072
	ds_read_b128 v[162:165], v175
	ds_read_b128 v[166:169], v175 offset:1024
	ds_read_b128 v[180:183], v175 offset:2048
	ds_read_b128 v[184:187], v175 offset:3072
	s_add_u32 s8, s0, 0xfffc0080
	s_addc_u32 s9, s1, -1
	s_cmp_eq_u32 vcc_lo, 12
	s_cselect_b32 s43, s3, s9
	s_cselect_b32 s42, s94, s8
	s_cselect_b32 s41, s5, s97
	s_cselect_b32 s40, s95, s96
	s_add_i32 m0, s47, 0xc000
	ds_read_b128 v[190:193], v176
	ds_read_b128 v[194:197], v176 offset:1024
	ds_read_b128 v[198:201], v176 offset:2048
	ds_read_b128 v[202:205], v176 offset:3072
	ds_read_b128 v[206:209], v176 offset:4096
	ds_read_b128 v[210:213], v176 offset:5120
	ds_read_b128 v[214:217], v176 offset:6144
	ds_read_b128 v[218:221], v176 offset:7168
	global_load_lds_dwordx4 v158, s[0:1]
	s_add_i32 m0, s47, 0xe000
	s_nop 0
	global_load_lds_dwordx4 v160, s[0:1]
	s_waitcnt vmcnt(8)
	s_waitcnt lgkmcnt(0)
	s_barrier
	s_setprio 1
	v_mfma_f32_16x16x32_bf16 v[124:127], v[128:131], v[190:193], v[124:127]
	v_mfma_f32_16x16x32_bf16 v[120:123], v[136:139], v[190:193], v[120:123]
	v_mfma_f32_16x16x32_bf16 v[108:111], v[128:131], v[198:201], v[108:111]
	v_mfma_f32_16x16x32_bf16 v[104:107], v[136:139], v[198:201], v[104:107]
	v_mfma_f32_16x16x32_bf16 v[92:95], v[128:131], v[206:209], v[92:95]
	v_mfma_f32_16x16x32_bf16 v[88:91], v[136:139], v[206:209], v[88:91]
	v_mfma_f32_16x16x32_bf16 v[76:79], v[128:131], v[214:217], v[76:79]
	v_mfma_f32_16x16x32_bf16 v[72:75], v[136:139], v[214:217], v[72:75]
	v_mfma_f32_16x16x32_bf16 v[124:127], v[132:135], v[194:197], v[124:127]
	v_mfma_f32_16x16x32_bf16 v[120:123], v[140:143], v[194:197], v[120:123]
	v_mfma_f32_16x16x32_bf16 v[108:111], v[132:135], v[202:205], v[108:111]
	v_mfma_f32_16x16x32_bf16 v[104:107], v[140:143], v[202:205], v[104:107]
	v_mfma_f32_16x16x32_bf16 v[92:95], v[132:135], v[210:213], v[92:95]
	v_mfma_f32_16x16x32_bf16 v[88:91], v[140:143], v[210:213], v[88:91]
	v_mfma_f32_16x16x32_bf16 v[76:79], v[132:135], v[218:221], v[76:79]
	v_mfma_f32_16x16x32_bf16 v[72:75], v[140:143], v[218:221], v[72:75]
	v_mfma_f32_16x16x32_bf16 v[116:119], v[162:165], v[190:193], v[116:119]
	v_mfma_f32_16x16x32_bf16 v[112:115], v[180:183], v[190:193], v[112:115]
	v_mfma_f32_16x16x32_bf16 v[100:103], v[162:165], v[198:201], v[100:103]
	v_mfma_f32_16x16x32_bf16 v[96:99], v[180:183], v[198:201], v[96:99]
	v_mfma_f32_16x16x32_bf16 v[84:87], v[162:165], v[206:209], v[84:87]
	v_mfma_f32_16x16x32_bf16 v[80:83], v[180:183], v[206:209], v[80:83]
	v_mfma_f32_16x16x32_bf16 v[68:71], v[162:165], v[214:217], v[68:71]
	v_mfma_f32_16x16x32_bf16 v[64:67], v[180:183], v[214:217], v[64:67]
	v_mfma_f32_16x16x32_bf16 v[116:119], v[166:169], v[194:197], v[116:119]
	v_mfma_f32_16x16x32_bf16 v[112:115], v[184:187], v[194:197], v[112:115]
	v_mfma_f32_16x16x32_bf16 v[100:103], v[166:169], v[202:205], v[100:103]
	v_mfma_f32_16x16x32_bf16 v[96:99], v[184:187], v[202:205], v[96:99]
	v_mfma_f32_16x16x32_bf16 v[84:87], v[166:169], v[210:213], v[84:87]
	v_mfma_f32_16x16x32_bf16 v[80:83], v[184:187], v[210:213], v[80:83]
	v_mfma_f32_16x16x32_bf16 v[68:71], v[166:169], v[218:221], v[68:71]
	v_mfma_f32_16x16x32_bf16 v[64:67], v[184:187], v[218:221], v[64:67]
	s_setprio 0
	s_barrier
	s_add_i32 s8, s76, s46
	v_lshl_add_u64 v[170:171], s[40:41], 0, v[146:147]
	s_mov_b32 m0, s8
	ds_read_b128 v[190:193], v176 offset:16384
	ds_read_b128 v[194:197], v176 offset:17408
	ds_read_b128 v[198:201], v176 offset:18432
	ds_read_b128 v[202:205], v176 offset:19456
	ds_read_b128 v[206:209], v176 offset:20480
	ds_read_b128 v[210:213], v176 offset:21504
	ds_read_b128 v[214:217], v176 offset:22528
	ds_read_b128 v[218:221], v176 offset:23552
	global_load_lds_dwordx4 v[170:171], off
	s_add_i32 m0, s8, 0x2000
	s_add_u32 s8, s40, 0x40000
	v_lshl_add_u64 v[222:223], s[40:41], 0, v[150:151]
	s_addc_u32 s9, s41, 0
	s_add_i32 s54, s77, s46
	global_load_lds_dwordx4 v[222:223], off
	s_mov_b32 m0, s54
	v_lshl_add_u64 v[226:227], s[42:43], 0, v[148:149]
	global_load_lds_dwordx4 v146, s[8:9]
	s_add_i32 m0, s54, 0x2000
	s_nop 0
	global_load_lds_dwordx4 v150, s[8:9]
	v_lshl_add_u64 v[224:225], s[42:43], 0, v[144:145]
	s_mov_b32 m0, s47
	s_nop 0
	global_load_lds_dwordx4 v[224:225], off
	s_mov_b32 m0, s48
	s_nop 0
	global_load_lds_dwordx4 v[226:227], off
	s_waitcnt vmcnt(8)
	s_waitcnt lgkmcnt(0)
	s_barrier
	s_setprio 1
	v_mfma_f32_16x16x32_bf16 v[60:63], v[128:131], v[190:193], v[60:63]
	v_mfma_f32_16x16x32_bf16 v[56:59], v[136:139], v[190:193], v[56:59]
	v_mfma_f32_16x16x32_bf16 v[44:47], v[128:131], v[198:201], v[44:47]
	v_mfma_f32_16x16x32_bf16 v[40:43], v[136:139], v[198:201], v[40:43]
	v_mfma_f32_16x16x32_bf16 v[28:31], v[128:131], v[206:209], v[28:31]
	v_mfma_f32_16x16x32_bf16 v[24:27], v[136:139], v[206:209], v[24:27]
	v_mfma_f32_16x16x32_bf16 v[12:15], v[128:131], v[214:217], v[12:15]
	v_mfma_f32_16x16x32_bf16 v[8:11], v[136:139], v[214:217], v[8:11]
	v_mfma_f32_16x16x32_bf16 v[60:63], v[132:135], v[194:197], v[60:63]
	v_mfma_f32_16x16x32_bf16 v[56:59], v[140:143], v[194:197], v[56:59]
	v_mfma_f32_16x16x32_bf16 v[44:47], v[132:135], v[202:205], v[44:47]
	v_mfma_f32_16x16x32_bf16 v[40:43], v[140:143], v[202:205], v[40:43]
	v_mfma_f32_16x16x32_bf16 v[28:31], v[132:135], v[210:213], v[28:31]
	v_mfma_f32_16x16x32_bf16 v[24:27], v[140:143], v[210:213], v[24:27]
	v_mfma_f32_16x16x32_bf16 v[12:15], v[132:135], v[218:221], v[12:15]
	v_mfma_f32_16x16x32_bf16 v[8:11], v[140:143], v[218:221], v[8:11]
	v_mfma_f32_16x16x32_bf16 v[52:55], v[162:165], v[190:193], v[52:55]
	v_mfma_f32_16x16x32_bf16 v[48:51], v[180:183], v[190:193], v[48:51]
	v_mfma_f32_16x16x32_bf16 v[36:39], v[162:165], v[198:201], v[36:39]
	v_mfma_f32_16x16x32_bf16 v[32:35], v[180:183], v[198:201], v[32:35]
	v_mfma_f32_16x16x32_bf16 v[20:23], v[162:165], v[206:209], v[20:23]
	v_mfma_f32_16x16x32_bf16 v[16:19], v[180:183], v[206:209], v[16:19]
	v_mfma_f32_16x16x32_bf16 v[4:7], v[162:165], v[214:217], v[4:7]
	v_mfma_f32_16x16x32_bf16 v[0:3], v[180:183], v[214:217], v[0:3]
	v_mfma_f32_16x16x32_bf16 v[52:55], v[166:169], v[194:197], v[52:55]
	v_mfma_f32_16x16x32_bf16 v[48:51], v[184:187], v[194:197], v[48:51]
	v_mfma_f32_16x16x32_bf16 v[36:39], v[166:169], v[202:205], v[36:39]
	v_mfma_f32_16x16x32_bf16 v[32:35], v[184:187], v[202:205], v[32:35]
	v_mfma_f32_16x16x32_bf16 v[20:23], v[166:169], v[210:213], v[20:23]
	v_mfma_f32_16x16x32_bf16 v[16:19], v[184:187], v[210:213], v[16:19]
	v_mfma_f32_16x16x32_bf16 v[4:7], v[166:169], v[218:221], v[4:7]
	v_mfma_f32_16x16x32_bf16 v[0:3], v[184:187], v[218:221], v[0:3]
	s_setprio 0
	s_barrier
; #define PG8_STAGE(bufoff, gbase, voff) do { _Pragma("unroll") for (int _i = 0; _i < 2; ++_i) \
;         __builtin_amdgcn_global_load_lds((const unsigned*)((const char*)(gbase) + (voff)[_i]), (PG8_LAS unsigned*)(lds + (bufoff) + ldsw + _i * 8192), 16, 0, 0); } while (0)
; #define PG8_LDA(dst, b, h) do { _Pragma("unroll") for (int m = 0; m < 4; ++m) _Pragma("unroll") for (int k = 0; k < 2; ++k) dst[m][k] = *(const PG8_LAS bf16x8*)(lds + PG8_SA(b, h) + aoff + m * 2048 + k * 1024); } while (0)
; #define PG8_LDB(dst, b, h) do { _Pragma("unroll") for (int n = 0; n < 2; ++n) _Pragma("unroll") for (int k = 0; k < 2; ++k) dst[n][k] = *(const PG8_LAS bf16x8*)(lds + PG8_SB(b, h) + boff + n * 2048 + k * 1024); } while (0)
; #define PG8_MMA(ai, bj, At, Bt) do { __builtin_amdgcn_s_setprio(1); _Pragma("unroll") for (int m = 0; m < 4; ++m) _Pragma("unroll") for (int n = 0; n < 2; ++n) _Pragma("unroll") for (int k = 0; k < 2; ++k) \
;         acc[ai][bj][m][n] = __builtin_amdgcn_mfma_f32_16x16x32_bf16(Bt[n][k], At[m][k], acc[ai][bj][m][n], 0, 0, 0); __builtin_amdgcn_s_setprio(0); } while (0)
; #define PG8_WAIT_V(n) asm volatile("s_waitcnt vmcnt(" #n ")" ::: "memory")
; #define PG8_WAIT_L(n) asm volatile("s_waitcnt lgkmcnt(" #n ")" ::: "memory")
; #define PG8_BAR __builtin_amdgcn_s_barrier()
; #define PG8_SCHED __builtin_amdgcn_sched_barrier(0)
; template <class Epi, class Sched, bool ALIGN_EPI = false, bool SP2 = false>
; __device__ __forceinline__ void gemm_phase(PG8_LAS unsigned char* lds, const Gemm g, const Sched& S, const Epi& E) {
;     ...
;             PG8_LDB(B0, 1, 0); PG8_LDB(B1, 1, 1); PG8_SCHED; PG8_LDA(At, 1, 0); PG8_STAGE(PG8_SA(0, 1), a2 + hstep, voffA);
;             PG8_WAIT_V(8); PG8_WAIT_L(0); PG8_BAR; PG8_MMA(0, 0, At, B0); PG8_MMA(0, 1, At, B1); PG8_BAR; PG8_SCHED;
;             PG8_LDA(At, 1, 1); PG8_STAGE(PG8_SB(1, 0), b3, voffB); PG8_STAGE(PG8_SB(1, 1), b3 + hstep, voffB); PG8_STAGE(PG8_SA(1, 0), a3, voffA);
;             PG8_WAIT_V(8); PG8_WAIT_L(0); PG8_BAR; PG8_MMA(1, 0, At, B0); PG8_MMA(1, 1, At, B1); PG8_BAR; PG8_SCHED;
	s_add_i32 s54, 0, 0x18000
	s_add_i32 s55, 0, 0x1c000
	v_add_u32_e32 v140, s54, v172
	v_add_u32_e32 v152, s55, v172
	ds_read_b128 v[128:131], v140
	ds_read_b128 v[132:135], v140 offset:1024
	ds_read_b128 v[136:139], v140 offset:2048
	ds_read_b128 v[140:143], v140 offset:3072
	ds_read_b128 v[162:165], v152
	ds_read_b128 v[166:169], v152 offset:1024
	ds_read_b128 v[180:183], v152 offset:2048
	ds_read_b128 v[184:187], v152 offset:3072
	s_add_u32 s8, s42, 0x40000
	s_addc_u32 s9, s43, 0
	s_mov_b32 m0, s49
	ds_read_b128 v[190:193], v176 offset:32768
	ds_read_b128 v[194:197], v176 offset:33792
	ds_read_b128 v[198:201], v176 offset:34816
	ds_read_b128 v[202:205], v176 offset:35840
	ds_read_b128 v[206:209], v176 offset:36864
	ds_read_b128 v[210:213], v176 offset:37888
	ds_read_b128 v[214:217], v176 offset:38912
	ds_read_b128 v[218:221], v176 offset:39936
	global_load_lds_dwordx4 v144, s[8:9]
	s_mov_b32 m0, s51
	s_nop 0
	global_load_lds_dwordx4 v148, s[8:9]
	s_waitcnt vmcnt(8)
	s_waitcnt lgkmcnt(0)
	s_barrier
	s_setprio 1
	v_mfma_f32_16x16x32_bf16 v[124:127], v[128:131], v[190:193], v[124:127]
	v_mfma_f32_16x16x32_bf16 v[120:123], v[136:139], v[190:193], v[120:123]
	v_mfma_f32_16x16x32_bf16 v[108:111], v[128:131], v[198:201], v[108:111]
	v_mfma_f32_16x16x32_bf16 v[104:107], v[136:139], v[198:201], v[104:107]
	v_mfma_f32_16x16x32_bf16 v[92:95], v[128:131], v[206:209], v[92:95]
	v_mfma_f32_16x16x32_bf16 v[88:91], v[136:139], v[206:209], v[88:91]
	v_mfma_f32_16x16x32_bf16 v[76:79], v[128:131], v[214:217], v[76:79]
	v_mfma_f32_16x16x32_bf16 v[72:75], v[136:139], v[214:217], v[72:75]
	v_mfma_f32_16x16x32_bf16 v[124:127], v[132:135], v[194:197], v[124:127]
	v_mfma_f32_16x16x32_bf16 v[120:123], v[140:143], v[194:197], v[120:123]
	v_mfma_f32_16x16x32_bf16 v[108:111], v[132:135], v[202:205], v[108:111]
	v_mfma_f32_16x16x32_bf16 v[104:107], v[140:143], v[202:205], v[104:107]
	v_mfma_f32_16x16x32_bf16 v[92:95], v[132:135], v[210:213], v[92:95]
	v_mfma_f32_16x16x32_bf16 v[88:91], v[140:143], v[210:213], v[88:91]
	v_mfma_f32_16x16x32_bf16 v[76:79], v[132:135], v[218:221], v[76:79]
	v_mfma_f32_16x16x32_bf16 v[72:75], v[140:143], v[218:221], v[72:75]
	v_mfma_f32_16x16x32_bf16 v[116:119], v[162:165], v[190:193], v[116:119]
	v_mfma_f32_16x16x32_bf16 v[112:115], v[180:183], v[190:193], v[112:115]
	v_mfma_f32_16x16x32_bf16 v[100:103], v[162:165], v[198:201], v[100:103]
	v_mfma_f32_16x16x32_bf16 v[96:99], v[180:183], v[198:201], v[96:99]
	v_mfma_f32_16x16x32_bf16 v[84:87], v[162:165], v[206:209], v[84:87]
	v_mfma_f32_16x16x32_bf16 v[80:83], v[180:183], v[206:209], v[80:83]
	v_mfma_f32_16x16x32_bf16 v[68:71], v[162:165], v[214:217], v[68:71]
	v_mfma_f32_16x16x32_bf16 v[64:67], v[180:183], v[214:217], v[64:67]
	v_mfma_f32_16x16x32_bf16 v[116:119], v[166:169], v[194:197], v[116:119]
	v_mfma_f32_16x16x32_bf16 v[112:115], v[184:187], v[194:197], v[112:115]
	v_mfma_f32_16x16x32_bf16 v[100:103], v[166:169], v[202:205], v[100:103]
	v_mfma_f32_16x16x32_bf16 v[96:99], v[184:187], v[202:205], v[96:99]
	v_mfma_f32_16x16x32_bf16 v[84:87], v[166:169], v[210:213], v[84:87]
	v_mfma_f32_16x16x32_bf16 v[80:83], v[184:187], v[210:213], v[80:83]
	v_mfma_f32_16x16x32_bf16 v[68:71], v[166:169], v[218:221], v[68:71]
	v_mfma_f32_16x16x32_bf16 v[64:67], v[184:187], v[218:221], v[64:67]
	s_setprio 0
	s_barrier
	s_add_i32 s8, s54, s46
	v_lshl_add_u64 v[170:171], v[170:171], 0, s[14:15]
	s_mov_b32 m0, s8
	ds_read_b128 v[190:193], v176 offset:49152
	ds_read_b128 v[194:197], v176 offset:50176
	ds_read_b128 v[198:201], v176 offset:51200
	ds_read_b128 v[202:205], v176 offset:52224
	ds_read_b128 v[206:209], v176 offset:53248
	ds_read_b128 v[210:213], v176 offset:54272
	ds_read_b128 v[214:217], v176 offset:55296
	ds_read_b128 v[218:221], v176 offset:56320
	global_load_lds_dwordx4 v[170:171], off
	s_add_i32 m0, s8, 0x2000
	s_add_u32 s8, s40, 0x40080
	v_lshl_add_u64 v[170:171], v[222:223], 0, s[14:15]
	s_addc_u32 s9, s41, 0
	s_add_i32 s40, s55, s46
	global_load_lds_dwordx4 v[170:171], off
	s_mov_b32 m0, s40
	s_nop 0
	global_load_lds_dwordx4 v146, s[8:9]
	s_add_i32 m0, s40, 0x2000
	s_nop 0
	global_load_lds_dwordx4 v150, s[8:9]
	v_lshl_add_u64 v[170:171], v[224:225], 0, s[14:15]
	s_mov_b32 m0, s66
	s_nop 0
	global_load_lds_dwordx4 v[170:171], off
	v_lshl_add_u64 v[170:171], v[226:227], 0, s[14:15]
	s_mov_b32 m0, s67
	s_nop 0
	global_load_lds_dwordx4 v[170:171], off
	s_waitcnt vmcnt(8)
	s_waitcnt lgkmcnt(0)
	s_barrier
	s_setprio 1
	v_mfma_f32_16x16x32_bf16 v[60:63], v[128:131], v[190:193], v[60:63]
	v_mfma_f32_16x16x32_bf16 v[56:59], v[136:139], v[190:193], v[56:59]
	v_mfma_f32_16x16x32_bf16 v[44:47], v[128:131], v[198:201], v[44:47]
	v_mfma_f32_16x16x32_bf16 v[40:43], v[136:139], v[198:201], v[40:43]
	v_mfma_f32_16x16x32_bf16 v[28:31], v[128:131], v[206:209], v[28:31]
	v_mfma_f32_16x16x32_bf16 v[24:27], v[136:139], v[206:209], v[24:27]
	v_mfma_f32_16x16x32_bf16 v[12:15], v[128:131], v[214:217], v[12:15]
	v_mfma_f32_16x16x32_bf16 v[8:11], v[136:139], v[214:217], v[8:11]
	v_mfma_f32_16x16x32_bf16 v[60:63], v[132:135], v[194:197], v[60:63]
	v_mfma_f32_16x16x32_bf16 v[56:59], v[140:143], v[194:197], v[56:59]
	v_mfma_f32_16x16x32_bf16 v[44:47], v[132:135], v[202:205], v[44:47]
	v_mfma_f32_16x16x32_bf16 v[40:43], v[140:143], v[202:205], v[40:43]
	v_mfma_f32_16x16x32_bf16 v[28:31], v[132:135], v[210:213], v[28:31]
	v_mfma_f32_16x16x32_bf16 v[24:27], v[140:143], v[210:213], v[24:27]
	v_mfma_f32_16x16x32_bf16 v[12:15], v[132:135], v[218:221], v[12:15]
	v_mfma_f32_16x16x32_bf16 v[8:11], v[140:143], v[218:221], v[8:11]
	v_mfma_f32_16x16x32_bf16 v[52:55], v[162:165], v[190:193], v[52:55]
	v_mfma_f32_16x16x32_bf16 v[48:51], v[180:183], v[190:193], v[48:51]
	v_mfma_f32_16x16x32_bf16 v[36:39], v[162:165], v[198:201], v[36:39]
	v_mfma_f32_16x16x32_bf16 v[32:35], v[180:183], v[198:201], v[32:35]
	v_mfma_f32_16x16x32_bf16 v[20:23], v[162:165], v[206:209], v[20:23]
	v_mfma_f32_16x16x32_bf16 v[16:19], v[180:183], v[206:209], v[16:19]
	v_mfma_f32_16x16x32_bf16 v[4:7], v[162:165], v[214:217], v[4:7]
	v_mfma_f32_16x16x32_bf16 v[0:3], v[180:183], v[214:217], v[0:3]
	v_mfma_f32_16x16x32_bf16 v[52:55], v[166:169], v[194:197], v[52:55]
	v_mfma_f32_16x16x32_bf16 v[48:51], v[184:187], v[194:197], v[48:51]
	v_mfma_f32_16x16x32_bf16 v[36:39], v[166:169], v[202:205], v[36:39]
	v_mfma_f32_16x16x32_bf16 v[32:35], v[184:187], v[202:205], v[32:35]
	v_mfma_f32_16x16x32_bf16 v[20:23], v[166:169], v[210:213], v[20:23]
	v_mfma_f32_16x16x32_bf16 v[16:19], v[184:187], v[210:213], v[16:19]
	v_mfma_f32_16x16x32_bf16 v[4:7], v[166:169], v[218:221], v[4:7]
	v_mfma_f32_16x16x32_bf16 v[0:3], v[184:187], v[218:221], v[0:3]
	s_setprio 0
	s_barrier
	s_add_i32 vcc_lo, vcc_lo, 2
	s_add_u32 s0, s0, 0x100
	s_addc_u32 s1, s1, 0
	s_add_u32 s96, s96, 0x100
	s_addc_u32 s97, s97, 0
	s_cmp_gt_u32 vcc_lo, 13
	s_cbranch_scc0 .LBB0_684
	s_and_b64 vcc, exec, s[18:19]
	s_cbranch_vccz .LBB0_687
	s_barrier

; #define PG8_STAGE(bufoff, gbase, voff) do { _Pragma("unroll") for (int _i = 0; _i < 2; ++_i) \
;         __builtin_amdgcn_global_load_lds((const unsigned*)((const char*)(gbase) + (voff)[_i]), (PG8_LAS unsigned*)(lds + (bufoff) + ldsw + _i * 8192), 16, 0, 0); } while (0)
; #define PG8_LDA(dst, b, h) do { _Pragma("unroll") for (int m = 0; m < 4; ++m) _Pragma("unroll") for (int k = 0; k < 2; ++k) dst[m][k] = *(const PG8_LAS bf16x8*)(lds + PG8_SA(b, h) + aoff + m * 2048 + k * 1024); } while (0)
; #define PG8_LDB(dst, b, h) do { _Pragma("unroll") for (int n = 0; n < 2; ++n) _Pragma("unroll") for (int k = 0; k < 2; ++k) dst[n][k] = *(const PG8_LAS bf16x8*)(lds + PG8_SB(b, h) + boff + n * 2048 + k * 1024); } while (0)
; #define PG8_MMA(ai, bj, At, Bt) do { __builtin_amdgcn_s_setprio(1); _Pragma("unroll") for (int m = 0; m < 4; ++m) _Pragma("unroll") for (int n = 0; n < 2; ++n) _Pragma("unroll") for (int k = 0; k < 2; ++k) \
;         acc[ai][bj][m][n] = __builtin_amdgcn_mfma_f32_16x16x32_bf16(Bt[n][k], At[m][k], acc[ai][bj][m][n], 0, 0, 0); __builtin_amdgcn_s_setprio(0); } while (0)
; #define PG8_WAIT_V(n) asm volatile("s_waitcnt vmcnt(" #n ")" ::: "memory")
; #define PG8_WAIT_L(n) asm volatile("s_waitcnt lgkmcnt(" #n ")" ::: "memory")
; #define PG8_BAR __builtin_amdgcn_s_barrier()
; #define PG8_SCHED __builtin_amdgcn_sched_barrier(0)
; template <class Epi, class Sched, bool ALIGN_EPI = false, bool SP2 = false>
; __device__ __forceinline__ void gemm_phase(PG8_LAS unsigned char* lds, const Gemm g, const Sched& S, const Epi& E) {
;     ...
;             PG8_LDB(B0, 0, 0); PG8_LDB(B1, 0, 1); PG8_SCHED; PG8_LDA(At, 0, 0); PG8_STAGE(PG8_SA(1, 1), a1 + hstep, voffA);
;             PG8_WAIT_V(8); PG8_WAIT_L(0); PG8_BAR; PG8_MMA(0, 0, At, B0); PG8_MMA(0, 1, At, B1); PG8_BAR; PG8_SCHED;
;             PG8_LDA(At, 0, 1); PG8_STAGE(PG8_SB(0, 0), b2, voffB); PG8_STAGE(PG8_SB(0, 1), b2 + hstep, voffB); PG8_STAGE(PG8_SA(0, 0), a2, voffA);
;             PG8_WAIT_V(8); PG8_WAIT_L(0); PG8_BAR; PG8_MMA(1, 0, At, B0); PG8_MMA(1, 1, At, B1); PG8_BAR; PG8_SCHED;
.LBB0_795:
	v_add_u32_e32 v162, s67, v186
	v_add_u32_e32 v178, s68, v186
	ds_read_b128 v[150:153], v162
	ds_read_b128 v[154:157], v162 offset:1024
	ds_read_b128 v[158:161], v162 offset:2048
	ds_read_b128 v[162:165], v162 offset:3072
	ds_read_b128 v[166:169], v178
	ds_read_b128 v[170:173], v178 offset:1024
	ds_read_b128 v[174:177], v178 offset:2048
	ds_read_b128 v[178:181], v178 offset:3072
	s_add_u32 s54, s46, 0xfff80080
	s_addc_u32 s55, s47, -1
	s_cmp_eq_u32 s82, 12
	s_cselect_b32 s57, s41, s55
	s_cselect_b32 s56, s78, s54
	s_cselect_b32 s55, s39, s81
	s_cselect_b32 s54, s79, s80
	s_add_i32 m0, s61, 0xc000
	ds_read_b128 v[182:185], v187
	ds_read_b128 v[190:193], v187 offset:1024
	ds_read_b128 v[194:197], v187 offset:2048
	ds_read_b128 v[198:201], v187 offset:3072
	ds_read_b128 v[202:205], v187 offset:4096
	ds_read_b128 v[206:209], v187 offset:5120
	ds_read_b128 v[210:213], v187 offset:6144
	ds_read_b128 v[214:217], v187 offset:7168
	global_load_lds_dwordx4 v142, s[46:47]
	s_add_i32 m0, s61, 0xe000
	s_nop 0
	global_load_lds_dwordx4 v144, s[46:47]
	s_waitcnt vmcnt(8)
	s_waitcnt lgkmcnt(0)
	s_barrier
	s_setprio 1
	v_mfma_f32_16x16x32_bf16 v[124:127], v[150:153], v[182:185], v[124:127]
	v_mfma_f32_16x16x32_bf16 v[120:123], v[158:161], v[182:185], v[120:123]
	v_mfma_f32_16x16x32_bf16 v[116:119], v[150:153], v[194:197], v[116:119]
	v_mfma_f32_16x16x32_bf16 v[112:115], v[158:161], v[194:197], v[112:115]
	v_mfma_f32_16x16x32_bf16 v[108:111], v[150:153], v[202:205], v[108:111]
	v_mfma_f32_16x16x32_bf16 v[104:107], v[158:161], v[202:205], v[104:107]
	v_mfma_f32_16x16x32_bf16 v[100:103], v[150:153], v[210:213], v[100:103]
	v_mfma_f32_16x16x32_bf16 v[96:99], v[158:161], v[210:213], v[96:99]
	v_mfma_f32_16x16x32_bf16 v[124:127], v[154:157], v[190:193], v[124:127]
	v_mfma_f32_16x16x32_bf16 v[120:123], v[162:165], v[190:193], v[120:123]
	v_mfma_f32_16x16x32_bf16 v[116:119], v[154:157], v[198:201], v[116:119]
	v_mfma_f32_16x16x32_bf16 v[112:115], v[162:165], v[198:201], v[112:115]
	v_mfma_f32_16x16x32_bf16 v[108:111], v[154:157], v[206:209], v[108:111]
	v_mfma_f32_16x16x32_bf16 v[104:107], v[162:165], v[206:209], v[104:107]
	v_mfma_f32_16x16x32_bf16 v[100:103], v[154:157], v[214:217], v[100:103]
	v_mfma_f32_16x16x32_bf16 v[96:99], v[162:165], v[214:217], v[96:99]
	v_mfma_f32_16x16x32_bf16 v[92:95], v[166:169], v[182:185], v[92:95]
	v_mfma_f32_16x16x32_bf16 v[88:91], v[174:177], v[182:185], v[88:91]
	v_mfma_f32_16x16x32_bf16 v[84:87], v[166:169], v[194:197], v[84:87]
	v_mfma_f32_16x16x32_bf16 v[80:83], v[174:177], v[194:197], v[80:83]
	v_mfma_f32_16x16x32_bf16 v[76:79], v[166:169], v[202:205], v[76:79]
	v_mfma_f32_16x16x32_bf16 v[72:75], v[174:177], v[202:205], v[72:75]
	v_mfma_f32_16x16x32_bf16 v[68:71], v[166:169], v[210:213], v[68:71]
	v_mfma_f32_16x16x32_bf16 v[64:67], v[174:177], v[210:213], v[64:67]
	v_mfma_f32_16x16x32_bf16 v[92:95], v[170:173], v[190:193], v[92:95]
	v_mfma_f32_16x16x32_bf16 v[88:91], v[178:181], v[190:193], v[88:91]
	v_mfma_f32_16x16x32_bf16 v[84:87], v[170:173], v[198:201], v[84:87]
	v_mfma_f32_16x16x32_bf16 v[80:83], v[178:181], v[198:201], v[80:83]
	v_mfma_f32_16x16x32_bf16 v[76:79], v[170:173], v[206:209], v[76:79]
	v_mfma_f32_16x16x32_bf16 v[72:75], v[178:181], v[206:209], v[72:75]
	v_mfma_f32_16x16x32_bf16 v[68:71], v[170:173], v[214:217], v[68:71]
	v_mfma_f32_16x16x32_bf16 v[64:67], v[178:181], v[214:217], v[64:67]
	s_setprio 0
	s_barrier
	s_add_i32 s83, s67, s60
	v_lshl_add_u64 v[218:219], s[54:55], 0, v[130:131]
	s_mov_b32 m0, s83
	ds_read_b128 v[182:185], v187 offset:16384
	ds_read_b128 v[190:193], v187 offset:17408
	ds_read_b128 v[194:197], v187 offset:18432
	ds_read_b128 v[198:201], v187 offset:19456
	ds_read_b128 v[202:205], v187 offset:20480
	ds_read_b128 v[206:209], v187 offset:21504
	ds_read_b128 v[210:213], v187 offset:22528
	ds_read_b128 v[214:217], v187 offset:23552
	global_load_lds_dwordx4 v[218:219], off
	s_add_i32 m0, s83, 0x2000
	s_add_u32 s86, s54, 0x80000
	v_lshl_add_u64 v[220:221], s[54:55], 0, v[134:135]
	s_addc_u32 s87, s55, 0
	s_add_i32 s83, s68, s60
	global_load_lds_dwordx4 v[220:221], off
	s_mov_b32 m0, s83
	v_lshl_add_u64 v[224:225], s[56:57], 0, v[132:133]
	global_load_lds_dwordx4 v130, s[86:87]
	s_add_i32 m0, s83, 0x2000
	s_nop 0
	global_load_lds_dwordx4 v134, s[86:87]
	v_lshl_add_u64 v[222:223], s[56:57], 0, v[128:129]
	s_mov_b32 m0, s61
	s_nop 0
	global_load_lds_dwordx4 v[222:223], off
	s_mov_b32 m0, s62
	s_nop 0
	global_load_lds_dwordx4 v[224:225], off
	s_waitcnt vmcnt(8)
	s_waitcnt lgkmcnt(0)
	s_barrier
; #define PG8_STAGE(bufoff, gbase, voff) do { _Pragma("unroll") for (int _i = 0; _i < 2; ++_i) \
;         __builtin_amdgcn_global_load_lds((const unsigned*)((const char*)(gbase) + (voff)[_i]), (PG8_LAS unsigned*)(lds + (bufoff) + ldsw + _i * 8192), 16, 0, 0); } while (0)
; #define PG8_LDA(dst, b, h) do { _Pragma("unroll") for (int m = 0; m < 4; ++m) _Pragma("unroll") for (int k = 0; k < 2; ++k) dst[m][k] = *(const PG8_LAS bf16x8*)(lds + PG8_SA(b, h) + aoff + m * 2048 + k * 1024); } while (0)
; #define PG8_LDB(dst, b, h) do { _Pragma("unroll") for (int n = 0; n < 2; ++n) _Pragma("unroll") for (int k = 0; k < 2; ++k) dst[n][k] = *(const PG8_LAS bf16x8*)(lds + PG8_SB(b, h) + boff + n * 2048 + k * 1024); } while (0)
; #define PG8_MMA(ai, bj, At, Bt) do { __builtin_amdgcn_s_setprio(1); _Pragma("unroll") for (int m = 0; m < 4; ++m) _Pragma("unroll") for (int n = 0; n < 2; ++n) _Pragma("unroll") for (int k = 0; k < 2; ++k) \
;         acc[ai][bj][m][n] = __builtin_amdgcn_mfma_f32_16x16x32_bf16(Bt[n][k], At[m][k], acc[ai][bj][m][n], 0, 0, 0); __builtin_amdgcn_s_setprio(0); } while (0)
; #define PG8_WAIT_V(n) asm volatile("s_waitcnt vmcnt(" #n ")" ::: "memory")
; #define PG8_WAIT_L(n) asm volatile("s_waitcnt lgkmcnt(" #n ")" ::: "memory")
; #define PG8_BAR __builtin_amdgcn_s_barrier()
; #define PG8_SCHED __builtin_amdgcn_sched_barrier(0)
; template <class Epi, class Sched, bool ALIGN_EPI = false, bool SP2 = false>
; __device__ __forceinline__ void gemm_phase(PG8_LAS unsigned char* lds, const Gemm g, const Sched& S, const Epi& E) {
;     ...
;             PG8_WAIT_V(8); PG8_WAIT_L(0); PG8_BAR; PG8_MMA(0, 0, At, B0); PG8_MMA(0, 1, At, B1); PG8_BAR; PG8_SCHED;
;             PG8_LDA(At, 0, 1); PG8_STAGE(PG8_SB(0, 0), b2, voffB); PG8_STAGE(PG8_SB(0, 1), b2 + hstep, voffB); PG8_STAGE(PG8_SA(0, 0), a2, voffA);
;             PG8_WAIT_V(8); PG8_WAIT_L(0); PG8_BAR; PG8_MMA(1, 0, At, B0); PG8_MMA(1, 1, At, B1); PG8_BAR; PG8_SCHED;
;             PG8_LDB(B0, 1, 0); PG8_LDB(B1, 1, 1); PG8_SCHED; PG8_LDA(At, 1, 0); PG8_STAGE(PG8_SA(0, 1), a2 + hstep, voffA);
;             PG8_WAIT_V(8); PG8_WAIT_L(0); PG8_BAR; PG8_MMA(0, 0, At, B0); PG8_MMA(0, 1, At, B1); PG8_BAR; PG8_SCHED;
	s_setprio 1
	v_mfma_f32_16x16x32_bf16 v[60:63], v[150:153], v[182:185], v[60:63]
	v_mfma_f32_16x16x32_bf16 v[56:59], v[158:161], v[182:185], v[56:59]
	v_mfma_f32_16x16x32_bf16 v[52:55], v[150:153], v[194:197], v[52:55]
	v_mfma_f32_16x16x32_bf16 v[48:51], v[158:161], v[194:197], v[48:51]
	v_mfma_f32_16x16x32_bf16 v[44:47], v[150:153], v[202:205], v[44:47]
	v_mfma_f32_16x16x32_bf16 v[40:43], v[158:161], v[202:205], v[40:43]
	v_mfma_f32_16x16x32_bf16 v[36:39], v[150:153], v[210:213], v[36:39]
	v_mfma_f32_16x16x32_bf16 v[32:35], v[158:161], v[210:213], v[32:35]
	v_mfma_f32_16x16x32_bf16 v[60:63], v[154:157], v[190:193], v[60:63]
	v_mfma_f32_16x16x32_bf16 v[56:59], v[162:165], v[190:193], v[56:59]
	v_mfma_f32_16x16x32_bf16 v[52:55], v[154:157], v[198:201], v[52:55]
	v_mfma_f32_16x16x32_bf16 v[48:51], v[162:165], v[198:201], v[48:51]
	v_mfma_f32_16x16x32_bf16 v[44:47], v[154:157], v[206:209], v[44:47]
	v_mfma_f32_16x16x32_bf16 v[40:43], v[162:165], v[206:209], v[40:43]
	v_mfma_f32_16x16x32_bf16 v[36:39], v[154:157], v[214:217], v[36:39]
	v_mfma_f32_16x16x32_bf16 v[32:35], v[162:165], v[214:217], v[32:35]
	v_mfma_f32_16x16x32_bf16 v[28:31], v[166:169], v[182:185], v[28:31]
	v_mfma_f32_16x16x32_bf16 v[24:27], v[174:177], v[182:185], v[24:27]
	v_mfma_f32_16x16x32_bf16 v[20:23], v[166:169], v[194:197], v[20:23]
	v_mfma_f32_16x16x32_bf16 v[16:19], v[174:177], v[194:197], v[16:19]
	v_mfma_f32_16x16x32_bf16 v[12:15], v[166:169], v[202:205], v[12:15]
	v_mfma_f32_16x16x32_bf16 v[8:11], v[174:177], v[202:205], v[8:11]
	v_mfma_f32_16x16x32_bf16 v[4:7], v[166:169], v[210:213], v[4:7]
	v_mfma_f32_16x16x32_bf16 v[0:3], v[174:177], v[210:213], v[0:3]
	v_mfma_f32_16x16x32_bf16 v[28:31], v[170:173], v[190:193], v[28:31]
	v_mfma_f32_16x16x32_bf16 v[24:27], v[178:181], v[190:193], v[24:27]
	v_mfma_f32_16x16x32_bf16 v[20:23], v[170:173], v[198:201], v[20:23]
	v_mfma_f32_16x16x32_bf16 v[16:19], v[178:181], v[198:201], v[16:19]
	v_mfma_f32_16x16x32_bf16 v[12:15], v[170:173], v[206:209], v[12:15]
	v_mfma_f32_16x16x32_bf16 v[8:11], v[178:181], v[206:209], v[8:11]
	v_mfma_f32_16x16x32_bf16 v[4:7], v[170:173], v[214:217], v[4:7]
	v_mfma_f32_16x16x32_bf16 v[0:3], v[178:181], v[214:217], v[0:3]
	s_setprio 0
	s_barrier
	s_add_i32 s83, 0, 0x18000
	s_add_i32 s86, 0, 0x1c000
	v_add_u32_e32 v162, s83, v186
	v_add_u32_e32 v178, s86, v186
	ds_read_b128 v[150:153], v162
	ds_read_b128 v[154:157], v162 offset:1024
	ds_read_b128 v[158:161], v162 offset:2048
	ds_read_b128 v[162:165], v162 offset:3072
	ds_read_b128 v[166:169], v178
	ds_read_b128 v[170:173], v178 offset:1024
	ds_read_b128 v[174:177], v178 offset:2048
	ds_read_b128 v[178:181], v178 offset:3072
	s_add_u32 s56, s56, 0x80000
	s_addc_u32 s57, s57, 0
	s_mov_b32 m0, s63
	ds_read_b128 v[182:185], v187 offset:32768
	ds_read_b128 v[190:193], v187 offset:33792
	ds_read_b128 v[194:197], v187 offset:34816
	ds_read_b128 v[198:201], v187 offset:35840
	ds_read_b128 v[202:205], v187 offset:36864
	ds_read_b128 v[206:209], v187 offset:37888
	ds_read_b128 v[210:213], v187 offset:38912
	ds_read_b128 v[214:217], v187 offset:39936
	global_load_lds_dwordx4 v128, s[56:57]
	s_mov_b32 m0, s64
	s_nop 0
	global_load_lds_dwordx4 v132, s[56:57]
	s_waitcnt vmcnt(8)
	s_waitcnt lgkmcnt(0)
	s_barrier
	s_setprio 1
	v_mfma_f32_16x16x32_bf16 v[124:127], v[150:153], v[182:185], v[124:127]
	v_mfma_f32_16x16x32_bf16 v[120:123], v[158:161], v[182:185], v[120:123]
	v_mfma_f32_16x16x32_bf16 v[116:119], v[150:153], v[194:197], v[116:119]
	v_mfma_f32_16x16x32_bf16 v[112:115], v[158:161], v[194:197], v[112:115]
	v_mfma_f32_16x16x32_bf16 v[108:111], v[150:153], v[202:205], v[108:111]
	v_mfma_f32_16x16x32_bf16 v[104:107], v[158:161], v[202:205], v[104:107]
	v_mfma_f32_16x16x32_bf16 v[100:103], v[150:153], v[210:213], v[100:103]
	v_mfma_f32_16x16x32_bf16 v[96:99], v[158:161], v[210:213], v[96:99]
	v_mfma_f32_16x16x32_bf16 v[124:127], v[154:157], v[190:193], v[124:127]
	v_mfma_f32_16x16x32_bf16 v[120:123], v[162:165], v[190:193], v[120:123]
	v_mfma_f32_16x16x32_bf16 v[116:119], v[154:157], v[198:201], v[116:119]
	v_mfma_f32_16x16x32_bf16 v[112:115], v[162:165], v[198:201], v[112:115]
	v_mfma_f32_16x16x32_bf16 v[108:111], v[154:157], v[206:209], v[108:111]
	v_mfma_f32_16x16x32_bf16 v[104:107], v[162:165], v[206:209], v[104:107]
	v_mfma_f32_16x16x32_bf16 v[100:103], v[154:157], v[214:217], v[100:103]
	v_mfma_f32_16x16x32_bf16 v[96:99], v[162:165], v[214:217], v[96:99]
	v_mfma_f32_16x16x32_bf16 v[92:95], v[166:169], v[182:185], v[92:95]
	v_mfma_f32_16x16x32_bf16 v[88:91], v[174:177], v[182:185], v[88:91]
	v_mfma_f32_16x16x32_bf16 v[84:87], v[166:169], v[194:197], v[84:87]
	v_mfma_f32_16x16x32_bf16 v[80:83], v[174:177], v[194:197], v[80:83]
	v_mfma_f32_16x16x32_bf16 v[76:79], v[166:169], v[202:205], v[76:79]
	v_mfma_f32_16x16x32_bf16 v[72:75], v[174:177], v[202:205], v[72:75]
	v_mfma_f32_16x16x32_bf16 v[68:71], v[166:169], v[210:213], v[68:71]
	v_mfma_f32_16x16x32_bf16 v[64:67], v[174:177], v[210:213], v[64:67]
	v_mfma_f32_16x16x32_bf16 v[92:95], v[170:173], v[190:193], v[92:95]
	v_mfma_f32_16x16x32_bf16 v[88:91], v[178:181], v[190:193], v[88:91]
	v_mfma_f32_16x16x32_bf16 v[84:87], v[170:173], v[198:201], v[84:87]
	v_mfma_f32_16x16x32_bf16 v[80:83], v[178:181], v[198:201], v[80:83]
	v_mfma_f32_16x16x32_bf16 v[76:79], v[170:173], v[206:209], v[76:79]
	v_mfma_f32_16x16x32_bf16 v[72:75], v[178:181], v[206:209], v[72:75]
	v_mfma_f32_16x16x32_bf16 v[68:71], v[170:173], v[214:217], v[68:71]
	v_mfma_f32_16x16x32_bf16 v[64:67], v[178:181], v[214:217], v[64:67]
	s_setprio 0
	s_barrier
; #define PG8_STAGE(bufoff, gbase, voff) do { _Pragma("unroll") for (int _i = 0; _i < 2; ++_i) \
;         __builtin_amdgcn_global_load_lds((const unsigned*)((const char*)(gbase) + (voff)[_i]), (PG8_LAS unsigned*)(lds + (bufoff) + ldsw + _i * 8192), 16, 0, 0); } while (0)
; #define PG8_LDA(dst, b, h) do { _Pragma("unroll") for (int m = 0; m < 4; ++m) _Pragma("unroll") for (int k = 0; k < 2; ++k) dst[m][k] = *(const PG8_LAS bf16x8*)(lds + PG8_SA(b, h) + aoff + m * 2048 + k * 1024); } while (0)
; #define PG8_MMA(ai, bj, At, Bt) do { __builtin_amdgcn_s_setprio(1); _Pragma("unroll") for (int m = 0; m < 4; ++m) _Pragma("unroll") for (int n = 0; n < 2; ++n) _Pragma("unroll") for (int k = 0; k < 2; ++k) \
;         acc[ai][bj][m][n] = __builtin_amdgcn_mfma_f32_16x16x32_bf16(Bt[n][k], At[m][k], acc[ai][bj][m][n], 0, 0, 0); __builtin_amdgcn_s_setprio(0); } while (0)
; #define PG8_WAIT_V(n) asm volatile("s_waitcnt vmcnt(" #n ")" ::: "memory")
; #define PG8_WAIT_L(n) asm volatile("s_waitcnt lgkmcnt(" #n ")" ::: "memory")
; #define PG8_BAR __builtin_amdgcn_s_barrier()
; #define PG8_SCHED __builtin_amdgcn_sched_barrier(0)
; template <class Epi, class Sched, bool ALIGN_EPI = false, bool SP2 = false>
; __device__ __forceinline__ void gemm_phase(PG8_LAS unsigned char* lds, const Gemm g, const Sched& S, const Epi& E) {
;     ...
;             PG8_LDA(At, 1, 1); PG8_STAGE(PG8_SB(1, 0), b3, voffB); PG8_STAGE(PG8_SB(1, 1), b3 + hstep, voffB); PG8_STAGE(PG8_SA(1, 0), a3, voffA);
;             PG8_WAIT_V(8); PG8_WAIT_L(0); PG8_BAR; PG8_MMA(1, 0, At, B0); PG8_MMA(1, 1, At, B1); PG8_BAR; PG8_SCHED;
	s_add_i32 s56, s83, s60
	v_lshl_add_u64 v[218:219], v[218:219], 0, s[14:15]
	s_mov_b32 m0, s56
	ds_read_b128 v[182:185], v187 offset:49152
	ds_read_b128 v[190:193], v187 offset:50176
	ds_read_b128 v[194:197], v187 offset:51200
	ds_read_b128 v[198:201], v187 offset:52224
	ds_read_b128 v[202:205], v187 offset:53248
	ds_read_b128 v[206:209], v187 offset:54272
	ds_read_b128 v[210:213], v187 offset:55296
	ds_read_b128 v[214:217], v187 offset:56320
	global_load_lds_dwordx4 v[218:219], off
	s_add_i32 m0, s56, 0x2000
	s_add_u32 s54, s54, 0x80080
	v_lshl_add_u64 v[218:219], v[220:221], 0, s[14:15]
	s_addc_u32 s55, s55, 0
	s_add_i32 s56, s86, s60
	global_load_lds_dwordx4 v[218:219], off
	s_mov_b32 m0, s56
	s_nop 0
	global_load_lds_dwordx4 v130, s[54:55]
	s_add_i32 m0, s56, 0x2000
	s_nop 0
	global_load_lds_dwordx4 v134, s[54:55]
	v_lshl_add_u64 v[218:219], v[222:223], 0, s[14:15]
	s_mov_b32 m0, s65
	s_nop 0
	global_load_lds_dwordx4 v[218:219], off
	v_lshl_add_u64 v[218:219], v[224:225], 0, s[14:15]
	s_mov_b32 m0, s66
	s_nop 0
	global_load_lds_dwordx4 v[218:219], off
	s_waitcnt vmcnt(8)
	s_waitcnt lgkmcnt(0)
	s_barrier
	s_setprio 1
	v_mfma_f32_16x16x32_bf16 v[60:63], v[150:153], v[182:185], v[60:63]
	v_mfma_f32_16x16x32_bf16 v[56:59], v[158:161], v[182:185], v[56:59]
	v_mfma_f32_16x16x32_bf16 v[52:55], v[150:153], v[194:197], v[52:55]
	v_mfma_f32_16x16x32_bf16 v[48:51], v[158:161], v[194:197], v[48:51]
	v_mfma_f32_16x16x32_bf16 v[44:47], v[150:153], v[202:205], v[44:47]
	v_mfma_f32_16x16x32_bf16 v[40:43], v[158:161], v[202:205], v[40:43]
	v_mfma_f32_16x16x32_bf16 v[36:39], v[150:153], v[210:213], v[36:39]
	v_mfma_f32_16x16x32_bf16 v[32:35], v[158:161], v[210:213], v[32:35]
	v_mfma_f32_16x16x32_bf16 v[60:63], v[154:157], v[190:193], v[60:63]
	v_mfma_f32_16x16x32_bf16 v[56:59], v[162:165], v[190:193], v[56:59]
	v_mfma_f32_16x16x32_bf16 v[52:55], v[154:157], v[198:201], v[52:55]
	v_mfma_f32_16x16x32_bf16 v[48:51], v[162:165], v[198:201], v[48:51]
	v_mfma_f32_16x16x32_bf16 v[44:47], v[154:157], v[206:209], v[44:47]
	v_mfma_f32_16x16x32_bf16 v[40:43], v[162:165], v[206:209], v[40:43]
	v_mfma_f32_16x16x32_bf16 v[36:39], v[154:157], v[214:217], v[36:39]
	v_mfma_f32_16x16x32_bf16 v[32:35], v[162:165], v[214:217], v[32:35]
	v_mfma_f32_16x16x32_bf16 v[28:31], v[166:169], v[182:185], v[28:31]
	v_mfma_f32_16x16x32_bf16 v[24:27], v[174:177], v[182:185], v[24:27]
	v_mfma_f32_16x16x32_bf16 v[20:23], v[166:169], v[194:197], v[20:23]
	v_mfma_f32_16x16x32_bf16 v[16:19], v[174:177], v[194:197], v[16:19]
	v_mfma_f32_16x16x32_bf16 v[12:15], v[166:169], v[202:205], v[12:15]
	v_mfma_f32_16x16x32_bf16 v[8:11], v[174:177], v[202:205], v[8:11]
	v_mfma_f32_16x16x32_bf16 v[4:7], v[166:169], v[210:213], v[4:7]
	v_mfma_f32_16x16x32_bf16 v[0:3], v[174:177], v[210:213], v[0:3]
	v_mfma_f32_16x16x32_bf16 v[28:31], v[170:173], v[190:193], v[28:31]
	v_mfma_f32_16x16x32_bf16 v[24:27], v[178:181], v[190:193], v[24:27]
	v_mfma_f32_16x16x32_bf16 v[20:23], v[170:173], v[198:201], v[20:23]
	v_mfma_f32_16x16x32_bf16 v[16:19], v[178:181], v[198:201], v[16:19]
	v_mfma_f32_16x16x32_bf16 v[12:15], v[170:173], v[206:209], v[12:15]
	v_mfma_f32_16x16x32_bf16 v[8:11], v[178:181], v[206:209], v[8:11]
	v_mfma_f32_16x16x32_bf16 v[4:7], v[170:173], v[214:217], v[4:7]
	v_mfma_f32_16x16x32_bf16 v[0:3], v[178:181], v[214:217], v[0:3]
	s_setprio 0
	s_barrier
	s_add_i32 s82, s82, 2
	s_add_u32 s46, s46, 0x100
	s_addc_u32 s47, s47, 0
	s_add_u32 s80, s80, 0x100
	s_addc_u32 s81, s81, 0
	s_cmp_gt_u32 s82, 13
	s_cbranch_scc0 .LBB0_795
	s_and_b64 vcc, exec, s[16:17]
	s_cbranch_vccz .LBB0_798
	s_barrier

; #define PG8_STAGE(bufoff, gbase, voff) do { _Pragma("unroll") for (int _i = 0; _i < 2; ++_i) \
;         __builtin_amdgcn_global_load_lds((const unsigned*)((const char*)(gbase) + (voff)[_i]), (PG8_LAS unsigned*)(lds + (bufoff) + ldsw + _i * 8192), 16, 0, 0); } while (0)
; #define PG8_LDA(dst, b, h) do { _Pragma("unroll") for (int m = 0; m < 4; ++m) _Pragma("unroll") for (int k = 0; k < 2; ++k) dst[m][k] = *(const PG8_LAS bf16x8*)(lds + PG8_SA(b, h) + aoff + m * 2048 + k * 1024); } while (0)
; #define PG8_LDB(dst, b, h) do { _Pragma("unroll") for (int n = 0; n < 2; ++n) _Pragma("unroll") for (int k = 0; k < 2; ++k) dst[n][k] = *(const PG8_LAS bf16x8*)(lds + PG8_SB(b, h) + boff + n * 2048 + k * 1024); } while (0)
; #define PG8_MMA(ai, bj, At, Bt) do { __builtin_amdgcn_s_setprio(1); _Pragma("unroll") for (int m = 0; m < 4; ++m) _Pragma("unroll") for (int n = 0; n < 2; ++n) _Pragma("unroll") for (int k = 0; k < 2; ++k) \
;         acc[ai][bj][m][n] = __builtin_amdgcn_mfma_f32_16x16x32_bf16(Bt[n][k], At[m][k], acc[ai][bj][m][n], 0, 0, 0); __builtin_amdgcn_s_setprio(0); } while (0)
; #define PG8_WAIT_V(n) asm volatile("s_waitcnt vmcnt(" #n ")" ::: "memory")
; #define PG8_WAIT_L(n) asm volatile("s_waitcnt lgkmcnt(" #n ")" ::: "memory")
; #define PG8_BAR __builtin_amdgcn_s_barrier()
; #define PG8_SCHED __builtin_amdgcn_sched_barrier(0)
; template <class Epi, class Sched, bool ALIGN_EPI = false, bool SP2 = false>
; __device__ __forceinline__ void gemm_phase(PG8_LAS unsigned char* lds, const Gemm g, const Sched& S, const Epi& E) {
;     ...
;             PG8_LDB(B0, 0, 0); PG8_LDB(B1, 0, 1); PG8_SCHED; PG8_LDA(At, 0, 0); PG8_STAGE(PG8_SA(1, 1), a1 + hstep, voffA);
;             PG8_WAIT_V(8); PG8_WAIT_L(0); PG8_BAR; PG8_MMA(0, 0, At, B0); PG8_MMA(0, 1, At, B1); PG8_BAR; PG8_SCHED;
;             PG8_LDA(At, 0, 1); PG8_STAGE(PG8_SB(0, 0), b2, voffB); PG8_STAGE(PG8_SB(0, 1), b2 + hstep, voffB); PG8_STAGE(PG8_SA(0, 0), a2, voffA);
;             PG8_WAIT_V(8); PG8_WAIT_L(0); PG8_BAR; PG8_MMA(1, 0, At, B0); PG8_MMA(1, 1, At, B1); PG8_BAR; PG8_SCHED;
.LBB0_882:
	ds_read_b128 v[128:131], v173
	ds_read_b128 v[132:135], v173 offset:1024
	ds_read_b128 v[136:139], v173 offset:2048
	ds_read_b128 v[140:143], v173 offset:3072
	ds_read_b128 v[164:167], v174
	ds_read_b128 v[168:171], v174 offset:1024
	ds_read_b128 v[178:181], v174 offset:2048
	ds_read_b128 v[182:185], v174 offset:3072
	s_add_u32 s34, s30, 0xfffc0080
	s_addc_u32 s35, s31, -1
	s_cmp_eq_u32 s61, 12
	s_cselect_b32 s37, s23, s35
	s_cselect_b32 s36, s29, s34
	s_cselect_b32 s35, s21, s60
	s_cselect_b32 s34, s58, s59
	s_add_i32 m0, s43, 0xc000
	ds_read_b128 v[190:193], v175
	ds_read_b128 v[194:197], v175 offset:1024
	ds_read_b128 v[198:201], v175 offset:2048
	ds_read_b128 v[202:205], v175 offset:3072
	ds_read_b128 v[206:209], v175 offset:4096
	ds_read_b128 v[210:213], v175 offset:5120
	ds_read_b128 v[214:217], v175 offset:6144
	ds_read_b128 v[218:221], v175 offset:7168
	global_load_lds_dwordx4 v156, s[30:31]
	s_add_i32 m0, s43, 0xe000
	s_nop 0
	global_load_lds_dwordx4 v158, s[30:31]
	s_waitcnt vmcnt(8)
	s_waitcnt lgkmcnt(0)
	s_barrier
	s_setprio 1
	v_mfma_f32_16x16x32_bf16 v[124:127], v[128:131], v[190:193], v[124:127]
	v_mfma_f32_16x16x32_bf16 v[120:123], v[136:139], v[190:193], v[120:123]
	v_mfma_f32_16x16x32_bf16 v[108:111], v[128:131], v[198:201], v[108:111]
	v_mfma_f32_16x16x32_bf16 v[104:107], v[136:139], v[198:201], v[104:107]
	v_mfma_f32_16x16x32_bf16 v[92:95], v[128:131], v[206:209], v[92:95]
	v_mfma_f32_16x16x32_bf16 v[88:91], v[136:139], v[206:209], v[88:91]
	v_mfma_f32_16x16x32_bf16 v[76:79], v[128:131], v[214:217], v[76:79]
	v_mfma_f32_16x16x32_bf16 v[72:75], v[136:139], v[214:217], v[72:75]
	v_mfma_f32_16x16x32_bf16 v[124:127], v[132:135], v[194:197], v[124:127]
	v_mfma_f32_16x16x32_bf16 v[120:123], v[140:143], v[194:197], v[120:123]
	v_mfma_f32_16x16x32_bf16 v[108:111], v[132:135], v[202:205], v[108:111]
	v_mfma_f32_16x16x32_bf16 v[104:107], v[140:143], v[202:205], v[104:107]
	v_mfma_f32_16x16x32_bf16 v[92:95], v[132:135], v[210:213], v[92:95]
	v_mfma_f32_16x16x32_bf16 v[88:91], v[140:143], v[210:213], v[88:91]
	v_mfma_f32_16x16x32_bf16 v[76:79], v[132:135], v[218:221], v[76:79]
	v_mfma_f32_16x16x32_bf16 v[72:75], v[140:143], v[218:221], v[72:75]
	v_mfma_f32_16x16x32_bf16 v[116:119], v[164:167], v[190:193], v[116:119]
	v_mfma_f32_16x16x32_bf16 v[112:115], v[178:181], v[190:193], v[112:115]
	v_mfma_f32_16x16x32_bf16 v[100:103], v[164:167], v[198:201], v[100:103]
	v_mfma_f32_16x16x32_bf16 v[96:99], v[178:181], v[198:201], v[96:99]
	v_mfma_f32_16x16x32_bf16 v[84:87], v[164:167], v[206:209], v[84:87]
	v_mfma_f32_16x16x32_bf16 v[80:83], v[178:181], v[206:209], v[80:83]
	v_mfma_f32_16x16x32_bf16 v[68:71], v[164:167], v[214:217], v[68:71]
	v_mfma_f32_16x16x32_bf16 v[64:67], v[178:181], v[214:217], v[64:67]
	v_mfma_f32_16x16x32_bf16 v[116:119], v[168:171], v[194:197], v[116:119]
	v_mfma_f32_16x16x32_bf16 v[112:115], v[182:185], v[194:197], v[112:115]
	v_mfma_f32_16x16x32_bf16 v[100:103], v[168:171], v[202:205], v[100:103]
	v_mfma_f32_16x16x32_bf16 v[96:99], v[182:185], v[202:205], v[96:99]
	v_mfma_f32_16x16x32_bf16 v[84:87], v[168:171], v[210:213], v[84:87]
	v_mfma_f32_16x16x32_bf16 v[80:83], v[182:185], v[210:213], v[80:83]
	v_mfma_f32_16x16x32_bf16 v[68:71], v[168:171], v[218:221], v[68:71]
	v_mfma_f32_16x16x32_bf16 v[64:67], v[182:185], v[218:221], v[64:67]
	s_setprio 0
	s_barrier
	s_add_i32 s62, s55, s42
	v_lshl_add_u64 v[186:187], s[34:35], 0, v[146:147]
	s_mov_b32 m0, s62
	ds_read_b128 v[190:193], v175 offset:16384
	ds_read_b128 v[194:197], v175 offset:17408
	ds_read_b128 v[198:201], v175 offset:18432
	ds_read_b128 v[202:205], v175 offset:19456
	ds_read_b128 v[206:209], v175 offset:20480
	ds_read_b128 v[210:213], v175 offset:21504
	ds_read_b128 v[214:217], v175 offset:22528
	ds_read_b128 v[218:221], v175 offset:23552
	global_load_lds_dwordx4 v[186:187], off
	s_add_i32 m0, s62, 0x2000
	s_add_u32 s62, s34, 0x40000
	v_lshl_add_u64 v[222:223], s[34:35], 0, v[150:151]
	s_addc_u32 s63, s35, 0
	s_add_i32 s64, s56, s42
	global_load_lds_dwordx4 v[222:223], off
	s_mov_b32 m0, s64
	v_lshl_add_u64 v[226:227], s[36:37], 0, v[148:149]
	global_load_lds_dwordx4 v146, s[62:63]
	s_add_i32 m0, s64, 0x2000
	s_nop 0
	global_load_lds_dwordx4 v150, s[62:63]
	v_lshl_add_u64 v[224:225], s[36:37], 0, v[144:145]
	s_mov_b32 m0, s43
	s_nop 0
	global_load_lds_dwordx4 v[224:225], off
	s_mov_b32 m0, s44
	s_nop 0
	global_load_lds_dwordx4 v[226:227], off
	s_waitcnt vmcnt(8)
	s_waitcnt lgkmcnt(0)
	s_barrier
	s_setprio 1
	v_mfma_f32_16x16x32_bf16 v[60:63], v[128:131], v[190:193], v[60:63]
	v_mfma_f32_16x16x32_bf16 v[56:59], v[136:139], v[190:193], v[56:59]
	v_mfma_f32_16x16x32_bf16 v[44:47], v[128:131], v[198:201], v[44:47]
	v_mfma_f32_16x16x32_bf16 v[40:43], v[136:139], v[198:201], v[40:43]
	v_mfma_f32_16x16x32_bf16 v[28:31], v[128:131], v[206:209], v[28:31]
	v_mfma_f32_16x16x32_bf16 v[24:27], v[136:139], v[206:209], v[24:27]
	v_mfma_f32_16x16x32_bf16 v[12:15], v[128:131], v[214:217], v[12:15]
	v_mfma_f32_16x16x32_bf16 v[8:11], v[136:139], v[214:217], v[8:11]
	v_mfma_f32_16x16x32_bf16 v[60:63], v[132:135], v[194:197], v[60:63]
	v_mfma_f32_16x16x32_bf16 v[56:59], v[140:143], v[194:197], v[56:59]
	v_mfma_f32_16x16x32_bf16 v[44:47], v[132:135], v[202:205], v[44:47]
	v_mfma_f32_16x16x32_bf16 v[40:43], v[140:143], v[202:205], v[40:43]
	v_mfma_f32_16x16x32_bf16 v[28:31], v[132:135], v[210:213], v[28:31]
	v_mfma_f32_16x16x32_bf16 v[24:27], v[140:143], v[210:213], v[24:27]
	v_mfma_f32_16x16x32_bf16 v[12:15], v[132:135], v[218:221], v[12:15]
	v_mfma_f32_16x16x32_bf16 v[8:11], v[140:143], v[218:221], v[8:11]
	v_mfma_f32_16x16x32_bf16 v[52:55], v[164:167], v[190:193], v[52:55]
	v_mfma_f32_16x16x32_bf16 v[48:51], v[178:181], v[190:193], v[48:51]
	v_mfma_f32_16x16x32_bf16 v[36:39], v[164:167], v[198:201], v[36:39]
	v_mfma_f32_16x16x32_bf16 v[32:35], v[178:181], v[198:201], v[32:35]
	v_mfma_f32_16x16x32_bf16 v[20:23], v[164:167], v[206:209], v[20:23]
	v_mfma_f32_16x16x32_bf16 v[16:19], v[178:181], v[206:209], v[16:19]
	v_mfma_f32_16x16x32_bf16 v[4:7], v[164:167], v[214:217], v[4:7]
	v_mfma_f32_16x16x32_bf16 v[0:3], v[178:181], v[214:217], v[0:3]
	v_mfma_f32_16x16x32_bf16 v[52:55], v[168:171], v[194:197], v[52:55]
	v_mfma_f32_16x16x32_bf16 v[48:51], v[182:185], v[194:197], v[48:51]
	v_mfma_f32_16x16x32_bf16 v[36:39], v[168:171], v[202:205], v[36:39]
	v_mfma_f32_16x16x32_bf16 v[32:35], v[182:185], v[202:205], v[32:35]
	v_mfma_f32_16x16x32_bf16 v[20:23], v[168:171], v[210:213], v[20:23]
	v_mfma_f32_16x16x32_bf16 v[16:19], v[182:185], v[210:213], v[16:19]
	v_mfma_f32_16x16x32_bf16 v[4:7], v[168:171], v[218:221], v[4:7]
	v_mfma_f32_16x16x32_bf16 v[0:3], v[182:185], v[218:221], v[0:3]
	s_setprio 0
	s_barrier
; #define PG8_STAGE(bufoff, gbase, voff) do { _Pragma("unroll") for (int _i = 0; _i < 2; ++_i) \
;         __builtin_amdgcn_global_load_lds((const unsigned*)((const char*)(gbase) + (voff)[_i]), (PG8_LAS unsigned*)(lds + (bufoff) + ldsw + _i * 8192), 16, 0, 0); } while (0)
; #define PG8_LDA(dst, b, h) do { _Pragma("unroll") for (int m = 0; m < 4; ++m) _Pragma("unroll") for (int k = 0; k < 2; ++k) dst[m][k] = *(const PG8_LAS bf16x8*)(lds + PG8_SA(b, h) + aoff + m * 2048 + k * 1024); } while (0)
; #define PG8_LDB(dst, b, h) do { _Pragma("unroll") for (int n = 0; n < 2; ++n) _Pragma("unroll") for (int k = 0; k < 2; ++k) dst[n][k] = *(const PG8_LAS bf16x8*)(lds + PG8_SB(b, h) + boff + n * 2048 + k * 1024); } while (0)
; #define PG8_MMA(ai, bj, At, Bt) do { __builtin_amdgcn_s_setprio(1); _Pragma("unroll") for (int m = 0; m < 4; ++m) _Pragma("unroll") for (int n = 0; n < 2; ++n) _Pragma("unroll") for (int k = 0; k < 2; ++k) \
;         acc[ai][bj][m][n] = __builtin_amdgcn_mfma_f32_16x16x32_bf16(Bt[n][k], At[m][k], acc[ai][bj][m][n], 0, 0, 0); __builtin_amdgcn_s_setprio(0); } while (0)
; #define PG8_WAIT_V(n) asm volatile("s_waitcnt vmcnt(" #n ")" ::: "memory")
; #define PG8_WAIT_L(n) asm volatile("s_waitcnt lgkmcnt(" #n ")" ::: "memory")
; #define PG8_BAR __builtin_amdgcn_s_barrier()
; #define PG8_SCHED __builtin_amdgcn_sched_barrier(0)
; template <class Epi, class Sched, bool ALIGN_EPI = false, bool SP2 = false>
; __device__ __forceinline__ void gemm_phase(PG8_LAS unsigned char* lds, const Gemm g, const Sched& S, const Epi& E) {
;     ...
;             PG8_LDB(B0, 1, 0); PG8_LDB(B1, 1, 1); PG8_SCHED; PG8_LDA(At, 1, 0); PG8_STAGE(PG8_SA(0, 1), a2 + hstep, voffA);
;             PG8_WAIT_V(8); PG8_WAIT_L(0); PG8_BAR; PG8_MMA(0, 0, At, B0); PG8_MMA(0, 1, At, B1); PG8_BAR; PG8_SCHED;
;             PG8_LDA(At, 1, 1); PG8_STAGE(PG8_SB(1, 0), b3, voffB); PG8_STAGE(PG8_SB(1, 1), b3 + hstep, voffB); PG8_STAGE(PG8_SA(1, 0), a3, voffA);
;             PG8_WAIT_V(8); PG8_WAIT_L(0); PG8_BAR; PG8_MMA(1, 0, At, B0); PG8_MMA(1, 1, At, B1); PG8_BAR; PG8_SCHED;
	s_add_i32 s62, 0, 0x18000
	s_add_i32 s63, 0, 0x1c000
	v_add_u32_e32 v140, s62, v172
	v_add_u32_e32 v177, s63, v172
	ds_read_b128 v[128:131], v140
	ds_read_b128 v[132:135], v140 offset:1024
	ds_read_b128 v[136:139], v140 offset:2048
	ds_read_b128 v[140:143], v140 offset:3072
	ds_read_b128 v[164:167], v177
	ds_read_b128 v[168:171], v177 offset:1024
	ds_read_b128 v[178:181], v177 offset:2048
	ds_read_b128 v[182:185], v177 offset:3072
	s_add_u32 s36, s36, 0x40000
	s_addc_u32 s37, s37, 0
	s_mov_b32 m0, s45
	ds_read_b128 v[190:193], v175 offset:32768
	ds_read_b128 v[194:197], v175 offset:33792
	ds_read_b128 v[198:201], v175 offset:34816
	ds_read_b128 v[202:205], v175 offset:35840
	ds_read_b128 v[206:209], v175 offset:36864
	ds_read_b128 v[210:213], v175 offset:37888
	ds_read_b128 v[214:217], v175 offset:38912
	ds_read_b128 v[218:221], v175 offset:39936
	global_load_lds_dwordx4 v144, s[36:37]
	s_mov_b32 m0, s46
	s_nop 0
	global_load_lds_dwordx4 v148, s[36:37]
	s_waitcnt vmcnt(8)
	s_waitcnt lgkmcnt(0)
	s_barrier
	s_setprio 1
	v_mfma_f32_16x16x32_bf16 v[124:127], v[128:131], v[190:193], v[124:127]
	v_mfma_f32_16x16x32_bf16 v[120:123], v[136:139], v[190:193], v[120:123]
	v_mfma_f32_16x16x32_bf16 v[108:111], v[128:131], v[198:201], v[108:111]
	v_mfma_f32_16x16x32_bf16 v[104:107], v[136:139], v[198:201], v[104:107]
	v_mfma_f32_16x16x32_bf16 v[92:95], v[128:131], v[206:209], v[92:95]
	v_mfma_f32_16x16x32_bf16 v[88:91], v[136:139], v[206:209], v[88:91]
	v_mfma_f32_16x16x32_bf16 v[76:79], v[128:131], v[214:217], v[76:79]
	v_mfma_f32_16x16x32_bf16 v[72:75], v[136:139], v[214:217], v[72:75]
	v_mfma_f32_16x16x32_bf16 v[124:127], v[132:135], v[194:197], v[124:127]
	v_mfma_f32_16x16x32_bf16 v[120:123], v[140:143], v[194:197], v[120:123]
	v_mfma_f32_16x16x32_bf16 v[108:111], v[132:135], v[202:205], v[108:111]
	v_mfma_f32_16x16x32_bf16 v[104:107], v[140:143], v[202:205], v[104:107]
	v_mfma_f32_16x16x32_bf16 v[92:95], v[132:135], v[210:213], v[92:95]
	v_mfma_f32_16x16x32_bf16 v[88:91], v[140:143], v[210:213], v[88:91]
	v_mfma_f32_16x16x32_bf16 v[76:79], v[132:135], v[218:221], v[76:79]
	v_mfma_f32_16x16x32_bf16 v[72:75], v[140:143], v[218:221], v[72:75]
	v_mfma_f32_16x16x32_bf16 v[116:119], v[164:167], v[190:193], v[116:119]
	v_mfma_f32_16x16x32_bf16 v[112:115], v[178:181], v[190:193], v[112:115]
	v_mfma_f32_16x16x32_bf16 v[100:103], v[164:167], v[198:201], v[100:103]
	v_mfma_f32_16x16x32_bf16 v[96:99], v[178:181], v[198:201], v[96:99]
	v_mfma_f32_16x16x32_bf16 v[84:87], v[164:167], v[206:209], v[84:87]
	v_mfma_f32_16x16x32_bf16 v[80:83], v[178:181], v[206:209], v[80:83]
	v_mfma_f32_16x16x32_bf16 v[68:71], v[164:167], v[214:217], v[68:71]
	v_mfma_f32_16x16x32_bf16 v[64:67], v[178:181], v[214:217], v[64:67]
	v_mfma_f32_16x16x32_bf16 v[116:119], v[168:171], v[194:197], v[116:119]
	v_mfma_f32_16x16x32_bf16 v[112:115], v[182:185], v[194:197], v[112:115]
	v_mfma_f32_16x16x32_bf16 v[100:103], v[168:171], v[202:205], v[100:103]
	v_mfma_f32_16x16x32_bf16 v[96:99], v[182:185], v[202:205], v[96:99]
	v_mfma_f32_16x16x32_bf16 v[84:87], v[168:171], v[210:213], v[84:87]
	v_mfma_f32_16x16x32_bf16 v[80:83], v[182:185], v[210:213], v[80:83]
	v_mfma_f32_16x16x32_bf16 v[68:71], v[168:171], v[218:221], v[68:71]
	v_mfma_f32_16x16x32_bf16 v[64:67], v[182:185], v[218:221], v[64:67]
	s_setprio 0
	s_barrier
	s_add_i32 s36, s62, s42
	v_lshl_add_u64 v[186:187], v[186:187], 0, s[16:17]
	s_mov_b32 m0, s36
	ds_read_b128 v[190:193], v175 offset:49152
	ds_read_b128 v[194:197], v175 offset:50176
	ds_read_b128 v[198:201], v175 offset:51200
	ds_read_b128 v[202:205], v175 offset:52224
	ds_read_b128 v[206:209], v175 offset:53248
	ds_read_b128 v[210:213], v175 offset:54272
	ds_read_b128 v[214:217], v175 offset:55296
	ds_read_b128 v[218:221], v175 offset:56320
	global_load_lds_dwordx4 v[186:187], off
	s_add_i32 m0, s36, 0x2000
	s_add_u32 s34, s34, 0x40080
	v_lshl_add_u64 v[186:187], v[222:223], 0, s[16:17]
	s_addc_u32 s35, s35, 0
	s_add_i32 s36, s63, s42
	global_load_lds_dwordx4 v[186:187], off
	s_mov_b32 m0, s36
	s_nop 0
	global_load_lds_dwordx4 v146, s[34:35]
	s_add_i32 m0, s36, 0x2000
	s_nop 0
	global_load_lds_dwordx4 v150, s[34:35]
	v_lshl_add_u64 v[186:187], v[224:225], 0, s[16:17]
	s_mov_b32 m0, s48
	s_nop 0
	global_load_lds_dwordx4 v[186:187], off
	v_lshl_add_u64 v[186:187], v[226:227], 0, s[16:17]
	s_mov_b32 m0, s49
	s_nop 0
	global_load_lds_dwordx4 v[186:187], off
	s_waitcnt vmcnt(8)
	s_waitcnt lgkmcnt(0)
	s_barrier
	s_setprio 1
	v_mfma_f32_16x16x32_bf16 v[60:63], v[128:131], v[190:193], v[60:63]
	v_mfma_f32_16x16x32_bf16 v[56:59], v[136:139], v[190:193], v[56:59]
	v_mfma_f32_16x16x32_bf16 v[44:47], v[128:131], v[198:201], v[44:47]
	v_mfma_f32_16x16x32_bf16 v[40:43], v[136:139], v[198:201], v[40:43]
	v_mfma_f32_16x16x32_bf16 v[28:31], v[128:131], v[206:209], v[28:31]
	v_mfma_f32_16x16x32_bf16 v[24:27], v[136:139], v[206:209], v[24:27]
	v_mfma_f32_16x16x32_bf16 v[12:15], v[128:131], v[214:217], v[12:15]
	v_mfma_f32_16x16x32_bf16 v[8:11], v[136:139], v[214:217], v[8:11]
	v_mfma_f32_16x16x32_bf16 v[60:63], v[132:135], v[194:197], v[60:63]
	v_mfma_f32_16x16x32_bf16 v[56:59], v[140:143], v[194:197], v[56:59]
	v_mfma_f32_16x16x32_bf16 v[44:47], v[132:135], v[202:205], v[44:47]
	v_mfma_f32_16x16x32_bf16 v[40:43], v[140:143], v[202:205], v[40:43]
	v_mfma_f32_16x16x32_bf16 v[28:31], v[132:135], v[210:213], v[28:31]
	v_mfma_f32_16x16x32_bf16 v[24:27], v[140:143], v[210:213], v[24:27]
	v_mfma_f32_16x16x32_bf16 v[12:15], v[132:135], v[218:221], v[12:15]
	v_mfma_f32_16x16x32_bf16 v[8:11], v[140:143], v[218:221], v[8:11]
	v_mfma_f32_16x16x32_bf16 v[52:55], v[164:167], v[190:193], v[52:55]
	v_mfma_f32_16x16x32_bf16 v[48:51], v[178:181], v[190:193], v[48:51]
	v_mfma_f32_16x16x32_bf16 v[36:39], v[164:167], v[198:201], v[36:39]
	v_mfma_f32_16x16x32_bf16 v[32:35], v[178:181], v[198:201], v[32:35]
	v_mfma_f32_16x16x32_bf16 v[20:23], v[164:167], v[206:209], v[20:23]
	v_mfma_f32_16x16x32_bf16 v[16:19], v[178:181], v[206:209], v[16:19]
	v_mfma_f32_16x16x32_bf16 v[4:7], v[164:167], v[214:217], v[4:7]
	v_mfma_f32_16x16x32_bf16 v[0:3], v[178:181], v[214:217], v[0:3]
	v_mfma_f32_16x16x32_bf16 v[52:55], v[168:171], v[194:197], v[52:55]
	v_mfma_f32_16x16x32_bf16 v[48:51], v[182:185], v[194:197], v[48:51]
	v_mfma_f32_16x16x32_bf16 v[36:39], v[168:171], v[202:205], v[36:39]
	v_mfma_f32_16x16x32_bf16 v[32:35], v[182:185], v[202:205], v[32:35]
	v_mfma_f32_16x16x32_bf16 v[20:23], v[168:171], v[210:213], v[20:23]
	v_mfma_f32_16x16x32_bf16 v[16:19], v[182:185], v[210:213], v[16:19]
	v_mfma_f32_16x16x32_bf16 v[4:7], v[168:171], v[218:221], v[4:7]
	v_mfma_f32_16x16x32_bf16 v[0:3], v[182:185], v[218:221], v[0:3]
	s_setprio 0
	s_barrier
	s_add_i32 s61, s61, 2
	s_add_u32 s30, s30, 0x100
	s_addc_u32 s31, s31, 0
	s_add_u32 s59, s59, 0x100
	s_addc_u32 s60, s60, 0
	s_cmp_gt_u32 s61, 13
	s_cbranch_scc0 .LBB0_882
	s_and_b64 vcc, exec, s[18:19]
	s_cbranch_vccz .LBB0_885
	s_barrier

; #define PG8_STAGE(bufoff, gbase, voff) do { _Pragma("unroll") for (int _i = 0; _i < 2; ++_i) \
;         __builtin_amdgcn_global_load_lds((const unsigned*)((const char*)(gbase) + (voff)[_i]), (PG8_LAS unsigned*)(lds + (bufoff) + ldsw + _i * 8192), 16, 0, 0); } while (0)
; #define PG8_LDA(dst, b, h) do { _Pragma("unroll") for (int m = 0; m < 4; ++m) _Pragma("unroll") for (int k = 0; k < 2; ++k) dst[m][k] = *(const PG8_LAS bf16x8*)(lds + PG8_SA(b, h) + aoff + m * 2048 + k * 1024); } while (0)
; #define PG8_LDB(dst, b, h) do { _Pragma("unroll") for (int n = 0; n < 2; ++n) _Pragma("unroll") for (int k = 0; k < 2; ++k) dst[n][k] = *(const PG8_LAS bf16x8*)(lds + PG8_SB(b, h) + boff + n * 2048 + k * 1024); } while (0)
; #define PG8_MMA(ai, bj, At, Bt) do { __builtin_amdgcn_s_setprio(1); _Pragma("unroll") for (int m = 0; m < 4; ++m) _Pragma("unroll") for (int n = 0; n < 2; ++n) _Pragma("unroll") for (int k = 0; k < 2; ++k) \
;         acc[ai][bj][m][n] = __builtin_amdgcn_mfma_f32_16x16x32_bf16(Bt[n][k], At[m][k], acc[ai][bj][m][n], 0, 0, 0); __builtin_amdgcn_s_setprio(0); } while (0)
; #define PG8_WAIT_V(n) asm volatile("s_waitcnt vmcnt(" #n ")" ::: "memory")
; #define PG8_WAIT_L(n) asm volatile("s_waitcnt lgkmcnt(" #n ")" ::: "memory")
; #define PG8_BAR __builtin_amdgcn_s_barrier()
; #define PG8_SCHED __builtin_amdgcn_sched_barrier(0)
; template <class Epi, class Sched, bool ALIGN_EPI = false, bool SP2 = false>
; __device__ __forceinline__ void gemm_phase(PG8_LAS unsigned char* lds, const Gemm g, const Sched& S, const Epi& E) {
;     ...
;             PG8_LDB(B0, 0, 0); PG8_LDB(B1, 0, 1); PG8_SCHED; PG8_LDA(At, 0, 0); PG8_STAGE(PG8_SA(1, 1), a1 + hstep, voffA);
;             PG8_WAIT_V(8); PG8_WAIT_L(0); PG8_BAR; PG8_MMA(0, 0, At, B0); PG8_MMA(0, 1, At, B1); PG8_BAR; PG8_SCHED;
;             PG8_LDA(At, 0, 1); PG8_STAGE(PG8_SB(0, 0), b2, voffB); PG8_STAGE(PG8_SB(0, 1), b2 + hstep, voffB); PG8_STAGE(PG8_SA(0, 0), a2, voffA);
;             PG8_WAIT_V(8); PG8_WAIT_L(0); PG8_BAR; PG8_MMA(1, 0, At, B0); PG8_MMA(1, 1, At, B1); PG8_BAR; PG8_SCHED;
.LBB0_969:
	ds_read_b128 v[128:131], v191
	ds_read_b128 v[132:135], v191 offset:1024
	ds_read_b128 v[136:139], v191 offset:2048
	ds_read_b128 v[140:143], v191 offset:3072
	ds_read_b128 v[144:147], v192
	ds_read_b128 v[148:151], v192 offset:1024
	ds_read_b128 v[172:175], v192 offset:2048
	ds_read_b128 v[176:179], v192 offset:3072
	s_add_u32 s26, s24, 0xfffc0080
	s_addc_u32 s27, s25, -1
	s_cmp_eq_u32 s57, 12
	s_cselect_b32 s29, s17, s27
	s_cselect_b32 s28, s51, s26
	s_cselect_b32 s27, s15, s56
	s_cselect_b32 s26, s54, s55
	s_add_i32 m0, s39, 0xc000
	ds_read_b128 v[180:183], v193
	ds_read_b128 v[184:187], v193 offset:1024
	ds_read_b128 v[196:199], v193 offset:2048
	ds_read_b128 v[200:203], v193 offset:3072
	ds_read_b128 v[204:207], v193 offset:4096
	ds_read_b128 v[208:211], v193 offset:5120
	ds_read_b128 v[212:215], v193 offset:6144
	ds_read_b128 v[216:219], v193 offset:7168
	global_load_lds_dwordx4 v164, s[24:25]
	s_add_i32 m0, s39, 0xe000
	s_nop 0
	global_load_lds_dwordx4 v166, s[24:25]
	s_waitcnt vmcnt(8)
	s_waitcnt lgkmcnt(0)
	s_barrier
	s_setprio 1
	v_mfma_f32_16x16x32_bf16 v[124:127], v[128:131], v[180:183], v[124:127]
	v_mfma_f32_16x16x32_bf16 v[120:123], v[136:139], v[180:183], v[120:123]
	v_mfma_f32_16x16x32_bf16 v[108:111], v[128:131], v[196:199], v[108:111]
	v_mfma_f32_16x16x32_bf16 v[104:107], v[136:139], v[196:199], v[104:107]
	v_mfma_f32_16x16x32_bf16 v[92:95], v[128:131], v[204:207], v[92:95]
	v_mfma_f32_16x16x32_bf16 v[84:87], v[136:139], v[204:207], v[84:87]
	v_mfma_f32_16x16x32_bf16 v[76:79], v[128:131], v[212:215], v[76:79]
	v_mfma_f32_16x16x32_bf16 v[72:75], v[136:139], v[212:215], v[72:75]
	v_mfma_f32_16x16x32_bf16 v[124:127], v[132:135], v[184:187], v[124:127]
	v_mfma_f32_16x16x32_bf16 v[120:123], v[140:143], v[184:187], v[120:123]
	v_mfma_f32_16x16x32_bf16 v[108:111], v[132:135], v[200:203], v[108:111]
	v_mfma_f32_16x16x32_bf16 v[104:107], v[140:143], v[200:203], v[104:107]
	v_mfma_f32_16x16x32_bf16 v[92:95], v[132:135], v[208:211], v[92:95]
	v_mfma_f32_16x16x32_bf16 v[84:87], v[140:143], v[208:211], v[84:87]
	v_mfma_f32_16x16x32_bf16 v[76:79], v[132:135], v[216:219], v[76:79]
	v_mfma_f32_16x16x32_bf16 v[72:75], v[140:143], v[216:219], v[72:75]
	v_mfma_f32_16x16x32_bf16 v[116:119], v[144:147], v[180:183], v[116:119]
	v_mfma_f32_16x16x32_bf16 v[112:115], v[172:175], v[180:183], v[112:115]
	v_mfma_f32_16x16x32_bf16 v[100:103], v[144:147], v[196:199], v[100:103]
	v_mfma_f32_16x16x32_bf16 v[96:99], v[172:175], v[196:199], v[96:99]
	v_mfma_f32_16x16x32_bf16 v[88:91], v[144:147], v[204:207], v[88:91]
	v_mfma_f32_16x16x32_bf16 v[80:83], v[172:175], v[204:207], v[80:83]
	v_mfma_f32_16x16x32_bf16 v[68:71], v[144:147], v[212:215], v[68:71]
	v_mfma_f32_16x16x32_bf16 v[64:67], v[172:175], v[212:215], v[64:67]
	v_mfma_f32_16x16x32_bf16 v[116:119], v[148:151], v[184:187], v[116:119]
	v_mfma_f32_16x16x32_bf16 v[112:115], v[176:179], v[184:187], v[112:115]
	v_mfma_f32_16x16x32_bf16 v[100:103], v[148:151], v[200:203], v[100:103]
	v_mfma_f32_16x16x32_bf16 v[96:99], v[176:179], v[200:203], v[96:99]
	v_mfma_f32_16x16x32_bf16 v[88:91], v[148:151], v[208:211], v[88:91]
	v_mfma_f32_16x16x32_bf16 v[80:83], v[176:179], v[208:211], v[80:83]
	v_mfma_f32_16x16x32_bf16 v[68:71], v[148:151], v[216:219], v[68:71]
	v_mfma_f32_16x16x32_bf16 v[64:67], v[176:179], v[216:219], v[64:67]
	s_setprio 0
	s_barrier
	s_add_i32 s58, s47, s36
	v_lshl_add_u64 v[220:221], s[26:27], 0, v[156:157]
	s_mov_b32 m0, s58
	ds_read_b128 v[180:183], v193 offset:16384
	ds_read_b128 v[184:187], v193 offset:17408
	ds_read_b128 v[196:199], v193 offset:18432
	ds_read_b128 v[200:203], v193 offset:19456
	ds_read_b128 v[204:207], v193 offset:20480
	ds_read_b128 v[208:211], v193 offset:21504
	ds_read_b128 v[212:215], v193 offset:22528
	ds_read_b128 v[216:219], v193 offset:23552
	global_load_lds_dwordx4 v[220:221], off
	s_add_i32 m0, s58, 0x2000
	s_add_u32 s58, s26, 0x40000
	v_lshl_add_u64 v[222:223], s[26:27], 0, v[152:153]
	s_addc_u32 s59, s27, 0
	s_add_i32 s60, s48, s36
	global_load_lds_dwordx4 v[222:223], off
	s_mov_b32 m0, s60
	v_lshl_add_u64 v[226:227], s[28:29], 0, v[154:155]
	global_load_lds_dwordx4 v156, s[58:59]
	s_add_i32 m0, s60, 0x2000
	s_nop 0
	global_load_lds_dwordx4 v152, s[58:59]
	v_lshl_add_u64 v[224:225], s[28:29], 0, v[158:159]
	s_mov_b32 m0, s39
	s_nop 0
	global_load_lds_dwordx4 v[224:225], off
	s_mov_b32 m0, s40
	s_nop 0
	global_load_lds_dwordx4 v[226:227], off
	s_waitcnt vmcnt(8)
	s_waitcnt lgkmcnt(0)
	s_barrier
	s_setprio 1
	v_mfma_f32_16x16x32_bf16 v[60:63], v[128:131], v[180:183], v[60:63]
	v_mfma_f32_16x16x32_bf16 v[52:55], v[136:139], v[180:183], v[52:55]
	v_mfma_f32_16x16x32_bf16 v[44:47], v[128:131], v[196:199], v[44:47]
	v_mfma_f32_16x16x32_bf16 v[40:43], v[136:139], v[196:199], v[40:43]
	v_mfma_f32_16x16x32_bf16 v[28:31], v[128:131], v[204:207], v[28:31]
	v_mfma_f32_16x16x32_bf16 v[20:23], v[136:139], v[204:207], v[20:23]
	v_mfma_f32_16x16x32_bf16 v[12:15], v[128:131], v[212:215], v[12:15]
	v_mfma_f32_16x16x32_bf16 v[8:11], v[136:139], v[212:215], v[8:11]
	v_mfma_f32_16x16x32_bf16 v[60:63], v[132:135], v[184:187], v[60:63]
	v_mfma_f32_16x16x32_bf16 v[52:55], v[140:143], v[184:187], v[52:55]
	v_mfma_f32_16x16x32_bf16 v[44:47], v[132:135], v[200:203], v[44:47]
	v_mfma_f32_16x16x32_bf16 v[40:43], v[140:143], v[200:203], v[40:43]
	v_mfma_f32_16x16x32_bf16 v[28:31], v[132:135], v[208:211], v[28:31]
	v_mfma_f32_16x16x32_bf16 v[20:23], v[140:143], v[208:211], v[20:23]
	v_mfma_f32_16x16x32_bf16 v[12:15], v[132:135], v[216:219], v[12:15]
	v_mfma_f32_16x16x32_bf16 v[8:11], v[140:143], v[216:219], v[8:11]
	v_mfma_f32_16x16x32_bf16 v[56:59], v[144:147], v[180:183], v[56:59]
	v_mfma_f32_16x16x32_bf16 v[48:51], v[172:175], v[180:183], v[48:51]
	v_mfma_f32_16x16x32_bf16 v[36:39], v[144:147], v[196:199], v[36:39]
	v_mfma_f32_16x16x32_bf16 v[32:35], v[172:175], v[196:199], v[32:35]
	v_mfma_f32_16x16x32_bf16 v[24:27], v[144:147], v[204:207], v[24:27]
	v_mfma_f32_16x16x32_bf16 v[16:19], v[172:175], v[204:207], v[16:19]
	v_mfma_f32_16x16x32_bf16 v[4:7], v[144:147], v[212:215], v[4:7]
	v_mfma_f32_16x16x32_bf16 v[0:3], v[172:175], v[212:215], v[0:3]
	v_mfma_f32_16x16x32_bf16 v[56:59], v[148:151], v[184:187], v[56:59]
	v_mfma_f32_16x16x32_bf16 v[48:51], v[176:179], v[184:187], v[48:51]
	v_mfma_f32_16x16x32_bf16 v[36:39], v[148:151], v[200:203], v[36:39]
	v_mfma_f32_16x16x32_bf16 v[32:35], v[176:179], v[200:203], v[32:35]
	v_mfma_f32_16x16x32_bf16 v[24:27], v[148:151], v[208:211], v[24:27]
	v_mfma_f32_16x16x32_bf16 v[16:19], v[176:179], v[208:211], v[16:19]
	v_mfma_f32_16x16x32_bf16 v[4:7], v[148:151], v[216:219], v[4:7]
	v_mfma_f32_16x16x32_bf16 v[0:3], v[176:179], v[216:219], v[0:3]
	s_setprio 0
	s_barrier
; #define PG8_STAGE(bufoff, gbase, voff) do { _Pragma("unroll") for (int _i = 0; _i < 2; ++_i) \
;         __builtin_amdgcn_global_load_lds((const unsigned*)((const char*)(gbase) + (voff)[_i]), (PG8_LAS unsigned*)(lds + (bufoff) + ldsw + _i * 8192), 16, 0, 0); } while (0)
; #define PG8_LDA(dst, b, h) do { _Pragma("unroll") for (int m = 0; m < 4; ++m) _Pragma("unroll") for (int k = 0; k < 2; ++k) dst[m][k] = *(const PG8_LAS bf16x8*)(lds + PG8_SA(b, h) + aoff + m * 2048 + k * 1024); } while (0)
; #define PG8_LDB(dst, b, h) do { _Pragma("unroll") for (int n = 0; n < 2; ++n) _Pragma("unroll") for (int k = 0; k < 2; ++k) dst[n][k] = *(const PG8_LAS bf16x8*)(lds + PG8_SB(b, h) + boff + n * 2048 + k * 1024); } while (0)
; #define PG8_MMA(ai, bj, At, Bt) do { __builtin_amdgcn_s_setprio(1); _Pragma("unroll") for (int m = 0; m < 4; ++m) _Pragma("unroll") for (int n = 0; n < 2; ++n) _Pragma("unroll") for (int k = 0; k < 2; ++k) \
;         acc[ai][bj][m][n] = __builtin_amdgcn_mfma_f32_16x16x32_bf16(Bt[n][k], At[m][k], acc[ai][bj][m][n], 0, 0, 0); __builtin_amdgcn_s_setprio(0); } while (0)
; #define PG8_WAIT_V(n) asm volatile("s_waitcnt vmcnt(" #n ")" ::: "memory")
; #define PG8_WAIT_L(n) asm volatile("s_waitcnt lgkmcnt(" #n ")" ::: "memory")
; #define PG8_BAR __builtin_amdgcn_s_barrier()
; #define PG8_SCHED __builtin_amdgcn_sched_barrier(0)
; template <class Epi, class Sched, bool ALIGN_EPI = false, bool SP2 = false>
; __device__ __forceinline__ void gemm_phase(PG8_LAS unsigned char* lds, const Gemm g, const Sched& S, const Epi& E) {
;     ...
;             PG8_LDB(B0, 1, 0); PG8_LDB(B1, 1, 1); PG8_SCHED; PG8_LDA(At, 1, 0); PG8_STAGE(PG8_SA(0, 1), a2 + hstep, voffA);
;             PG8_WAIT_V(8); PG8_WAIT_L(0); PG8_BAR; PG8_MMA(0, 0, At, B0); PG8_MMA(0, 1, At, B1); PG8_BAR; PG8_SCHED;
;             PG8_LDA(At, 1, 1); PG8_STAGE(PG8_SB(1, 0), b3, voffB); PG8_STAGE(PG8_SB(1, 1), b3 + hstep, voffB); PG8_STAGE(PG8_SA(1, 0), a3, voffA);
;             PG8_WAIT_V(8); PG8_WAIT_L(0); PG8_BAR; PG8_MMA(1, 0, At, B0); PG8_MMA(1, 1, At, B1); PG8_BAR; PG8_SCHED;
	s_add_i32 s58, 0, 0x18000
	s_add_i32 s59, 0, 0x1c000
	v_add_u32_e32 v140, s58, v190
	v_add_u32_e32 v176, s59, v190
	ds_read_b128 v[128:131], v140
	ds_read_b128 v[132:135], v140 offset:1024
	ds_read_b128 v[136:139], v140 offset:2048
	ds_read_b128 v[140:143], v140 offset:3072
	ds_read_b128 v[144:147], v176
	ds_read_b128 v[148:151], v176 offset:1024
	ds_read_b128 v[172:175], v176 offset:2048
	ds_read_b128 v[176:179], v176 offset:3072
	s_add_u32 s28, s28, 0x40000
	s_addc_u32 s29, s29, 0
	s_mov_b32 m0, s41
	ds_read_b128 v[180:183], v193 offset:32768
	ds_read_b128 v[184:187], v193 offset:33792
	ds_read_b128 v[196:199], v193 offset:34816
	ds_read_b128 v[200:203], v193 offset:35840
	ds_read_b128 v[204:207], v193 offset:36864
	ds_read_b128 v[208:211], v193 offset:37888
	ds_read_b128 v[212:215], v193 offset:38912
	ds_read_b128 v[216:219], v193 offset:39936
	global_load_lds_dwordx4 v158, s[28:29]
	s_mov_b32 m0, s42
	s_nop 0
	global_load_lds_dwordx4 v154, s[28:29]
	s_waitcnt vmcnt(8)
	s_waitcnt lgkmcnt(0)
	s_barrier
	s_setprio 1
	v_mfma_f32_16x16x32_bf16 v[124:127], v[128:131], v[180:183], v[124:127]
	v_mfma_f32_16x16x32_bf16 v[120:123], v[136:139], v[180:183], v[120:123]
	v_mfma_f32_16x16x32_bf16 v[108:111], v[128:131], v[196:199], v[108:111]
	v_mfma_f32_16x16x32_bf16 v[104:107], v[136:139], v[196:199], v[104:107]
	v_mfma_f32_16x16x32_bf16 v[92:95], v[128:131], v[204:207], v[92:95]
	v_mfma_f32_16x16x32_bf16 v[84:87], v[136:139], v[204:207], v[84:87]
	v_mfma_f32_16x16x32_bf16 v[76:79], v[128:131], v[212:215], v[76:79]
	v_mfma_f32_16x16x32_bf16 v[72:75], v[136:139], v[212:215], v[72:75]
	v_mfma_f32_16x16x32_bf16 v[124:127], v[132:135], v[184:187], v[124:127]
	v_mfma_f32_16x16x32_bf16 v[120:123], v[140:143], v[184:187], v[120:123]
	v_mfma_f32_16x16x32_bf16 v[108:111], v[132:135], v[200:203], v[108:111]
	v_mfma_f32_16x16x32_bf16 v[104:107], v[140:143], v[200:203], v[104:107]
	v_mfma_f32_16x16x32_bf16 v[92:95], v[132:135], v[208:211], v[92:95]
	v_mfma_f32_16x16x32_bf16 v[84:87], v[140:143], v[208:211], v[84:87]
	v_mfma_f32_16x16x32_bf16 v[76:79], v[132:135], v[216:219], v[76:79]
	v_mfma_f32_16x16x32_bf16 v[72:75], v[140:143], v[216:219], v[72:75]
	v_mfma_f32_16x16x32_bf16 v[116:119], v[144:147], v[180:183], v[116:119]
	v_mfma_f32_16x16x32_bf16 v[112:115], v[172:175], v[180:183], v[112:115]
	v_mfma_f32_16x16x32_bf16 v[100:103], v[144:147], v[196:199], v[100:103]
	v_mfma_f32_16x16x32_bf16 v[96:99], v[172:175], v[196:199], v[96:99]
	v_mfma_f32_16x16x32_bf16 v[88:91], v[144:147], v[204:207], v[88:91]
	v_mfma_f32_16x16x32_bf16 v[80:83], v[172:175], v[204:207], v[80:83]
	v_mfma_f32_16x16x32_bf16 v[68:71], v[144:147], v[212:215], v[68:71]
	v_mfma_f32_16x16x32_bf16 v[64:67], v[172:175], v[212:215], v[64:67]
	v_mfma_f32_16x16x32_bf16 v[116:119], v[148:151], v[184:187], v[116:119]
	v_mfma_f32_16x16x32_bf16 v[112:115], v[176:179], v[184:187], v[112:115]
	v_mfma_f32_16x16x32_bf16 v[100:103], v[148:151], v[200:203], v[100:103]
	v_mfma_f32_16x16x32_bf16 v[96:99], v[176:179], v[200:203], v[96:99]
	v_mfma_f32_16x16x32_bf16 v[88:91], v[148:151], v[208:211], v[88:91]
	v_mfma_f32_16x16x32_bf16 v[80:83], v[176:179], v[208:211], v[80:83]
	v_mfma_f32_16x16x32_bf16 v[68:71], v[148:151], v[216:219], v[68:71]
	v_mfma_f32_16x16x32_bf16 v[64:67], v[176:179], v[216:219], v[64:67]
	s_setprio 0
	s_barrier
	s_add_i32 s28, s58, s36
	v_lshl_add_u64 v[220:221], v[220:221], 0, s[10:11]
	s_mov_b32 m0, s28
	ds_read_b128 v[180:183], v193 offset:49152
	ds_read_b128 v[184:187], v193 offset:50176
	ds_read_b128 v[196:199], v193 offset:51200
	ds_read_b128 v[200:203], v193 offset:52224
	ds_read_b128 v[204:207], v193 offset:53248
	ds_read_b128 v[208:211], v193 offset:54272
	ds_read_b128 v[212:215], v193 offset:55296
	ds_read_b128 v[216:219], v193 offset:56320
	global_load_lds_dwordx4 v[220:221], off
	s_add_i32 m0, s28, 0x2000
	s_add_u32 s26, s26, 0x40080
	v_lshl_add_u64 v[220:221], v[222:223], 0, s[10:11]
	s_addc_u32 s27, s27, 0
	s_add_i32 s28, s59, s36
	global_load_lds_dwordx4 v[220:221], off
	s_mov_b32 m0, s28
	s_nop 0
	global_load_lds_dwordx4 v156, s[26:27]
	s_add_i32 m0, s28, 0x2000
	s_nop 0
	global_load_lds_dwordx4 v152, s[26:27]
	v_lshl_add_u64 v[220:221], v[224:225], 0, s[10:11]
	s_mov_b32 m0, s43
	s_nop 0
	global_load_lds_dwordx4 v[220:221], off
	v_lshl_add_u64 v[220:221], v[226:227], 0, s[10:11]
	s_mov_b32 m0, s44
	s_nop 0
	global_load_lds_dwordx4 v[220:221], off
	s_waitcnt vmcnt(8)
	s_waitcnt lgkmcnt(0)
	s_barrier
	s_setprio 1
	v_mfma_f32_16x16x32_bf16 v[60:63], v[128:131], v[180:183], v[60:63]
	v_mfma_f32_16x16x32_bf16 v[52:55], v[136:139], v[180:183], v[52:55]
	v_mfma_f32_16x16x32_bf16 v[44:47], v[128:131], v[196:199], v[44:47]
	v_mfma_f32_16x16x32_bf16 v[40:43], v[136:139], v[196:199], v[40:43]
	v_mfma_f32_16x16x32_bf16 v[28:31], v[128:131], v[204:207], v[28:31]
	v_mfma_f32_16x16x32_bf16 v[20:23], v[136:139], v[204:207], v[20:23]
	v_mfma_f32_16x16x32_bf16 v[12:15], v[128:131], v[212:215], v[12:15]
	v_mfma_f32_16x16x32_bf16 v[8:11], v[136:139], v[212:215], v[8:11]
	v_mfma_f32_16x16x32_bf16 v[60:63], v[132:135], v[184:187], v[60:63]
	v_mfma_f32_16x16x32_bf16 v[52:55], v[140:143], v[184:187], v[52:55]
	v_mfma_f32_16x16x32_bf16 v[44:47], v[132:135], v[200:203], v[44:47]
	v_mfma_f32_16x16x32_bf16 v[40:43], v[140:143], v[200:203], v[40:43]
	v_mfma_f32_16x16x32_bf16 v[28:31], v[132:135], v[208:211], v[28:31]
	v_mfma_f32_16x16x32_bf16 v[20:23], v[140:143], v[208:211], v[20:23]
	v_mfma_f32_16x16x32_bf16 v[12:15], v[132:135], v[216:219], v[12:15]
	v_mfma_f32_16x16x32_bf16 v[8:11], v[140:143], v[216:219], v[8:11]
	v_mfma_f32_16x16x32_bf16 v[56:59], v[144:147], v[180:183], v[56:59]
	v_mfma_f32_16x16x32_bf16 v[48:51], v[172:175], v[180:183], v[48:51]
	v_mfma_f32_16x16x32_bf16 v[36:39], v[144:147], v[196:199], v[36:39]
	v_mfma_f32_16x16x32_bf16 v[32:35], v[172:175], v[196:199], v[32:35]
	v_mfma_f32_16x16x32_bf16 v[24:27], v[144:147], v[204:207], v[24:27]
	v_mfma_f32_16x16x32_bf16 v[16:19], v[172:175], v[204:207], v[16:19]
	v_mfma_f32_16x16x32_bf16 v[4:7], v[144:147], v[212:215], v[4:7]
	v_mfma_f32_16x16x32_bf16 v[0:3], v[172:175], v[212:215], v[0:3]
	v_mfma_f32_16x16x32_bf16 v[56:59], v[148:151], v[184:187], v[56:59]
	v_mfma_f32_16x16x32_bf16 v[48:51], v[176:179], v[184:187], v[48:51]
	v_mfma_f32_16x16x32_bf16 v[36:39], v[148:151], v[200:203], v[36:39]
	v_mfma_f32_16x16x32_bf16 v[32:35], v[176:179], v[200:203], v[32:35]
	v_mfma_f32_16x16x32_bf16 v[24:27], v[148:151], v[208:211], v[24:27]
	v_mfma_f32_16x16x32_bf16 v[16:19], v[176:179], v[208:211], v[16:19]
	v_mfma_f32_16x16x32_bf16 v[4:7], v[148:151], v[216:219], v[4:7]
	v_mfma_f32_16x16x32_bf16 v[0:3], v[176:179], v[216:219], v[0:3]
	s_setprio 0
	s_barrier
	s_add_i32 s57, s57, 2
	s_add_u32 s24, s24, 0x100
	s_addc_u32 s25, s25, 0
	s_add_u32 s55, s55, 0x100
	s_addc_u32 s56, s56, 0
	s_cmp_gt_u32 s57, 13
	s_cbranch_scc0 .LBB0_969
	s_and_b64 vcc, exec, s[12:13]
	s_cbranch_vccz .LBB0_972
	s_barrier

; #define PG8_STAGE(bufoff, gbase, voff) do { _Pragma("unroll") for (int _i = 0; _i < 2; ++_i) \
;         __builtin_amdgcn_global_load_lds((const unsigned*)((const char*)(gbase) + (voff)[_i]), (PG8_LAS unsigned*)(lds + (bufoff) + ldsw + _i * 8192), 16, 0, 0); } while (0)
; #define PG8_LDA(dst, b, h) do { _Pragma("unroll") for (int m = 0; m < 4; ++m) _Pragma("unroll") for (int k = 0; k < 2; ++k) dst[m][k] = *(const PG8_LAS bf16x8*)(lds + PG8_SA(b, h) + aoff + m * 2048 + k * 1024); } while (0)
; #define PG8_LDB(dst, b, h) do { _Pragma("unroll") for (int n = 0; n < 2; ++n) _Pragma("unroll") for (int k = 0; k < 2; ++k) dst[n][k] = *(const PG8_LAS bf16x8*)(lds + PG8_SB(b, h) + boff + n * 2048 + k * 1024); } while (0)
; #define PG8_MMA(ai, bj, At, Bt) do { __builtin_amdgcn_s_setprio(1); _Pragma("unroll") for (int m = 0; m < 4; ++m) _Pragma("unroll") for (int n = 0; n < 2; ++n) _Pragma("unroll") for (int k = 0; k < 2; ++k) \
;         acc[ai][bj][m][n] = __builtin_amdgcn_mfma_f32_16x16x32_bf16(Bt[n][k], At[m][k], acc[ai][bj][m][n], 0, 0, 0); __builtin_amdgcn_s_setprio(0); } while (0)
; #define PG8_WAIT_V(n) asm volatile("s_waitcnt vmcnt(" #n ")" ::: "memory")
; #define PG8_WAIT_L(n) asm volatile("s_waitcnt lgkmcnt(" #n ")" ::: "memory")
; #define PG8_BAR __builtin_amdgcn_s_barrier()
; #define PG8_SCHED __builtin_amdgcn_sched_barrier(0)
; template <class Epi, class Sched, bool ALIGN_EPI = false, bool SP2 = false>
; __device__ __forceinline__ void gemm_phase(PG8_LAS unsigned char* lds, const Gemm g, const Sched& S, const Epi& E) {
;     ...
;             PG8_LDB(B0, 0, 0); PG8_LDB(B1, 0, 1); PG8_SCHED; PG8_LDA(At, 0, 0); PG8_STAGE(PG8_SA(1, 1), a1 + hstep, voffA);
;             PG8_WAIT_V(8); PG8_WAIT_L(0); PG8_BAR; PG8_MMA(0, 0, At, B0); PG8_MMA(0, 1, At, B1); PG8_BAR; PG8_SCHED;
;             PG8_LDA(At, 0, 1); PG8_STAGE(PG8_SB(0, 0), b2, voffB); PG8_STAGE(PG8_SB(0, 1), b2 + hstep, voffB); PG8_STAGE(PG8_SA(0, 0), a2, voffA);
;             PG8_WAIT_V(8); PG8_WAIT_L(0); PG8_BAR; PG8_MMA(1, 0, At, B0); PG8_MMA(1, 1, At, B1); PG8_BAR; PG8_SCHED;
.LBB0_1052:
	ds_read_b128 v[146:149], v153
	ds_read_b128 v[156:159], v153 offset:1024
	ds_read_b128 v[160:163], v153 offset:2048
	ds_read_b128 v[164:167], v153 offset:3072
	ds_read_b128 v[168:171], v154
	ds_read_b128 v[172:175], v154 offset:1024
	ds_read_b128 v[176:179], v154 offset:2048
	ds_read_b128 v[180:183], v154 offset:3072
	s_add_u32 s24, s22, 0x100
	s_addc_u32 s25, s23, 0
	s_cmp_eq_u32 s56, 40
	s_cselect_b32 s29, s3, s25
	s_cselect_b32 s28, s2, s24
	s_cselect_b32 s27, s21, s55
	s_cselect_b32 s26, s20, s54
	s_add_i32 m0, s38, 0xc000
	ds_read_b128 v[184:187], v155
	ds_read_b128 v[188:191], v155 offset:1024
	ds_read_b128 v[192:195], v155 offset:2048
	ds_read_b128 v[196:199], v155 offset:3072
	ds_read_b128 v[200:203], v155 offset:4096
	ds_read_b128 v[204:207], v155 offset:5120
	ds_read_b128 v[208:211], v155 offset:6144
	ds_read_b128 v[212:215], v155 offset:7168
	global_load_lds_dwordx4 v138, s[22:23]
	s_add_i32 m0, s38, 0xe000
	s_nop 0
	global_load_lds_dwordx4 v140, s[22:23]
	s_waitcnt vmcnt(8)
	s_waitcnt lgkmcnt(0)
	s_barrier
	s_setprio 1
	v_mfma_f32_16x16x32_bf16 v[124:127], v[146:149], v[184:187], v[124:127]
	v_mfma_f32_16x16x32_bf16 v[120:123], v[160:163], v[184:187], v[120:123]
	v_mfma_f32_16x16x32_bf16 v[116:119], v[146:149], v[192:195], v[116:119]
	v_mfma_f32_16x16x32_bf16 v[112:115], v[160:163], v[192:195], v[112:115]
	v_mfma_f32_16x16x32_bf16 v[92:95], v[146:149], v[200:203], v[92:95]
	v_mfma_f32_16x16x32_bf16 v[88:91], v[160:163], v[200:203], v[88:91]
	v_mfma_f32_16x16x32_bf16 v[76:79], v[146:149], v[208:211], v[76:79]
	v_mfma_f32_16x16x32_bf16 v[72:75], v[160:163], v[208:211], v[72:75]
	v_mfma_f32_16x16x32_bf16 v[124:127], v[156:159], v[188:191], v[124:127]
	v_mfma_f32_16x16x32_bf16 v[120:123], v[164:167], v[188:191], v[120:123]
	v_mfma_f32_16x16x32_bf16 v[116:119], v[156:159], v[196:199], v[116:119]
	v_mfma_f32_16x16x32_bf16 v[112:115], v[164:167], v[196:199], v[112:115]
	v_mfma_f32_16x16x32_bf16 v[92:95], v[156:159], v[204:207], v[92:95]
	v_mfma_f32_16x16x32_bf16 v[88:91], v[164:167], v[204:207], v[88:91]
	v_mfma_f32_16x16x32_bf16 v[76:79], v[156:159], v[212:215], v[76:79]
	v_mfma_f32_16x16x32_bf16 v[72:75], v[164:167], v[212:215], v[72:75]
	v_mfma_f32_16x16x32_bf16 v[108:111], v[168:171], v[184:187], v[108:111]
	v_mfma_f32_16x16x32_bf16 v[104:107], v[176:179], v[184:187], v[104:107]
	v_mfma_f32_16x16x32_bf16 v[100:103], v[168:171], v[192:195], v[100:103]
	v_mfma_f32_16x16x32_bf16 v[96:99], v[176:179], v[192:195], v[96:99]
	v_mfma_f32_16x16x32_bf16 v[84:87], v[168:171], v[200:203], v[84:87]
	v_mfma_f32_16x16x32_bf16 v[80:83], v[176:179], v[200:203], v[80:83]
	v_mfma_f32_16x16x32_bf16 v[68:71], v[168:171], v[208:211], v[68:71]
	v_mfma_f32_16x16x32_bf16 v[64:67], v[176:179], v[208:211], v[64:67]
	v_mfma_f32_16x16x32_bf16 v[108:111], v[172:175], v[188:191], v[108:111]
	v_mfma_f32_16x16x32_bf16 v[104:107], v[180:183], v[188:191], v[104:107]
	v_mfma_f32_16x16x32_bf16 v[100:103], v[172:175], v[196:199], v[100:103]
	v_mfma_f32_16x16x32_bf16 v[96:99], v[180:183], v[196:199], v[96:99]
	v_mfma_f32_16x16x32_bf16 v[84:87], v[172:175], v[204:207], v[84:87]
	v_mfma_f32_16x16x32_bf16 v[80:83], v[180:183], v[204:207], v[80:83]
	v_mfma_f32_16x16x32_bf16 v[68:71], v[172:175], v[212:215], v[68:71]
	v_mfma_f32_16x16x32_bf16 v[64:67], v[180:183], v[212:215], v[64:67]
	s_setprio 0
	s_barrier
	s_add_i32 s22, s46, s37
	v_lshl_add_u64 v[150:151], s[26:27], 0, v[130:131]
	s_mov_b32 m0, s22
	ds_read_b128 v[184:187], v155 offset:16384
	ds_read_b128 v[188:191], v155 offset:17408
	ds_read_b128 v[192:195], v155 offset:18432
	ds_read_b128 v[196:199], v155 offset:19456
	ds_read_b128 v[200:203], v155 offset:20480
	ds_read_b128 v[204:207], v155 offset:21504
	ds_read_b128 v[208:211], v155 offset:22528
	ds_read_b128 v[212:215], v155 offset:23552
	global_load_lds_dwordx4 v[150:151], off
	s_add_i32 m0, s22, 0x2000
	s_add_u32 s22, s26, 0xb0000
	v_lshl_add_u64 v[216:217], s[26:27], 0, v[134:135]
	s_addc_u32 s23, s27, 0
	s_add_i32 s57, s47, s37
	global_load_lds_dwordx4 v[216:217], off
	s_mov_b32 m0, s57
	v_lshl_add_u64 v[220:221], s[28:29], 0, v[132:133]
	global_load_lds_dwordx4 v130, s[22:23]
	s_add_i32 m0, s57, 0x2000
	s_nop 0
	global_load_lds_dwordx4 v134, s[22:23]
	v_lshl_add_u64 v[218:219], s[28:29], 0, v[128:129]
	s_mov_b32 m0, s38
	s_nop 0
	global_load_lds_dwordx4 v[218:219], off
	s_mov_b32 m0, s39
	s_nop 0
	global_load_lds_dwordx4 v[220:221], off
	s_waitcnt vmcnt(8)
	s_waitcnt lgkmcnt(0)
	s_barrier
	s_setprio 1
	v_mfma_f32_16x16x32_bf16 v[60:63], v[146:149], v[184:187], v[60:63]
	v_mfma_f32_16x16x32_bf16 v[56:59], v[160:163], v[184:187], v[56:59]
	v_mfma_f32_16x16x32_bf16 v[44:47], v[146:149], v[192:195], v[44:47]
	v_mfma_f32_16x16x32_bf16 v[40:43], v[160:163], v[192:195], v[40:43]
	v_mfma_f32_16x16x32_bf16 v[28:31], v[146:149], v[200:203], v[28:31]
	v_mfma_f32_16x16x32_bf16 v[24:27], v[160:163], v[200:203], v[24:27]
	v_mfma_f32_16x16x32_bf16 v[12:15], v[146:149], v[208:211], v[12:15]
	v_mfma_f32_16x16x32_bf16 v[8:11], v[160:163], v[208:211], v[8:11]
	v_mfma_f32_16x16x32_bf16 v[60:63], v[156:159], v[188:191], v[60:63]
	v_mfma_f32_16x16x32_bf16 v[56:59], v[164:167], v[188:191], v[56:59]
	v_mfma_f32_16x16x32_bf16 v[44:47], v[156:159], v[196:199], v[44:47]
	v_mfma_f32_16x16x32_bf16 v[40:43], v[164:167], v[196:199], v[40:43]
	v_mfma_f32_16x16x32_bf16 v[28:31], v[156:159], v[204:207], v[28:31]
	v_mfma_f32_16x16x32_bf16 v[24:27], v[164:167], v[204:207], v[24:27]
	v_mfma_f32_16x16x32_bf16 v[12:15], v[156:159], v[212:215], v[12:15]
	v_mfma_f32_16x16x32_bf16 v[8:11], v[164:167], v[212:215], v[8:11]
	v_mfma_f32_16x16x32_bf16 v[52:55], v[168:171], v[184:187], v[52:55]
	v_mfma_f32_16x16x32_bf16 v[48:51], v[176:179], v[184:187], v[48:51]
	v_mfma_f32_16x16x32_bf16 v[36:39], v[168:171], v[192:195], v[36:39]
	v_mfma_f32_16x16x32_bf16 v[32:35], v[176:179], v[192:195], v[32:35]
	v_mfma_f32_16x16x32_bf16 v[20:23], v[168:171], v[200:203], v[20:23]
	v_mfma_f32_16x16x32_bf16 v[16:19], v[176:179], v[200:203], v[16:19]
	v_mfma_f32_16x16x32_bf16 v[4:7], v[168:171], v[208:211], v[4:7]
	v_mfma_f32_16x16x32_bf16 v[0:3], v[176:179], v[208:211], v[0:3]
	v_mfma_f32_16x16x32_bf16 v[52:55], v[172:175], v[188:191], v[52:55]
	v_mfma_f32_16x16x32_bf16 v[48:51], v[180:183], v[188:191], v[48:51]
	v_mfma_f32_16x16x32_bf16 v[36:39], v[172:175], v[196:199], v[36:39]
	v_mfma_f32_16x16x32_bf16 v[32:35], v[180:183], v[196:199], v[32:35]
	v_mfma_f32_16x16x32_bf16 v[20:23], v[172:175], v[204:207], v[20:23]
	v_mfma_f32_16x16x32_bf16 v[16:19], v[180:183], v[204:207], v[16:19]
	v_mfma_f32_16x16x32_bf16 v[4:7], v[172:175], v[212:215], v[4:7]
	v_mfma_f32_16x16x32_bf16 v[0:3], v[180:183], v[212:215], v[0:3]
	s_setprio 0
	s_barrier
; #define PG8_STAGE(bufoff, gbase, voff) do { _Pragma("unroll") for (int _i = 0; _i < 2; ++_i) \
;         __builtin_amdgcn_global_load_lds((const unsigned*)((const char*)(gbase) + (voff)[_i]), (PG8_LAS unsigned*)(lds + (bufoff) + ldsw + _i * 8192), 16, 0, 0); } while (0)
; #define PG8_LDA(dst, b, h) do { _Pragma("unroll") for (int m = 0; m < 4; ++m) _Pragma("unroll") for (int k = 0; k < 2; ++k) dst[m][k] = *(const PG8_LAS bf16x8*)(lds + PG8_SA(b, h) + aoff + m * 2048 + k * 1024); } while (0)
; #define PG8_LDB(dst, b, h) do { _Pragma("unroll") for (int n = 0; n < 2; ++n) _Pragma("unroll") for (int k = 0; k < 2; ++k) dst[n][k] = *(const PG8_LAS bf16x8*)(lds + PG8_SB(b, h) + boff + n * 2048 + k * 1024); } while (0)
; #define PG8_MMA(ai, bj, At, Bt) do { __builtin_amdgcn_s_setprio(1); _Pragma("unroll") for (int m = 0; m < 4; ++m) _Pragma("unroll") for (int n = 0; n < 2; ++n) _Pragma("unroll") for (int k = 0; k < 2; ++k) \
;         acc[ai][bj][m][n] = __builtin_amdgcn_mfma_f32_16x16x32_bf16(Bt[n][k], At[m][k], acc[ai][bj][m][n], 0, 0, 0); __builtin_amdgcn_s_setprio(0); } while (0)
; #define PG8_WAIT_V(n) asm volatile("s_waitcnt vmcnt(" #n ")" ::: "memory")
; #define PG8_WAIT_L(n) asm volatile("s_waitcnt lgkmcnt(" #n ")" ::: "memory")
; #define PG8_BAR __builtin_amdgcn_s_barrier()
; #define PG8_SCHED __builtin_amdgcn_sched_barrier(0)
; template <class Epi, class Sched, bool ALIGN_EPI = false, bool SP2 = false>
; __device__ __forceinline__ void gemm_phase(PG8_LAS unsigned char* lds, const Gemm g, const Sched& S, const Epi& E) {
;     ...
;             PG8_LDB(B0, 1, 0); PG8_LDB(B1, 1, 1); PG8_SCHED; PG8_LDA(At, 1, 0); PG8_STAGE(PG8_SA(0, 1), a2 + hstep, voffA);
;             PG8_WAIT_V(8); PG8_WAIT_L(0); PG8_BAR; PG8_MMA(0, 0, At, B0); PG8_MMA(0, 1, At, B1); PG8_BAR; PG8_SCHED;
;             PG8_LDA(At, 1, 1); PG8_STAGE(PG8_SB(1, 0), b3, voffB); PG8_STAGE(PG8_SB(1, 1), b3 + hstep, voffB); PG8_STAGE(PG8_SA(1, 0), a3, voffA);
;             PG8_WAIT_V(8); PG8_WAIT_L(0); PG8_BAR; PG8_MMA(1, 0, At, B0); PG8_MMA(1, 1, At, B1); PG8_BAR; PG8_SCHED;
	s_add_i32 s57, 0, 0x18000
	s_add_i32 s58, 0, 0x1c000
	v_add_u32_e32 v164, s57, v152
	v_add_u32_e32 v180, s58, v152
	ds_read_b128 v[146:149], v164
	ds_read_b128 v[156:159], v164 offset:1024
	ds_read_b128 v[160:163], v164 offset:2048
	ds_read_b128 v[164:167], v164 offset:3072
	ds_read_b128 v[168:171], v180
	ds_read_b128 v[172:175], v180 offset:1024
	ds_read_b128 v[176:179], v180 offset:2048
	ds_read_b128 v[180:183], v180 offset:3072
	s_add_u32 s22, s28, 0xb0000
	s_addc_u32 s23, s29, 0
	s_mov_b32 m0, s40
	ds_read_b128 v[184:187], v155 offset:32768
	ds_read_b128 v[188:191], v155 offset:33792
	ds_read_b128 v[192:195], v155 offset:34816
	ds_read_b128 v[196:199], v155 offset:35840
	ds_read_b128 v[200:203], v155 offset:36864
	ds_read_b128 v[204:207], v155 offset:37888
	ds_read_b128 v[208:211], v155 offset:38912
	ds_read_b128 v[212:215], v155 offset:39936
	global_load_lds_dwordx4 v128, s[22:23]
	s_mov_b32 m0, s41
	s_nop 0
	global_load_lds_dwordx4 v132, s[22:23]
	s_waitcnt vmcnt(8)
	s_waitcnt lgkmcnt(0)
	s_barrier
	s_setprio 1
	v_mfma_f32_16x16x32_bf16 v[124:127], v[146:149], v[184:187], v[124:127]
	v_mfma_f32_16x16x32_bf16 v[120:123], v[160:163], v[184:187], v[120:123]
	v_mfma_f32_16x16x32_bf16 v[116:119], v[146:149], v[192:195], v[116:119]
	v_mfma_f32_16x16x32_bf16 v[112:115], v[160:163], v[192:195], v[112:115]
	v_mfma_f32_16x16x32_bf16 v[92:95], v[146:149], v[200:203], v[92:95]
	v_mfma_f32_16x16x32_bf16 v[88:91], v[160:163], v[200:203], v[88:91]
	v_mfma_f32_16x16x32_bf16 v[76:79], v[146:149], v[208:211], v[76:79]
	v_mfma_f32_16x16x32_bf16 v[72:75], v[160:163], v[208:211], v[72:75]
	v_mfma_f32_16x16x32_bf16 v[124:127], v[156:159], v[188:191], v[124:127]
	v_mfma_f32_16x16x32_bf16 v[120:123], v[164:167], v[188:191], v[120:123]
	v_mfma_f32_16x16x32_bf16 v[116:119], v[156:159], v[196:199], v[116:119]
	v_mfma_f32_16x16x32_bf16 v[112:115], v[164:167], v[196:199], v[112:115]
	v_mfma_f32_16x16x32_bf16 v[92:95], v[156:159], v[204:207], v[92:95]
	v_mfma_f32_16x16x32_bf16 v[88:91], v[164:167], v[204:207], v[88:91]
	v_mfma_f32_16x16x32_bf16 v[76:79], v[156:159], v[212:215], v[76:79]
	v_mfma_f32_16x16x32_bf16 v[72:75], v[164:167], v[212:215], v[72:75]
	v_mfma_f32_16x16x32_bf16 v[108:111], v[168:171], v[184:187], v[108:111]
	v_mfma_f32_16x16x32_bf16 v[104:107], v[176:179], v[184:187], v[104:107]
	v_mfma_f32_16x16x32_bf16 v[100:103], v[168:171], v[192:195], v[100:103]
	v_mfma_f32_16x16x32_bf16 v[96:99], v[176:179], v[192:195], v[96:99]
	v_mfma_f32_16x16x32_bf16 v[84:87], v[168:171], v[200:203], v[84:87]
	v_mfma_f32_16x16x32_bf16 v[80:83], v[176:179], v[200:203], v[80:83]
	v_mfma_f32_16x16x32_bf16 v[68:71], v[168:171], v[208:211], v[68:71]
	v_mfma_f32_16x16x32_bf16 v[64:67], v[176:179], v[208:211], v[64:67]
	v_mfma_f32_16x16x32_bf16 v[108:111], v[172:175], v[188:191], v[108:111]
	v_mfma_f32_16x16x32_bf16 v[104:107], v[180:183], v[188:191], v[104:107]
	v_mfma_f32_16x16x32_bf16 v[100:103], v[172:175], v[196:199], v[100:103]
	v_mfma_f32_16x16x32_bf16 v[96:99], v[180:183], v[196:199], v[96:99]
	v_mfma_f32_16x16x32_bf16 v[84:87], v[172:175], v[204:207], v[84:87]
	v_mfma_f32_16x16x32_bf16 v[80:83], v[180:183], v[204:207], v[80:83]
	v_mfma_f32_16x16x32_bf16 v[68:71], v[172:175], v[212:215], v[68:71]
	v_mfma_f32_16x16x32_bf16 v[64:67], v[180:183], v[212:215], v[64:67]
	s_setprio 0
	s_barrier
	s_add_i32 s22, s57, s37
	v_lshl_add_u64 v[150:151], v[150:151], 0, s[8:9]
	s_mov_b32 m0, s22
	ds_read_b128 v[184:187], v155 offset:49152
	ds_read_b128 v[188:191], v155 offset:50176
	ds_read_b128 v[192:195], v155 offset:51200
	ds_read_b128 v[196:199], v155 offset:52224
	ds_read_b128 v[200:203], v155 offset:53248
	ds_read_b128 v[204:207], v155 offset:54272
	ds_read_b128 v[208:211], v155 offset:55296
	ds_read_b128 v[212:215], v155 offset:56320
	global_load_lds_dwordx4 v[150:151], off
	s_add_i32 m0, s22, 0x2000
	s_add_u32 s22, s26, 0xb0080
	v_lshl_add_u64 v[150:151], v[216:217], 0, s[8:9]
	s_addc_u32 s23, s27, 0
	s_add_i32 s26, s58, s37
	global_load_lds_dwordx4 v[150:151], off
	s_mov_b32 m0, s26
	s_nop 0
	global_load_lds_dwordx4 v130, s[22:23]
	s_add_i32 m0, s26, 0x2000
	s_nop 0
	global_load_lds_dwordx4 v134, s[22:23]
	v_lshl_add_u64 v[150:151], v[218:219], 0, s[8:9]
	s_mov_b32 m0, s43
	s_nop 0
	global_load_lds_dwordx4 v[150:151], off
	v_lshl_add_u64 v[150:151], v[220:221], 0, s[8:9]
	s_mov_b32 m0, s44
	s_nop 0
	global_load_lds_dwordx4 v[150:151], off
	s_waitcnt vmcnt(8)
	s_waitcnt lgkmcnt(0)
	s_barrier
	s_setprio 1
	v_mfma_f32_16x16x32_bf16 v[60:63], v[146:149], v[184:187], v[60:63]
	v_mfma_f32_16x16x32_bf16 v[56:59], v[160:163], v[184:187], v[56:59]
	v_mfma_f32_16x16x32_bf16 v[44:47], v[146:149], v[192:195], v[44:47]
	v_mfma_f32_16x16x32_bf16 v[40:43], v[160:163], v[192:195], v[40:43]
	v_mfma_f32_16x16x32_bf16 v[28:31], v[146:149], v[200:203], v[28:31]
	v_mfma_f32_16x16x32_bf16 v[24:27], v[160:163], v[200:203], v[24:27]
	v_mfma_f32_16x16x32_bf16 v[12:15], v[146:149], v[208:211], v[12:15]
	v_mfma_f32_16x16x32_bf16 v[8:11], v[160:163], v[208:211], v[8:11]
	v_mfma_f32_16x16x32_bf16 v[60:63], v[156:159], v[188:191], v[60:63]
	v_mfma_f32_16x16x32_bf16 v[56:59], v[164:167], v[188:191], v[56:59]
	v_mfma_f32_16x16x32_bf16 v[44:47], v[156:159], v[196:199], v[44:47]
	v_mfma_f32_16x16x32_bf16 v[40:43], v[164:167], v[196:199], v[40:43]
	v_mfma_f32_16x16x32_bf16 v[28:31], v[156:159], v[204:207], v[28:31]
	v_mfma_f32_16x16x32_bf16 v[24:27], v[164:167], v[204:207], v[24:27]
	v_mfma_f32_16x16x32_bf16 v[12:15], v[156:159], v[212:215], v[12:15]
	v_mfma_f32_16x16x32_bf16 v[8:11], v[164:167], v[212:215], v[8:11]
	v_mfma_f32_16x16x32_bf16 v[52:55], v[168:171], v[184:187], v[52:55]
	v_mfma_f32_16x16x32_bf16 v[48:51], v[176:179], v[184:187], v[48:51]
	v_mfma_f32_16x16x32_bf16 v[36:39], v[168:171], v[192:195], v[36:39]
	v_mfma_f32_16x16x32_bf16 v[32:35], v[176:179], v[192:195], v[32:35]
	v_mfma_f32_16x16x32_bf16 v[20:23], v[168:171], v[200:203], v[20:23]
	v_mfma_f32_16x16x32_bf16 v[16:19], v[176:179], v[200:203], v[16:19]
	v_mfma_f32_16x16x32_bf16 v[4:7], v[168:171], v[208:211], v[4:7]
	v_mfma_f32_16x16x32_bf16 v[0:3], v[176:179], v[208:211], v[0:3]
	v_mfma_f32_16x16x32_bf16 v[52:55], v[172:175], v[188:191], v[52:55]
	v_mfma_f32_16x16x32_bf16 v[48:51], v[180:183], v[188:191], v[48:51]
	v_mfma_f32_16x16x32_bf16 v[36:39], v[172:175], v[196:199], v[36:39]
	v_mfma_f32_16x16x32_bf16 v[32:35], v[180:183], v[196:199], v[32:35]
	v_mfma_f32_16x16x32_bf16 v[20:23], v[172:175], v[204:207], v[20:23]
	v_mfma_f32_16x16x32_bf16 v[16:19], v[180:183], v[204:207], v[16:19]
	v_mfma_f32_16x16x32_bf16 v[4:7], v[172:175], v[212:215], v[4:7]
	v_mfma_f32_16x16x32_bf16 v[0:3], v[180:183], v[212:215], v[0:3]
	s_setprio 0
	s_barrier
	s_add_i32 s56, s56, 2
	s_add_u32 s54, s54, 0x100
	s_addc_u32 s55, s55, 0
	s_cmp_gt_u32 s56, 41
	s_mov_b64 s[22:23], s[24:25]
	s_cbranch_scc0 .LBB0_1052
	s_and_b64 vcc, exec, s[10:11]
	s_cbranch_vccz .LBB0_1055
	s_barrier
